# attention: cross-lane max/sum all-reduce with v_permlane16/32_swap instead of ds_bpermute round trips
# speedup vs baseline: 1.0207x; 1.0007x over previous
.Lat738_i0_nomask:
	v_max3_f32 v245, v44, v45, v46
	v_max3_f32 v245, v245, v47, v48
	v_max3_f32 v245, v245, v49, v50
	v_max3_f32 v245, v245, v51, v52
	v_max3_f32 v245, v245, v53, v54
	v_max3_f32 v245, v245, v55, v56
	v_max3_f32 v245, v245, v57, v58
	v_max3_f32 v245, v245, v59, v60
	v_max3_f32 v245, v245, v61, v62
	v_max3_f32 v245, v245, v63, v64
	v_max3_f32 v245, v245, v65, v66
	v_max3_f32 v245, v245, v67, v68
	v_max3_f32 v245, v245, v69, v70
	v_max3_f32 v245, v245, v71, v72
	v_max3_f32 v245, v245, v73, v74
	v_max3_f32 v245, v245, v75, v76
	v_max3_f32 v245, v245, v77, v78
	v_max_f32_e32 v245, v245, v79
	v_mov_b32_e32 v148, v245
	s_nop 1
	v_permlane16_swap_b32 v245, v148
	v_max_f32_e32 v245, v245, v148
	v_mov_b32_e32 v148, v245
	s_nop 1
	v_permlane32_swap_b32 v245, v148
	v_max_f32_e32 v245, v245, v148
	v_sub_f32_e32 v44, v44, v245
	v_sub_f32_e32 v45, v45, v245
	v_sub_f32_e32 v46, v46, v245
	v_sub_f32_e32 v47, v47, v245
	v_exp_f32_e32 v44, v44
	v_exp_f32_e32 v45, v45
	v_exp_f32_e32 v46, v46
	v_exp_f32_e32 v47, v47
	v_sub_f32_e32 v48, v48, v245
	v_sub_f32_e32 v49, v49, v245
	v_sub_f32_e32 v50, v50, v245
	v_sub_f32_e32 v51, v51, v245
	v_exp_f32_e32 v48, v48
	v_exp_f32_e32 v49, v49
	v_exp_f32_e32 v50, v50
	v_exp_f32_e32 v51, v51
	v_mov_b32_e32 v149, v44
	v_mov_b32_e32 v150, v45
	v_mov_b32_e32 v151, v46
	v_mov_b32_e32 v152, v47
	v_cvt_pk_bf16_f32 v44, v44, v45
	v_cvt_pk_bf16_f32 v45, v46, v47
	v_sub_f32_e32 v52, v52, v245
	v_sub_f32_e32 v53, v53, v245
	v_sub_f32_e32 v54, v54, v245
	v_sub_f32_e32 v55, v55, v245
	v_exp_f32_e32 v52, v52
	v_exp_f32_e32 v53, v53
	v_exp_f32_e32 v54, v54
	v_exp_f32_e32 v55, v55
	v_add_f32_e32 v149, v149, v48
	v_add_f32_e32 v150, v150, v49
	v_add_f32_e32 v151, v151, v50
	v_add_f32_e32 v152, v152, v51
	v_cvt_pk_bf16_f32 v46, v48, v49
	v_cvt_pk_bf16_f32 v47, v50, v51
	v_sub_f32_e32 v56, v56, v245
	v_sub_f32_e32 v57, v57, v245
	v_sub_f32_e32 v58, v58, v245
	v_sub_f32_e32 v59, v59, v245
	v_exp_f32_e32 v56, v56
	v_exp_f32_e32 v57, v57
	v_exp_f32_e32 v58, v58
	v_exp_f32_e32 v59, v59
	v_add_f32_e32 v149, v149, v52
	v_add_f32_e32 v150, v150, v53
	v_add_f32_e32 v151, v151, v54
	v_add_f32_e32 v152, v152, v55
	v_cvt_pk_bf16_f32 v52, v52, v53
	v_cvt_pk_bf16_f32 v53, v54, v55
	v_sub_f32_e32 v60, v60, v245
	v_sub_f32_e32 v61, v61, v245
	v_sub_f32_e32 v62, v62, v245
	v_sub_f32_e32 v63, v63, v245
	v_exp_f32_e32 v60, v60
	v_exp_f32_e32 v61, v61
	v_exp_f32_e32 v62, v62
	v_exp_f32_e32 v63, v63
	v_add_f32_e32 v149, v149, v56
	v_add_f32_e32 v150, v150, v57
	v_add_f32_e32 v151, v151, v58
	v_add_f32_e32 v152, v152, v59
	v_cvt_pk_bf16_f32 v54, v56, v57
	v_cvt_pk_bf16_f32 v55, v58, v59
	v_sub_f32_e32 v64, v64, v245
	v_sub_f32_e32 v65, v65, v245
	v_sub_f32_e32 v66, v66, v245
	v_sub_f32_e32 v67, v67, v245
	v_exp_f32_e32 v64, v64
	v_exp_f32_e32 v65, v65
	v_exp_f32_e32 v66, v66
	v_exp_f32_e32 v67, v67
	v_add_f32_e32 v149, v149, v60
	v_add_f32_e32 v150, v150, v61
	v_add_f32_e32 v151, v151, v62
	v_add_f32_e32 v152, v152, v63
	v_cvt_pk_bf16_f32 v60, v60, v61
	v_cvt_pk_bf16_f32 v61, v62, v63
	v_sub_f32_e32 v68, v68, v245
	v_sub_f32_e32 v69, v69, v245
	v_sub_f32_e32 v70, v70, v245
	v_sub_f32_e32 v71, v71, v245
	v_exp_f32_e32 v68, v68
	v_exp_f32_e32 v69, v69
	v_exp_f32_e32 v70, v70
	v_exp_f32_e32 v71, v71
	v_add_f32_e32 v149, v149, v64
	v_add_f32_e32 v150, v150, v65
	v_add_f32_e32 v151, v151, v66
	v_add_f32_e32 v152, v152, v67
	v_cvt_pk_bf16_f32 v62, v64, v65
	v_cvt_pk_bf16_f32 v63, v66, v67
	v_sub_f32_e32 v72, v72, v245
	v_sub_f32_e32 v73, v73, v245
	v_sub_f32_e32 v74, v74, v245
	v_sub_f32_e32 v75, v75, v245
	v_exp_f32_e32 v72, v72
	v_exp_f32_e32 v73, v73
	v_exp_f32_e32 v74, v74
	v_exp_f32_e32 v75, v75
	v_add_f32_e32 v149, v149, v68
	v_add_f32_e32 v150, v150, v69
	v_add_f32_e32 v151, v151, v70
	v_add_f32_e32 v152, v152, v71
	v_cvt_pk_bf16_f32 v68, v68, v69
	v_cvt_pk_bf16_f32 v69, v70, v71
	v_sub_f32_e32 v76, v76, v245
	v_sub_f32_e32 v77, v77, v245
	v_sub_f32_e32 v78, v78, v245
	v_sub_f32_e32 v79, v79, v245
	v_exp_f32_e32 v76, v76
	v_exp_f32_e32 v77, v77
	v_exp_f32_e32 v78, v78
	v_exp_f32_e32 v79, v79
	v_add_f32_e32 v149, v149, v72
	v_add_f32_e32 v150, v150, v73
	v_add_f32_e32 v151, v151, v74
	v_add_f32_e32 v152, v152, v75
	v_cvt_pk_bf16_f32 v70, v72, v73
	v_cvt_pk_bf16_f32 v71, v74, v75
	s_nop 0
	v_add_f32_e32 v149, v149, v76
	v_add_f32_e32 v150, v150, v77
	v_add_f32_e32 v151, v151, v78
	v_add_f32_e32 v152, v152, v79
	v_cvt_pk_bf16_f32 v76, v76, v77
	v_cvt_pk_bf16_f32 v77, v78, v79
	v_mov_b32_e32 v78, 0
	v_mov_b32_e32 v79, 0
	v_add_f32_e32 v149, v149, v150
	v_add_f32_e32 v151, v151, v152
	v_add_f32_e32 v246, v149, v151
	s_waitcnt lgkmcnt(0)
	v_mfma_f32_16x16x32_bf16 v[80:83], v[4:7], v[44:47], 0
	v_mfma_f32_16x16x32_bf16 v[84:87], v[8:11], v[44:47], 0
	v_mfma_f32_16x16x32_bf16 v[88:91], v[12:15], v[44:47], 0
	v_mfma_f32_16x16x32_bf16 v[92:95], v[16:19], v[44:47], 0
	s_cmp_gt_u32 s6, 4
	s_cselect_b32 s74, 0, 0xffff0000
	v_add_u32_e32 v146, s74, v225
	ds_read_b64 v[4:5], v146 offset:49152
	ds_read_b64 v[8:9], v146 offset:53248
	ds_read_b64 v[12:13], v146 offset:57344
	ds_read_b64 v[16:17], v146 offset:61440
	s_cmp_gt_u32 s6, 5
	s_cselect_b32 s74, 0, 0xffff0000
	v_add_u32_e32 v146, s74, v226
	ds_read_b64 v[6:7], v146 offset:49152
	ds_read_b64 v[10:11], v146 offset:53248
	ds_read_b64 v[14:15], v146 offset:57344
	ds_read_b64 v[18:19], v146 offset:61440
	v_mfma_f32_16x16x32_bf16 v[80:83], v[20:23], v[52:55], v[80:83]
	v_mfma_f32_16x16x32_bf16 v[84:87], v[24:27], v[52:55], v[84:87]
	v_mfma_f32_16x16x32_bf16 v[88:91], v[28:31], v[52:55], v[88:91]
	v_mfma_f32_16x16x32_bf16 v[92:95], v[32:35], v[52:55], v[92:95]
	s_cmp_gt_u32 s6, 6
	s_cselect_b32 s74, 0, 0xffff0000
	v_add_u32_e32 v146, s74, v227
	ds_read_b64 v[20:21], v146 offset:49152
	ds_read_b64 v[24:25], v146 offset:53248
	ds_read_b64 v[28:29], v146 offset:57344
	ds_read_b64 v[32:33], v146 offset:61440
	s_cmp_gt_u32 s6, 7
	s_cselect_b32 s74, 0, 0xffff0000
	v_add_u32_e32 v146, s74, v228
	ds_read_b64 v[22:23], v146 offset:49152
	ds_read_b64 v[26:27], v146 offset:53248
	ds_read_b64 v[30:31], v146 offset:57344
	ds_read_b64 v[34:35], v146 offset:61440
	s_waitcnt lgkmcnt(8)
	v_mfma_f32_16x16x32_bf16 v[80:83], v[4:7], v[60:63], v[80:83]
	v_mfma_f32_16x16x32_bf16 v[84:87], v[8:11], v[60:63], v[84:87]
	v_mfma_f32_16x16x32_bf16 v[88:91], v[12:15], v[60:63], v[88:91]
	v_mfma_f32_16x16x32_bf16 v[92:95], v[16:19], v[60:63], v[92:95]
	s_cmp_gt_u32 s6, 8
	s_cselect_b32 s74, 0, 0xffff0000
	v_add_u32_e32 v146, s74, v229
	ds_read_b64 v[4:5], v146 offset:49152
	ds_read_b64 v[8:9], v146 offset:53248
	ds_read_b64 v[12:13], v146 offset:57344
	ds_read_b64 v[16:17], v146 offset:61440
	v_mov_b32_e32 v6, 0
	v_mov_b32_e32 v7, 0
	v_mov_b32_e32 v10, 0
	v_mov_b32_e32 v11, 0
	v_mov_b32_e32 v14, 0
	v_mov_b32_e32 v15, 0
	v_mov_b32_e32 v18, 0
	v_mov_b32_e32 v19, 0
	s_waitcnt lgkmcnt(4)
	v_mfma_f32_16x16x32_bf16 v[80:83], v[20:23], v[68:71], v[80:83]
	v_mfma_f32_16x16x32_bf16 v[84:87], v[24:27], v[68:71], v[84:87]
	v_mfma_f32_16x16x32_bf16 v[88:91], v[28:31], v[68:71], v[88:91]
	v_mfma_f32_16x16x32_bf16 v[92:95], v[32:35], v[68:71], v[92:95]
	s_waitcnt lgkmcnt(0)
	v_mfma_f32_16x16x32_bf16 v[80:83], v[4:7], v[76:79], v[80:83]
	v_mfma_f32_16x16x32_bf16 v[84:87], v[8:11], v[76:79], v[84:87]
	v_mfma_f32_16x16x32_bf16 v[88:91], v[12:15], v[76:79], v[88:91]
	v_mfma_f32_16x16x32_bf16 v[92:95], v[16:19], v[76:79], v[92:95]
	v_mov_b32_e32 v148, v246
	s_nop 1
	v_permlane16_swap_b32 v246, v148
	v_add_f32_e32 v246, v246, v148
	v_mov_b32_e32 v148, v246
	s_nop 1
	v_permlane32_swap_b32 v246, v148
	v_add_f32_e32 v246, v246, v148
	v_rcp_f32_e32 v149, v246
	v_log_f32_e32 v150, v246
	s_nop 0
	v_add_f32_e32 v151, v245, v150
	v_mul_f32_e32 v151, 0x3f317218, v151
	v_mov_b32_e32 v140, v151
	v_mul_f32_e32 v80, v80, v149
	v_mul_f32_e32 v81, v81, v149
	v_mul_f32_e32 v82, v82, v149
	v_mul_f32_e32 v83, v83, v149
	v_mul_f32_e32 v84, v84, v149
	v_mul_f32_e32 v85, v85, v149
	v_mul_f32_e32 v86, v86, v149
	v_mul_f32_e32 v87, v87, v149
	v_mul_f32_e32 v88, v88, v149
	v_mul_f32_e32 v89, v89, v149
	v_mul_f32_e32 v90, v90, v149
	v_mul_f32_e32 v91, v91, v149
	v_mul_f32_e32 v92, v92, v149
	v_mul_f32_e32 v93, v93, v149
	v_mul_f32_e32 v94, v94, v149
	v_mul_f32_e32 v95, v95, v149
	v_cvt_pk_bf16_f32 v132, v80, v81
	v_cvt_pk_bf16_f32 v133, v82, v83
	v_cvt_pk_bf16_f32 v134, v84, v85
	v_cvt_pk_bf16_f32 v135, v86, v87
	v_cvt_pk_bf16_f32 v136, v88, v89
	v_cvt_pk_bf16_f32 v137, v90, v91
	v_cvt_pk_bf16_f32 v138, v92, v93
	v_cvt_pk_bf16_f32 v139, v94, v95
	s_mov_b64 s[26:27], s[86:87]
	s_mov_b64 s[28:29], s[88:89]
	s_mov_b64 s[86:87], s[12:13]
	s_mov_b64 s[88:89], s[14:15]
	s_mov_b32 s4, s83
	s_mov_b32 s5, s84
	s_waitcnt vmcnt(0)
	s_barrier
	ds_read_b128 v[4:7], v230 offset:0
	ds_read_b128 v[8:11], v231 offset:0
	ds_read_b128 v[12:15], v230 offset:2048
	ds_read_b128 v[16:19], v231 offset:2048
	ds_read_b128 v[20:23], v230 offset:4096
	ds_read_b128 v[24:27], v231 offset:4096
	ds_read_b128 v[28:31], v230 offset:6144
	ds_read_b128 v[32:35], v231 offset:6144
	ds_read_b128 v[36:39], v230 offset:8192
	ds_read_b128 v[40:43], v231 offset:8192
	global_store_dwordx2 v237, v[132:133], s[26:27]
	global_store_dwordx2 v237, v[134:135], s[26:27] offset:32
	global_store_dwordx2 v237, v[136:137], s[26:27] offset:64
	global_store_dwordx2 v237, v[138:139], s[26:27] offset:96
	s_mov_b64 s[90:91], exec
	s_mov_b64 exec, 0xffff
	global_store_dword v238, v140, s[28:29]
	s_mov_b64 exec, s[90:91]
	s_add_u32 s83, s4, 1
	s_mov_b32 s84, s5
	s_mul_i32 s74, s84, 4096
	s_lshl_b32 s75, s83, 7
	s_add_u32 s74, s74, s75
	s_lshl_b32 s75, s74, 7
	s_add_u32 s16, s60, s75
	s_addc_u32 s17, s61, 0
	s_lshl_b32 s75, s74, 1
	s_add_u32 s24, s64, s75
	s_addc_u32 s25, s65, 0
	s_add_u32 m0, s70, 0x8000
	s_nop 0
	global_load_lds_dwordx4 v232, s[16:17] nt
	s_add_u32 m0, s70, 0xa000
	s_nop 0
	global_load_lds_dwordx4 v233, s[16:17] nt
	s_add_u32 m0, s70, 0x18000
	s_nop 0
	global_load_lds_dwordx4 v234, s[24:25] nt
	s_add_u32 m0, s70, 0x1a000
	s_nop 0
	global_load_lds_dwordx4 v235, s[24:25] nt
	s_lshl_b32 s74, s83, 7
	s_add_u32 s74, s74, s84
	s_lshl_b32 s75, s74, 7
	s_add_u32 s10, s30, s75
	s_addc_u32 s11, s31, 0
	s_add_u32 s12, s34, s75
	s_addc_u32 s13, s35, 0
	s_lshl_b32 s75, s74, 2
	s_add_u32 s14, s58, s75
	s_addc_u32 s15, s59, 0
	global_load_dwordx4 v[96:99], v236, s[10:11]
	global_load_dwordx4 v[100:103], v236, s[10:11] offset:64
	s_waitcnt lgkmcnt(0)
	v_mfma_f32_16x16x32_bf16 v[44:47], v[4:7], v[104:107], 0
	v_mfma_f32_16x16x32_bf16 v[48:51], v[12:15], v[104:107], 0
	v_mfma_f32_16x16x32_bf16 v[52:55], v[20:23], v[104:107], 0
	v_mfma_f32_16x16x32_bf16 v[56:59], v[28:31], v[104:107], 0
	v_mfma_f32_16x16x32_bf16 v[60:63], v[36:39], v[104:107], 0
	v_mfma_f32_16x16x32_bf16 v[44:47], v[8:11], v[108:111], v[44:47]
	v_mfma_f32_16x16x32_bf16 v[48:51], v[16:19], v[108:111], v[48:51]
	v_mfma_f32_16x16x32_bf16 v[52:55], v[24:27], v[108:111], v[52:55]
	v_mfma_f32_16x16x32_bf16 v[56:59], v[32:35], v[108:111], v[56:59]
	v_mfma_f32_16x16x32_bf16 v[60:63], v[40:43], v[108:111], v[60:63]
	ds_read_b128 v[4:7], v230 offset:10240
	ds_read_b128 v[8:11], v231 offset:10240
	ds_read_b128 v[12:15], v230 offset:12288
	ds_read_b128 v[16:19], v231 offset:12288
	ds_read_b128 v[20:23], v230 offset:14336
	ds_read_b128 v[24:27], v231 offset:14336
	ds_read_b128 v[28:31], v230 offset:16384
	ds_read_b128 v[32:35], v231 offset:16384
	s_nop 1
	v_fma_f32 v44, v44, s79, v185
	v_fma_f32 v45, v45, s79, v186
	v_fma_f32 v46, v46, s79, v187
	v_fma_f32 v47, v47, s79, v188
	v_fma_f32 v48, v48, s79, v189
	v_fma_f32 v49, v49, s79, v190
	v_fma_f32 v50, v50, s79, v191
	v_fma_f32 v51, v51, s79, v192
	v_fma_f32 v52, v52, s79, v193
	v_fma_f32 v53, v53, s79, v194
	v_fma_f32 v54, v54, s79, v195
	v_fma_f32 v55, v55, s79, v196
	v_fma_f32 v56, v56, s79, v197
	v_fma_f32 v57, v57, s79, v198
	v_fma_f32 v58, v58, s79, v199
	v_fma_f32 v59, v59, s79, v200
	v_fma_f32 v60, v60, s79, v201
	v_fma_f32 v61, v61, s79, v202
	v_fma_f32 v62, v62, s79, v203
	v_fma_f32 v63, v63, s79, v204
	s_waitcnt lgkmcnt(0)
	v_mfma_f32_16x16x32_bf16 v[64:67], v[4:7], v[104:107], 0
	v_mfma_f32_16x16x32_bf16 v[68:71], v[12:15], v[104:107], 0
	v_mfma_f32_16x16x32_bf16 v[72:75], v[20:23], v[104:107], 0
	v_mfma_f32_16x16x32_bf16 v[76:79], v[28:31], v[104:107], 0
	v_mfma_f32_16x16x32_bf16 v[64:67], v[8:11], v[108:111], v[64:67]
	v_mfma_f32_16x16x32_bf16 v[68:71], v[16:19], v[108:111], v[68:71]
	v_mfma_f32_16x16x32_bf16 v[72:75], v[24:27], v[108:111], v[72:75]
	v_mfma_f32_16x16x32_bf16 v[76:79], v[32:35], v[108:111], v[76:79]
	ds_read_b64 v[4:5], v221 offset:0
	ds_read_b64 v[8:9], v221 offset:4096
	ds_read_b64 v[12:13], v221 offset:8192
	ds_read_b64 v[16:17], v221 offset:12288
	ds_read_b64 v[6:7], v222 offset:0
	ds_read_b64 v[10:11], v222 offset:4096
	ds_read_b64 v[14:15], v222 offset:8192
	ds_read_b64 v[18:19], v222 offset:12288
	s_nop 1
	v_fma_f32 v64, v64, s79, v205
	v_fma_f32 v65, v65, s79, v206
	v_fma_f32 v66, v66, s79, v207
	v_fma_f32 v67, v67, s79, v208
	v_fma_f32 v68, v68, s79, v209
	v_fma_f32 v69, v69, s79, v210
	v_fma_f32 v70, v70, s79, v211
	v_fma_f32 v71, v71, s79, v212
	v_fma_f32 v72, v72, s79, v213
	v_fma_f32 v73, v73, s79, v214
	v_fma_f32 v74, v74, s79, v215
	v_fma_f32 v75, v75, s79, v216
	v_fma_f32 v76, v76, s79, v217
	v_fma_f32 v77, v77, s79, v218
	v_fma_f32 v78, v78, s79, v219
	v_fma_f32 v79, v79, s79, v220
	ds_read_b64 v[20:21], v223 offset:0
	ds_read_b64 v[24:25], v223 offset:4096
	ds_read_b64 v[28:29], v223 offset:8192
	ds_read_b64 v[32:33], v223 offset:12288
	ds_read_b64 v[22:23], v224 offset:0
	ds_read_b64 v[26:27], v224 offset:4096
	ds_read_b64 v[30:31], v224 offset:8192
	ds_read_b64 v[34:35], v224 offset:12288
	s_cmp_lg_u32 s4, 0
	s_cbranch_scc1 .Lat738_i1_nomask
	s_cmp_le_u32 s6, 0
	s_cbranch_scc1 .Lat738_i1_nomask
	v_mov_b32_e32 v44, v244
	v_mov_b32_e32 v45, v244
	v_mov_b32_e32 v46, v244
	v_mov_b32_e32 v47, v244
	s_cmp_le_u32 s6, 1
	s_cbranch_scc1 .Lat738_i1_nomask
	v_mov_b32_e32 v48, v244
	v_mov_b32_e32 v49, v244
	v_mov_b32_e32 v50, v244
	v_mov_b32_e32 v51, v244
	s_cmp_le_u32 s6, 2
	s_cbranch_scc1 .Lat738_i1_nomask
	v_mov_b32_e32 v52, v244
	v_mov_b32_e32 v53, v244
	v_mov_b32_e32 v54, v244
	v_mov_b32_e32 v55, v244
	s_cmp_le_u32 s6, 3
	s_cbranch_scc1 .Lat738_i1_nomask
	v_mov_b32_e32 v56, v244
	v_mov_b32_e32 v57, v244
	v_mov_b32_e32 v58, v244
	v_mov_b32_e32 v59, v244
	s_cmp_le_u32 s6, 4
	s_cbranch_scc1 .Lat738_i1_nomask
	v_mov_b32_e32 v60, v244
	v_mov_b32_e32 v61, v244
	v_mov_b32_e32 v62, v244
	v_mov_b32_e32 v63, v244
	s_cmp_le_u32 s6, 5
	s_cbranch_scc1 .Lat738_i1_nomask
	v_mov_b32_e32 v64, v244
	v_mov_b32_e32 v65, v244
	v_mov_b32_e32 v66, v244
	v_mov_b32_e32 v67, v244
	s_cmp_le_u32 s6, 6
	s_cbranch_scc1 .Lat738_i1_nomask
	v_mov_b32_e32 v68, v244
	v_mov_b32_e32 v69, v244
	v_mov_b32_e32 v70, v244
	v_mov_b32_e32 v71, v244
	s_cmp_le_u32 s6, 7
	s_cbranch_scc1 .Lat738_i1_nomask
	v_mov_b32_e32 v72, v244
	v_mov_b32_e32 v73, v244
	v_mov_b32_e32 v74, v244
	v_mov_b32_e32 v75, v244
.Lat738_i1_nomask:
	v_max3_f32 v245, v44, v45, v46
	v_max3_f32 v245, v245, v47, v48
	v_max3_f32 v245, v245, v49, v50
	v_max3_f32 v245, v245, v51, v52
	v_max3_f32 v245, v245, v53, v54
	v_max3_f32 v245, v245, v55, v56
	v_max3_f32 v245, v245, v57, v58
	v_max3_f32 v245, v245, v59, v60
	v_max3_f32 v245, v245, v61, v62
	v_max3_f32 v245, v245, v63, v64
	v_max3_f32 v245, v245, v65, v66
	v_max3_f32 v245, v245, v67, v68
	v_max3_f32 v245, v245, v69, v70
	v_max3_f32 v245, v245, v71, v72
	v_max3_f32 v245, v245, v73, v74
	v_max3_f32 v245, v245, v75, v76
	v_max3_f32 v245, v245, v77, v78
	v_max_f32_e32 v245, v245, v79
	v_mov_b32_e32 v148, v245
	s_nop 1
	v_permlane16_swap_b32 v245, v148
	v_max_f32_e32 v245, v245, v148
	v_mov_b32_e32 v148, v245
	s_nop 1
	v_permlane32_swap_b32 v245, v148
	v_max_f32_e32 v245, v245, v148
	v_sub_f32_e32 v44, v44, v245
	v_sub_f32_e32 v45, v45, v245
	v_sub_f32_e32 v46, v46, v245
	v_sub_f32_e32 v47, v47, v245
	v_exp_f32_e32 v44, v44
	v_exp_f32_e32 v45, v45
	v_exp_f32_e32 v46, v46
	v_exp_f32_e32 v47, v47
	v_sub_f32_e32 v48, v48, v245
	v_sub_f32_e32 v49, v49, v245
	v_sub_f32_e32 v50, v50, v245
	v_sub_f32_e32 v51, v51, v245
	v_exp_f32_e32 v48, v48
	v_exp_f32_e32 v49, v49
	v_exp_f32_e32 v50, v50
	v_exp_f32_e32 v51, v51
	v_mov_b32_e32 v149, v44
	v_mov_b32_e32 v150, v45
	v_mov_b32_e32 v151, v46
	v_mov_b32_e32 v152, v47
	v_cvt_pk_bf16_f32 v44, v44, v45
	v_cvt_pk_bf16_f32 v45, v46, v47
	v_sub_f32_e32 v52, v52, v245
	v_sub_f32_e32 v53, v53, v245
	v_sub_f32_e32 v54, v54, v245
	v_sub_f32_e32 v55, v55, v245
	v_exp_f32_e32 v52, v52
	v_exp_f32_e32 v53, v53
	v_exp_f32_e32 v54, v54
	v_exp_f32_e32 v55, v55
	v_add_f32_e32 v149, v149, v48
	v_add_f32_e32 v150, v150, v49
	v_add_f32_e32 v151, v151, v50
	v_add_f32_e32 v152, v152, v51
	v_cvt_pk_bf16_f32 v46, v48, v49
	v_cvt_pk_bf16_f32 v47, v50, v51
	v_sub_f32_e32 v56, v56, v245
	v_sub_f32_e32 v57, v57, v245
	v_sub_f32_e32 v58, v58, v245
	v_sub_f32_e32 v59, v59, v245
	v_exp_f32_e32 v56, v56
	v_exp_f32_e32 v57, v57
	v_exp_f32_e32 v58, v58
	v_exp_f32_e32 v59, v59
	v_add_f32_e32 v149, v149, v52
	v_add_f32_e32 v150, v150, v53
	v_add_f32_e32 v151, v151, v54
	v_add_f32_e32 v152, v152, v55
	v_cvt_pk_bf16_f32 v52, v52, v53
	v_cvt_pk_bf16_f32 v53, v54, v55
	v_sub_f32_e32 v60, v60, v245
	v_sub_f32_e32 v61, v61, v245
	v_sub_f32_e32 v62, v62, v245
	v_sub_f32_e32 v63, v63, v245
	v_exp_f32_e32 v60, v60
	v_exp_f32_e32 v61, v61
	v_exp_f32_e32 v62, v62
	v_exp_f32_e32 v63, v63
	v_add_f32_e32 v149, v149, v56
	v_add_f32_e32 v150, v150, v57
	v_add_f32_e32 v151, v151, v58
	v_add_f32_e32 v152, v152, v59
	v_cvt_pk_bf16_f32 v54, v56, v57
	v_cvt_pk_bf16_f32 v55, v58, v59
	v_sub_f32_e32 v64, v64, v245
	v_sub_f32_e32 v65, v65, v245
	v_sub_f32_e32 v66, v66, v245
	v_sub_f32_e32 v67, v67, v245
	v_exp_f32_e32 v64, v64
	v_exp_f32_e32 v65, v65
	v_exp_f32_e32 v66, v66
	v_exp_f32_e32 v67, v67
	v_add_f32_e32 v149, v149, v60
	v_add_f32_e32 v150, v150, v61
	v_add_f32_e32 v151, v151, v62
	v_add_f32_e32 v152, v152, v63
	v_cvt_pk_bf16_f32 v60, v60, v61
	v_cvt_pk_bf16_f32 v61, v62, v63
	v_sub_f32_e32 v68, v68, v245
	v_sub_f32_e32 v69, v69, v245
	v_sub_f32_e32 v70, v70, v245
	v_sub_f32_e32 v71, v71, v245
	v_exp_f32_e32 v68, v68
	v_exp_f32_e32 v69, v69
	v_exp_f32_e32 v70, v70
	v_exp_f32_e32 v71, v71
	v_add_f32_e32 v149, v149, v64
	v_add_f32_e32 v150, v150, v65
	v_add_f32_e32 v151, v151, v66
	v_add_f32_e32 v152, v152, v67
	v_cvt_pk_bf16_f32 v62, v64, v65
	v_cvt_pk_bf16_f32 v63, v66, v67
	v_sub_f32_e32 v72, v72, v245
	v_sub_f32_e32 v73, v73, v245
	v_sub_f32_e32 v74, v74, v245
	v_sub_f32_e32 v75, v75, v245
	v_exp_f32_e32 v72, v72
	v_exp_f32_e32 v73, v73
	v_exp_f32_e32 v74, v74
	v_exp_f32_e32 v75, v75
	v_add_f32_e32 v149, v149, v68
	v_add_f32_e32 v150, v150, v69
	v_add_f32_e32 v151, v151, v70
	v_add_f32_e32 v152, v152, v71
	v_cvt_pk_bf16_f32 v68, v68, v69
	v_cvt_pk_bf16_f32 v69, v70, v71
	v_sub_f32_e32 v76, v76, v245
	v_sub_f32_e32 v77, v77, v245
	v_sub_f32_e32 v78, v78, v245
	v_sub_f32_e32 v79, v79, v245
	v_exp_f32_e32 v76, v76
	v_exp_f32_e32 v77, v77
	v_exp_f32_e32 v78, v78
	v_exp_f32_e32 v79, v79
	v_add_f32_e32 v149, v149, v72
	v_add_f32_e32 v150, v150, v73
	v_add_f32_e32 v151, v151, v74
	v_add_f32_e32 v152, v152, v75
	v_cvt_pk_bf16_f32 v70, v72, v73
	v_cvt_pk_bf16_f32 v71, v74, v75
	s_nop 0
	v_add_f32_e32 v149, v149, v76
	v_add_f32_e32 v150, v150, v77
	v_add_f32_e32 v151, v151, v78
	v_add_f32_e32 v152, v152, v79
	v_cvt_pk_bf16_f32 v76, v76, v77
	v_cvt_pk_bf16_f32 v77, v78, v79
	v_mov_b32_e32 v78, 0
	v_mov_b32_e32 v79, 0
	v_add_f32_e32 v149, v149, v150
	v_add_f32_e32 v151, v151, v152
	v_add_f32_e32 v246, v149, v151
	s_waitcnt lgkmcnt(0)
	v_mfma_f32_16x16x32_bf16 v[80:83], v[4:7], v[44:47], 0
	v_mfma_f32_16x16x32_bf16 v[84:87], v[8:11], v[44:47], 0
	v_mfma_f32_16x16x32_bf16 v[88:91], v[12:15], v[44:47], 0
	v_mfma_f32_16x16x32_bf16 v[92:95], v[16:19], v[44:47], 0
	ds_read_b64 v[4:5], v225 offset:0
	ds_read_b64 v[8:9], v225 offset:4096
	ds_read_b64 v[12:13], v225 offset:8192
	ds_read_b64 v[16:17], v225 offset:12288
	ds_read_b64 v[6:7], v226 offset:0
	ds_read_b64 v[10:11], v226 offset:4096
	ds_read_b64 v[14:15], v226 offset:8192
	ds_read_b64 v[18:19], v226 offset:12288
	v_mfma_f32_16x16x32_bf16 v[80:83], v[20:23], v[52:55], v[80:83]
	v_mfma_f32_16x16x32_bf16 v[84:87], v[24:27], v[52:55], v[84:87]
	v_mfma_f32_16x16x32_bf16 v[88:91], v[28:31], v[52:55], v[88:91]
	v_mfma_f32_16x16x32_bf16 v[92:95], v[32:35], v[52:55], v[92:95]
	ds_read_b64 v[20:21], v227 offset:0
	ds_read_b64 v[24:25], v227 offset:4096
	ds_read_b64 v[28:29], v227 offset:8192
	ds_read_b64 v[32:33], v227 offset:12288
	ds_read_b64 v[22:23], v228 offset:0
	ds_read_b64 v[26:27], v228 offset:4096
	ds_read_b64 v[30:31], v228 offset:8192
	ds_read_b64 v[34:35], v228 offset:12288
	s_waitcnt lgkmcnt(8)
	v_mfma_f32_16x16x32_bf16 v[80:83], v[4:7], v[60:63], v[80:83]
	v_mfma_f32_16x16x32_bf16 v[84:87], v[8:11], v[60:63], v[84:87]
	v_mfma_f32_16x16x32_bf16 v[88:91], v[12:15], v[60:63], v[88:91]
	v_mfma_f32_16x16x32_bf16 v[92:95], v[16:19], v[60:63], v[92:95]
	ds_read_b64 v[4:5], v229 offset:0
	ds_read_b64 v[8:9], v229 offset:4096
	ds_read_b64 v[12:13], v229 offset:8192
	ds_read_b64 v[16:17], v229 offset:12288
	v_mov_b32_e32 v6, 0
	v_mov_b32_e32 v7, 0
	v_mov_b32_e32 v10, 0
	v_mov_b32_e32 v11, 0
	v_mov_b32_e32 v14, 0
	v_mov_b32_e32 v15, 0
	v_mov_b32_e32 v18, 0
	v_mov_b32_e32 v19, 0
	s_waitcnt lgkmcnt(4)
	v_mfma_f32_16x16x32_bf16 v[80:83], v[20:23], v[68:71], v[80:83]
	v_mfma_f32_16x16x32_bf16 v[84:87], v[24:27], v[68:71], v[84:87]
	v_mfma_f32_16x16x32_bf16 v[88:91], v[28:31], v[68:71], v[88:91]
	v_mfma_f32_16x16x32_bf16 v[92:95], v[32:35], v[68:71], v[92:95]
	s_waitcnt lgkmcnt(0)
	v_mfma_f32_16x16x32_bf16 v[80:83], v[4:7], v[76:79], v[80:83]
	v_mfma_f32_16x16x32_bf16 v[84:87], v[8:11], v[76:79], v[84:87]
	v_mfma_f32_16x16x32_bf16 v[88:91], v[12:15], v[76:79], v[88:91]
	v_mfma_f32_16x16x32_bf16 v[92:95], v[16:19], v[76:79], v[92:95]
	v_mov_b32_e32 v148, v246
	s_nop 1
	v_permlane16_swap_b32 v246, v148
	v_add_f32_e32 v246, v246, v148
	v_mov_b32_e32 v148, v246
	s_nop 1
	v_permlane32_swap_b32 v246, v148
	v_add_f32_e32 v246, v246, v148
	v_rcp_f32_e32 v149, v246
	v_log_f32_e32 v150, v246
	s_nop 0
	v_add_f32_e32 v151, v245, v150
	v_mul_f32_e32 v151, 0x3f317218, v151
	v_mov_b32_e32 v140, v151
	v_mul_f32_e32 v80, v80, v149
	v_mul_f32_e32 v81, v81, v149
	v_mul_f32_e32 v82, v82, v149
	v_mul_f32_e32 v83, v83, v149
	v_mul_f32_e32 v84, v84, v149
	v_mul_f32_e32 v85, v85, v149
	v_mul_f32_e32 v86, v86, v149
	v_mul_f32_e32 v87, v87, v149
	v_mul_f32_e32 v88, v88, v149
	v_mul_f32_e32 v89, v89, v149
	v_mul_f32_e32 v90, v90, v149
	v_mul_f32_e32 v91, v91, v149
	v_mul_f32_e32 v92, v92, v149
	v_mul_f32_e32 v93, v93, v149
	v_mul_f32_e32 v94, v94, v149
	v_mul_f32_e32 v95, v95, v149
	v_cvt_pk_bf16_f32 v132, v80, v81
	v_cvt_pk_bf16_f32 v133, v82, v83
	v_cvt_pk_bf16_f32 v134, v84, v85
	v_cvt_pk_bf16_f32 v135, v86, v87
	v_cvt_pk_bf16_f32 v136, v88, v89
	v_cvt_pk_bf16_f32 v137, v90, v91
	v_cvt_pk_bf16_f32 v138, v92, v93
	v_cvt_pk_bf16_f32 v139, v94, v95
	s_mov_b64 s[26:27], s[86:87]
	s_mov_b64 s[28:29], s[88:89]
	s_mov_b64 s[86:87], s[12:13]
	s_mov_b64 s[88:89], s[14:15]
	s_mov_b32 s4, s83
	s_mov_b32 s5, s84
	s_waitcnt vmcnt(0)
	s_barrier
	ds_read_b128 v[4:7], v230 offset:16384
	ds_read_b128 v[8:11], v231 offset:16384
	ds_read_b128 v[12:15], v230 offset:18432
	ds_read_b128 v[16:19], v231 offset:18432
	ds_read_b128 v[20:23], v230 offset:20480
	ds_read_b128 v[24:27], v231 offset:20480
	ds_read_b128 v[28:31], v230 offset:22528
	ds_read_b128 v[32:35], v231 offset:22528
	ds_read_b128 v[36:39], v230 offset:24576
	ds_read_b128 v[40:43], v231 offset:24576
	global_store_dwordx2 v237, v[132:133], s[26:27]
	global_store_dwordx2 v237, v[134:135], s[26:27] offset:32
	global_store_dwordx2 v237, v[136:137], s[26:27] offset:64
	global_store_dwordx2 v237, v[138:139], s[26:27] offset:96
	s_mov_b64 s[90:91], exec
	s_mov_b64 exec, 0xffff
	global_store_dword v238, v140, s[28:29]
	s_mov_b64 exec, s[90:91]
	s_add_u32 s83, s4, 1
	s_mov_b32 s84, s5
	s_mul_i32 s74, s84, 4096
	s_lshl_b32 s75, s83, 7
	s_add_u32 s74, s74, s75
	s_lshl_b32 s75, s74, 7
	s_add_u32 s16, s60, s75
	s_addc_u32 s17, s61, 0
	s_lshl_b32 s75, s74, 1
	s_add_u32 s24, s64, s75
	s_addc_u32 s25, s65, 0
	s_add_u32 m0, s70, 0xc000
	s_nop 0
	global_load_lds_dwordx4 v232, s[16:17] nt
	s_add_u32 m0, s70, 0xe000
	s_nop 0
	global_load_lds_dwordx4 v233, s[16:17] nt
	s_add_u32 m0, s70, 0x1c000
	s_nop 0
	global_load_lds_dwordx4 v234, s[24:25] nt
	s_add_u32 m0, s70, 0x1e000
	s_nop 0
	global_load_lds_dwordx4 v235, s[24:25] nt
	s_lshl_b32 s74, s83, 7
	s_add_u32 s74, s74, s84
	s_lshl_b32 s75, s74, 7
	s_add_u32 s10, s30, s75
	s_addc_u32 s11, s31, 0
	s_add_u32 s12, s34, s75
	s_addc_u32 s13, s35, 0
	s_lshl_b32 s75, s74, 2
	s_add_u32 s14, s58, s75
	s_addc_u32 s15, s59, 0
	global_load_dwordx4 v[104:107], v236, s[10:11]
	global_load_dwordx4 v[108:111], v236, s[10:11] offset:64
	s_waitcnt lgkmcnt(0)
	v_mfma_f32_16x16x32_bf16 v[44:47], v[4:7], v[96:99], 0
	v_mfma_f32_16x16x32_bf16 v[48:51], v[12:15], v[96:99], 0
	v_mfma_f32_16x16x32_bf16 v[52:55], v[20:23], v[96:99], 0
	v_mfma_f32_16x16x32_bf16 v[56:59], v[28:31], v[96:99], 0
	v_mfma_f32_16x16x32_bf16 v[60:63], v[36:39], v[96:99], 0
	v_mfma_f32_16x16x32_bf16 v[44:47], v[8:11], v[100:103], v[44:47]
	v_mfma_f32_16x16x32_bf16 v[48:51], v[16:19], v[100:103], v[48:51]
	v_mfma_f32_16x16x32_bf16 v[52:55], v[24:27], v[100:103], v[52:55]
	v_mfma_f32_16x16x32_bf16 v[56:59], v[32:35], v[100:103], v[56:59]
	v_mfma_f32_16x16x32_bf16 v[60:63], v[40:43], v[100:103], v[60:63]
	ds_read_b128 v[4:7], v230 offset:26624
	ds_read_b128 v[8:11], v231 offset:26624
	ds_read_b128 v[12:15], v230 offset:28672
	ds_read_b128 v[16:19], v231 offset:28672
	ds_read_b128 v[20:23], v230 offset:30720
	ds_read_b128 v[24:27], v231 offset:30720
	ds_read_b128 v[28:31], v230 offset:32768
	ds_read_b128 v[32:35], v231 offset:32768
	s_nop 1
	v_fma_f32 v44, v44, s79, v185
	v_fma_f32 v45, v45, s79, v186
	v_fma_f32 v46, v46, s79, v187
	v_fma_f32 v47, v47, s79, v188
	v_fma_f32 v48, v48, s79, v189
	v_fma_f32 v49, v49, s79, v190
	v_fma_f32 v50, v50, s79, v191
	v_fma_f32 v51, v51, s79, v192
	v_fma_f32 v52, v52, s79, v193
	v_fma_f32 v53, v53, s79, v194
	v_fma_f32 v54, v54, s79, v195
	v_fma_f32 v55, v55, s79, v196
	v_fma_f32 v56, v56, s79, v197
	v_fma_f32 v57, v57, s79, v198
	v_fma_f32 v58, v58, s79, v199
	v_fma_f32 v59, v59, s79, v200
	v_fma_f32 v60, v60, s79, v201
	v_fma_f32 v61, v61, s79, v202
	v_fma_f32 v62, v62, s79, v203
	v_fma_f32 v63, v63, s79, v204
	s_waitcnt lgkmcnt(0)
	v_mfma_f32_16x16x32_bf16 v[64:67], v[4:7], v[96:99], 0
	v_mfma_f32_16x16x32_bf16 v[68:71], v[12:15], v[96:99], 0
	v_mfma_f32_16x16x32_bf16 v[72:75], v[20:23], v[96:99], 0
	v_mfma_f32_16x16x32_bf16 v[76:79], v[28:31], v[96:99], 0
	v_mfma_f32_16x16x32_bf16 v[64:67], v[8:11], v[100:103], v[64:67]
	v_mfma_f32_16x16x32_bf16 v[68:71], v[16:19], v[100:103], v[68:71]
	v_mfma_f32_16x16x32_bf16 v[72:75], v[24:27], v[100:103], v[72:75]
	v_mfma_f32_16x16x32_bf16 v[76:79], v[32:35], v[100:103], v[76:79]
	ds_read_b64 v[4:5], v221 offset:16384
	ds_read_b64 v[8:9], v221 offset:20480
	ds_read_b64 v[12:13], v221 offset:24576
	ds_read_b64 v[16:17], v221 offset:28672
	ds_read_b64 v[6:7], v222 offset:16384
	ds_read_b64 v[10:11], v222 offset:20480
	ds_read_b64 v[14:15], v222 offset:24576
	ds_read_b64 v[18:19], v222 offset:28672
	s_nop 1
	v_fma_f32 v64, v64, s79, v205
	v_fma_f32 v65, v65, s79, v206
	v_fma_f32 v66, v66, s79, v207
	v_fma_f32 v67, v67, s79, v208
	v_fma_f32 v68, v68, s79, v209
	v_fma_f32 v69, v69, s79, v210
	v_fma_f32 v70, v70, s79, v211
	v_fma_f32 v71, v71, s79, v212
	v_fma_f32 v72, v72, s79, v213
	v_fma_f32 v73, v73, s79, v214
	v_fma_f32 v74, v74, s79, v215
	v_fma_f32 v75, v75, s79, v216
	v_fma_f32 v76, v76, s79, v217
	v_fma_f32 v77, v77, s79, v218
	v_fma_f32 v78, v78, s79, v219
	v_fma_f32 v79, v79, s79, v220
	ds_read_b64 v[20:21], v223 offset:16384
	ds_read_b64 v[24:25], v223 offset:20480
	ds_read_b64 v[28:29], v223 offset:24576
	ds_read_b64 v[32:33], v223 offset:28672
	ds_read_b64 v[22:23], v224 offset:16384
	ds_read_b64 v[26:27], v224 offset:20480
	ds_read_b64 v[30:31], v224 offset:24576
	ds_read_b64 v[34:35], v224 offset:28672
	s_cmp_lg_u32 s4, 0
	s_cbranch_scc1 .Lat738_i2_nomask
	s_cmp_le_u32 s6, 0
	s_cbranch_scc1 .Lat738_i2_nomask
	v_mov_b32_e32 v44, v244
	v_mov_b32_e32 v45, v244
	v_mov_b32_e32 v46, v244
	v_mov_b32_e32 v47, v244
	s_cmp_le_u32 s6, 1
	s_cbranch_scc1 .Lat738_i2_nomask
	v_mov_b32_e32 v48, v244
	v_mov_b32_e32 v49, v244
	v_mov_b32_e32 v50, v244
	v_mov_b32_e32 v51, v244
	s_cmp_le_u32 s6, 2
	s_cbranch_scc1 .Lat738_i2_nomask
	v_mov_b32_e32 v52, v244
	v_mov_b32_e32 v53, v244
	v_mov_b32_e32 v54, v244
	v_mov_b32_e32 v55, v244
	s_cmp_le_u32 s6, 3
	s_cbranch_scc1 .Lat738_i2_nomask
	v_mov_b32_e32 v56, v244
	v_mov_b32_e32 v57, v244
	v_mov_b32_e32 v58, v244
	v_mov_b32_e32 v59, v244
	s_cmp_le_u32 s6, 4
	s_cbranch_scc1 .Lat738_i2_nomask
	v_mov_b32_e32 v60, v244
	v_mov_b32_e32 v61, v244
	v_mov_b32_e32 v62, v244
	v_mov_b32_e32 v63, v244
	s_cmp_le_u32 s6, 5
	s_cbranch_scc1 .Lat738_i2_nomask
	v_mov_b32_e32 v64, v244
	v_mov_b32_e32 v65, v244
	v_mov_b32_e32 v66, v244
	v_mov_b32_e32 v67, v244
	s_cmp_le_u32 s6, 6
	s_cbranch_scc1 .Lat738_i2_nomask
	v_mov_b32_e32 v68, v244
	v_mov_b32_e32 v69, v244
	v_mov_b32_e32 v70, v244
	v_mov_b32_e32 v71, v244
	s_cmp_le_u32 s6, 7
	s_cbranch_scc1 .Lat738_i2_nomask
	v_mov_b32_e32 v72, v244
	v_mov_b32_e32 v73, v244
	v_mov_b32_e32 v74, v244
	v_mov_b32_e32 v75, v244
.Lat738_i2_nomask:
	v_max3_f32 v245, v44, v45, v46
	v_max3_f32 v245, v245, v47, v48
	v_max3_f32 v245, v245, v49, v50
	v_max3_f32 v245, v245, v51, v52
	v_max3_f32 v245, v245, v53, v54
	v_max3_f32 v245, v245, v55, v56
	v_max3_f32 v245, v245, v57, v58
	v_max3_f32 v245, v245, v59, v60
	v_max3_f32 v245, v245, v61, v62
	v_max3_f32 v245, v245, v63, v64
	v_max3_f32 v245, v245, v65, v66
	v_max3_f32 v245, v245, v67, v68
	v_max3_f32 v245, v245, v69, v70
	v_max3_f32 v245, v245, v71, v72
	v_max3_f32 v245, v245, v73, v74
	v_max3_f32 v245, v245, v75, v76
	v_max3_f32 v245, v245, v77, v78
	v_max_f32_e32 v245, v245, v79
	v_mov_b32_e32 v148, v245
	s_nop 1
	v_permlane16_swap_b32 v245, v148
	v_max_f32_e32 v245, v245, v148
	v_mov_b32_e32 v148, v245
	s_nop 1
	v_permlane32_swap_b32 v245, v148
	v_max_f32_e32 v245, v245, v148
	v_sub_f32_e32 v44, v44, v245
	v_sub_f32_e32 v45, v45, v245
	v_sub_f32_e32 v46, v46, v245
	v_sub_f32_e32 v47, v47, v245
	v_exp_f32_e32 v44, v44
	v_exp_f32_e32 v45, v45
	v_exp_f32_e32 v46, v46
	v_exp_f32_e32 v47, v47
	v_sub_f32_e32 v48, v48, v245
	v_sub_f32_e32 v49, v49, v245
	v_sub_f32_e32 v50, v50, v245
	v_sub_f32_e32 v51, v51, v245
	v_exp_f32_e32 v48, v48
	v_exp_f32_e32 v49, v49
	v_exp_f32_e32 v50, v50
	v_exp_f32_e32 v51, v51
	v_mov_b32_e32 v149, v44
	v_mov_b32_e32 v150, v45
	v_mov_b32_e32 v151, v46
	v_mov_b32_e32 v152, v47
	v_cvt_pk_bf16_f32 v44, v44, v45
	v_cvt_pk_bf16_f32 v45, v46, v47
	v_sub_f32_e32 v52, v52, v245
	v_sub_f32_e32 v53, v53, v245
	v_sub_f32_e32 v54, v54, v245
	v_sub_f32_e32 v55, v55, v245
	v_exp_f32_e32 v52, v52
	v_exp_f32_e32 v53, v53
	v_exp_f32_e32 v54, v54
	v_exp_f32_e32 v55, v55
	v_add_f32_e32 v149, v149, v48
	v_add_f32_e32 v150, v150, v49
	v_add_f32_e32 v151, v151, v50
	v_add_f32_e32 v152, v152, v51
	v_cvt_pk_bf16_f32 v46, v48, v49
	v_cvt_pk_bf16_f32 v47, v50, v51
	v_sub_f32_e32 v56, v56, v245
	v_sub_f32_e32 v57, v57, v245
	v_sub_f32_e32 v58, v58, v245
	v_sub_f32_e32 v59, v59, v245
	v_exp_f32_e32 v56, v56
	v_exp_f32_e32 v57, v57
	v_exp_f32_e32 v58, v58
	v_exp_f32_e32 v59, v59
	v_add_f32_e32 v149, v149, v52
	v_add_f32_e32 v150, v150, v53
	v_add_f32_e32 v151, v151, v54
	v_add_f32_e32 v152, v152, v55
	v_cvt_pk_bf16_f32 v52, v52, v53
	v_cvt_pk_bf16_f32 v53, v54, v55
	v_sub_f32_e32 v60, v60, v245
	v_sub_f32_e32 v61, v61, v245
	v_sub_f32_e32 v62, v62, v245
	v_sub_f32_e32 v63, v63, v245
	v_exp_f32_e32 v60, v60
	v_exp_f32_e32 v61, v61
	v_exp_f32_e32 v62, v62
	v_exp_f32_e32 v63, v63
	v_add_f32_e32 v149, v149, v56
	v_add_f32_e32 v150, v150, v57
	v_add_f32_e32 v151, v151, v58
	v_add_f32_e32 v152, v152, v59
	v_cvt_pk_bf16_f32 v54, v56, v57
	v_cvt_pk_bf16_f32 v55, v58, v59
	v_sub_f32_e32 v64, v64, v245
	v_sub_f32_e32 v65, v65, v245
	v_sub_f32_e32 v66, v66, v245
	v_sub_f32_e32 v67, v67, v245
	v_exp_f32_e32 v64, v64
	v_exp_f32_e32 v65, v65
	v_exp_f32_e32 v66, v66
	v_exp_f32_e32 v67, v67
	v_add_f32_e32 v149, v149, v60
	v_add_f32_e32 v150, v150, v61
	v_add_f32_e32 v151, v151, v62
	v_add_f32_e32 v152, v152, v63
	v_cvt_pk_bf16_f32 v60, v60, v61
	v_cvt_pk_bf16_f32 v61, v62, v63
	v_sub_f32_e32 v68, v68, v245
	v_sub_f32_e32 v69, v69, v245
	v_sub_f32_e32 v70, v70, v245
	v_sub_f32_e32 v71, v71, v245
	v_exp_f32_e32 v68, v68
	v_exp_f32_e32 v69, v69
	v_exp_f32_e32 v70, v70
	v_exp_f32_e32 v71, v71
	v_add_f32_e32 v149, v149, v64
	v_add_f32_e32 v150, v150, v65
	v_add_f32_e32 v151, v151, v66
	v_add_f32_e32 v152, v152, v67
	v_cvt_pk_bf16_f32 v62, v64, v65
	v_cvt_pk_bf16_f32 v63, v66, v67
	v_sub_f32_e32 v72, v72, v245
	v_sub_f32_e32 v73, v73, v245
	v_sub_f32_e32 v74, v74, v245
	v_sub_f32_e32 v75, v75, v245
	v_exp_f32_e32 v72, v72
	v_exp_f32_e32 v73, v73
	v_exp_f32_e32 v74, v74
	v_exp_f32_e32 v75, v75
	v_add_f32_e32 v149, v149, v68
	v_add_f32_e32 v150, v150, v69
	v_add_f32_e32 v151, v151, v70
	v_add_f32_e32 v152, v152, v71
	v_cvt_pk_bf16_f32 v68, v68, v69
	v_cvt_pk_bf16_f32 v69, v70, v71
	v_sub_f32_e32 v76, v76, v245
	v_sub_f32_e32 v77, v77, v245
	v_sub_f32_e32 v78, v78, v245
	v_sub_f32_e32 v79, v79, v245
	v_exp_f32_e32 v76, v76
	v_exp_f32_e32 v77, v77
	v_exp_f32_e32 v78, v78
	v_exp_f32_e32 v79, v79
	v_add_f32_e32 v149, v149, v72
	v_add_f32_e32 v150, v150, v73
	v_add_f32_e32 v151, v151, v74
	v_add_f32_e32 v152, v152, v75
	v_cvt_pk_bf16_f32 v70, v72, v73
	v_cvt_pk_bf16_f32 v71, v74, v75
	s_nop 0
	v_add_f32_e32 v149, v149, v76
	v_add_f32_e32 v150, v150, v77
	v_add_f32_e32 v151, v151, v78
	v_add_f32_e32 v152, v152, v79
	v_cvt_pk_bf16_f32 v76, v76, v77
	v_cvt_pk_bf16_f32 v77, v78, v79
	v_mov_b32_e32 v78, 0
	v_mov_b32_e32 v79, 0
	v_add_f32_e32 v149, v149, v150
	v_add_f32_e32 v151, v151, v152
	v_add_f32_e32 v246, v149, v151
	s_waitcnt lgkmcnt(0)
	v_mfma_f32_16x16x32_bf16 v[80:83], v[4:7], v[44:47], 0
	v_mfma_f32_16x16x32_bf16 v[84:87], v[8:11], v[44:47], 0
	v_mfma_f32_16x16x32_bf16 v[88:91], v[12:15], v[44:47], 0
	v_mfma_f32_16x16x32_bf16 v[92:95], v[16:19], v[44:47], 0
	ds_read_b64 v[4:5], v225 offset:16384
	ds_read_b64 v[8:9], v225 offset:20480
	ds_read_b64 v[12:13], v225 offset:24576
	ds_read_b64 v[16:17], v225 offset:28672
	ds_read_b64 v[6:7], v226 offset:16384
	ds_read_b64 v[10:11], v226 offset:20480
	ds_read_b64 v[14:15], v226 offset:24576
	ds_read_b64 v[18:19], v226 offset:28672
	v_mfma_f32_16x16x32_bf16 v[80:83], v[20:23], v[52:55], v[80:83]
	v_mfma_f32_16x16x32_bf16 v[84:87], v[24:27], v[52:55], v[84:87]
	v_mfma_f32_16x16x32_bf16 v[88:91], v[28:31], v[52:55], v[88:91]
	v_mfma_f32_16x16x32_bf16 v[92:95], v[32:35], v[52:55], v[92:95]
	ds_read_b64 v[20:21], v227 offset:16384
	ds_read_b64 v[24:25], v227 offset:20480
	ds_read_b64 v[28:29], v227 offset:24576
	ds_read_b64 v[32:33], v227 offset:28672
	ds_read_b64 v[22:23], v228 offset:16384
	ds_read_b64 v[26:27], v228 offset:20480
	ds_read_b64 v[30:31], v228 offset:24576
	ds_read_b64 v[34:35], v228 offset:28672
	s_waitcnt lgkmcnt(8)
	v_mfma_f32_16x16x32_bf16 v[80:83], v[4:7], v[60:63], v[80:83]
	v_mfma_f32_16x16x32_bf16 v[84:87], v[8:11], v[60:63], v[84:87]
	v_mfma_f32_16x16x32_bf16 v[88:91], v[12:15], v[60:63], v[88:91]
	v_mfma_f32_16x16x32_bf16 v[92:95], v[16:19], v[60:63], v[92:95]
	ds_read_b64 v[4:5], v229 offset:16384
	ds_read_b64 v[8:9], v229 offset:20480
	ds_read_b64 v[12:13], v229 offset:24576
	ds_read_b64 v[16:17], v229 offset:28672
	v_mov_b32_e32 v6, 0
	v_mov_b32_e32 v7, 0
	v_mov_b32_e32 v10, 0
	v_mov_b32_e32 v11, 0
	v_mov_b32_e32 v14, 0
	v_mov_b32_e32 v15, 0
	v_mov_b32_e32 v18, 0
	v_mov_b32_e32 v19, 0
	s_waitcnt lgkmcnt(4)
	v_mfma_f32_16x16x32_bf16 v[80:83], v[20:23], v[68:71], v[80:83]
	v_mfma_f32_16x16x32_bf16 v[84:87], v[24:27], v[68:71], v[84:87]
	v_mfma_f32_16x16x32_bf16 v[88:91], v[28:31], v[68:71], v[88:91]
	v_mfma_f32_16x16x32_bf16 v[92:95], v[32:35], v[68:71], v[92:95]
	s_waitcnt lgkmcnt(0)
	v_mfma_f32_16x16x32_bf16 v[80:83], v[4:7], v[76:79], v[80:83]
	v_mfma_f32_16x16x32_bf16 v[84:87], v[8:11], v[76:79], v[84:87]
	v_mfma_f32_16x16x32_bf16 v[88:91], v[12:15], v[76:79], v[88:91]
	v_mfma_f32_16x16x32_bf16 v[92:95], v[16:19], v[76:79], v[92:95]
	v_mov_b32_e32 v148, v246
	s_nop 1
	v_permlane16_swap_b32 v246, v148
	v_add_f32_e32 v246, v246, v148
	v_mov_b32_e32 v148, v246
	s_nop 1
	v_permlane32_swap_b32 v246, v148
	v_add_f32_e32 v246, v246, v148
	v_rcp_f32_e32 v149, v246
	v_log_f32_e32 v150, v246
	s_nop 0
	v_add_f32_e32 v151, v245, v150
	v_mul_f32_e32 v151, 0x3f317218, v151
	v_mov_b32_e32 v140, v151
	v_mul_f32_e32 v80, v80, v149
	v_mul_f32_e32 v81, v81, v149
	v_mul_f32_e32 v82, v82, v149
	v_mul_f32_e32 v83, v83, v149
	v_mul_f32_e32 v84, v84, v149
	v_mul_f32_e32 v85, v85, v149
	v_mul_f32_e32 v86, v86, v149
	v_mul_f32_e32 v87, v87, v149
	v_mul_f32_e32 v88, v88, v149
	v_mul_f32_e32 v89, v89, v149
	v_mul_f32_e32 v90, v90, v149
	v_mul_f32_e32 v91, v91, v149
	v_mul_f32_e32 v92, v92, v149
	v_mul_f32_e32 v93, v93, v149
	v_mul_f32_e32 v94, v94, v149
	v_mul_f32_e32 v95, v95, v149
	v_cvt_pk_bf16_f32 v132, v80, v81
	v_cvt_pk_bf16_f32 v133, v82, v83
	v_cvt_pk_bf16_f32 v134, v84, v85
	v_cvt_pk_bf16_f32 v135, v86, v87
	v_cvt_pk_bf16_f32 v136, v88, v89
	v_cvt_pk_bf16_f32 v137, v90, v91
	v_cvt_pk_bf16_f32 v138, v92, v93
	v_cvt_pk_bf16_f32 v139, v94, v95
	s_mov_b64 s[26:27], s[86:87]
	s_mov_b64 s[28:29], s[88:89]
	s_mov_b64 s[86:87], s[12:13]
	s_mov_b64 s[88:89], s[14:15]
	s_mov_b32 s4, s83
	s_mov_b32 s5, s84
	s_waitcnt vmcnt(0)
	s_barrier
	ds_read_b128 v[4:7], v230 offset:32768
	ds_read_b128 v[8:11], v231 offset:32768
	ds_read_b128 v[12:15], v230 offset:34816
	ds_read_b128 v[16:19], v231 offset:34816
	ds_read_b128 v[20:23], v230 offset:36864
	ds_read_b128 v[24:27], v231 offset:36864
	ds_read_b128 v[28:31], v230 offset:38912
	ds_read_b128 v[32:35], v231 offset:38912
	ds_read_b128 v[36:39], v230 offset:40960
	ds_read_b128 v[40:43], v231 offset:40960
	global_store_dwordx2 v237, v[132:133], s[26:27]
	global_store_dwordx2 v237, v[134:135], s[26:27] offset:32
	global_store_dwordx2 v237, v[136:137], s[26:27] offset:64
	global_store_dwordx2 v237, v[138:139], s[26:27] offset:96
	s_mov_b64 s[90:91], exec
	s_mov_b64 exec, 0xffff
	global_store_dword v238, v140, s[28:29]
	s_mov_b64 exec, s[90:91]
	s_cmp_eq_u32 s7, 1
	s_cbranch_scc1 .Lat738_i3_nonext
	s_add_u32 s83, s4, 1
	s_mov_b32 s84, s5
	s_mul_i32 s74, s84, 4096
	s_lshl_b32 s75, s83, 7
	s_add_u32 s74, s74, s75
	s_lshl_b32 s75, s74, 7
	s_add_u32 s16, s60, s75
	s_addc_u32 s17, s61, 0
	s_lshl_b32 s75, s74, 1
	s_add_u32 s24, s64, s75
	s_addc_u32 s25, s65, 0
	s_add_u32 m0, s70, 0x0
	s_nop 0
	global_load_lds_dwordx4 v232, s[16:17] nt
	s_add_u32 m0, s70, 0x2000
	s_nop 0
	global_load_lds_dwordx4 v233, s[16:17] nt
	s_add_u32 m0, s70, 0x10000
	s_nop 0
	global_load_lds_dwordx4 v234, s[24:25] nt
	s_add_u32 m0, s70, 0x12000
	s_nop 0
	global_load_lds_dwordx4 v235, s[24:25] nt
	s_lshl_b32 s74, s83, 7
	s_add_u32 s74, s74, s84
	s_lshl_b32 s75, s74, 7
	s_add_u32 s10, s30, s75
	s_addc_u32 s11, s31, 0
	s_add_u32 s12, s34, s75
	s_addc_u32 s13, s35, 0
	s_lshl_b32 s75, s74, 2
	s_add_u32 s14, s58, s75
	s_addc_u32 s15, s59, 0
	global_load_dwordx4 v[96:99], v236, s[10:11]
	global_load_dwordx4 v[100:103], v236, s[10:11] offset:64

.Lat738_i3_nomask:
	v_max3_f32 v245, v44, v45, v46
	v_max3_f32 v245, v245, v47, v48
	v_max3_f32 v245, v245, v49, v50
	v_max3_f32 v245, v245, v51, v52
	v_max3_f32 v245, v245, v53, v54
	v_max3_f32 v245, v245, v55, v56
	v_max3_f32 v245, v245, v57, v58
	v_max3_f32 v245, v245, v59, v60
	v_max3_f32 v245, v245, v61, v62
	v_max3_f32 v245, v245, v63, v64
	v_max3_f32 v245, v245, v65, v66
	v_max3_f32 v245, v245, v67, v68
	v_max3_f32 v245, v245, v69, v70
	v_max3_f32 v245, v245, v71, v72
	v_max3_f32 v245, v245, v73, v74
	v_max3_f32 v245, v245, v75, v76
	v_max3_f32 v245, v245, v77, v78
	v_max_f32_e32 v245, v245, v79
	v_mov_b32_e32 v148, v245
	s_nop 1
	v_permlane16_swap_b32 v245, v148
	v_max_f32_e32 v245, v245, v148
	v_mov_b32_e32 v148, v245
	s_nop 1
	v_permlane32_swap_b32 v245, v148
	v_max_f32_e32 v245, v245, v148
	v_sub_f32_e32 v44, v44, v245
	v_sub_f32_e32 v45, v45, v245
	v_sub_f32_e32 v46, v46, v245
	v_sub_f32_e32 v47, v47, v245
	v_exp_f32_e32 v44, v44
	v_exp_f32_e32 v45, v45
	v_exp_f32_e32 v46, v46
	v_exp_f32_e32 v47, v47
	v_sub_f32_e32 v48, v48, v245
	v_sub_f32_e32 v49, v49, v245
	v_sub_f32_e32 v50, v50, v245
	v_sub_f32_e32 v51, v51, v245
	v_exp_f32_e32 v48, v48
	v_exp_f32_e32 v49, v49
	v_exp_f32_e32 v50, v50
	v_exp_f32_e32 v51, v51
	v_mov_b32_e32 v149, v44
	v_mov_b32_e32 v150, v45
	v_mov_b32_e32 v151, v46
	v_mov_b32_e32 v152, v47
	v_cvt_pk_bf16_f32 v44, v44, v45
	v_cvt_pk_bf16_f32 v45, v46, v47
	v_sub_f32_e32 v52, v52, v245
	v_sub_f32_e32 v53, v53, v245
	v_sub_f32_e32 v54, v54, v245
	v_sub_f32_e32 v55, v55, v245
	v_exp_f32_e32 v52, v52
	v_exp_f32_e32 v53, v53
	v_exp_f32_e32 v54, v54
	v_exp_f32_e32 v55, v55
	v_add_f32_e32 v149, v149, v48
	v_add_f32_e32 v150, v150, v49
	v_add_f32_e32 v151, v151, v50
	v_add_f32_e32 v152, v152, v51
	v_cvt_pk_bf16_f32 v46, v48, v49
	v_cvt_pk_bf16_f32 v47, v50, v51
	v_sub_f32_e32 v56, v56, v245
	v_sub_f32_e32 v57, v57, v245
	v_sub_f32_e32 v58, v58, v245
	v_sub_f32_e32 v59, v59, v245
	v_exp_f32_e32 v56, v56
	v_exp_f32_e32 v57, v57
	v_exp_f32_e32 v58, v58
	v_exp_f32_e32 v59, v59
	v_add_f32_e32 v149, v149, v52
	v_add_f32_e32 v150, v150, v53
	v_add_f32_e32 v151, v151, v54
	v_add_f32_e32 v152, v152, v55
	v_cvt_pk_bf16_f32 v52, v52, v53
	v_cvt_pk_bf16_f32 v53, v54, v55
	v_sub_f32_e32 v60, v60, v245
	v_sub_f32_e32 v61, v61, v245
	v_sub_f32_e32 v62, v62, v245
	v_sub_f32_e32 v63, v63, v245
	v_exp_f32_e32 v60, v60
	v_exp_f32_e32 v61, v61
	v_exp_f32_e32 v62, v62
	v_exp_f32_e32 v63, v63
	v_add_f32_e32 v149, v149, v56
	v_add_f32_e32 v150, v150, v57
	v_add_f32_e32 v151, v151, v58
	v_add_f32_e32 v152, v152, v59
	v_cvt_pk_bf16_f32 v54, v56, v57
	v_cvt_pk_bf16_f32 v55, v58, v59
	v_sub_f32_e32 v64, v64, v245
	v_sub_f32_e32 v65, v65, v245
	v_sub_f32_e32 v66, v66, v245
	v_sub_f32_e32 v67, v67, v245
	v_exp_f32_e32 v64, v64
	v_exp_f32_e32 v65, v65
	v_exp_f32_e32 v66, v66
	v_exp_f32_e32 v67, v67
	v_add_f32_e32 v149, v149, v60
	v_add_f32_e32 v150, v150, v61
	v_add_f32_e32 v151, v151, v62
	v_add_f32_e32 v152, v152, v63
	v_cvt_pk_bf16_f32 v60, v60, v61
	v_cvt_pk_bf16_f32 v61, v62, v63
	v_sub_f32_e32 v68, v68, v245
	v_sub_f32_e32 v69, v69, v245
	v_sub_f32_e32 v70, v70, v245
	v_sub_f32_e32 v71, v71, v245
	v_exp_f32_e32 v68, v68
	v_exp_f32_e32 v69, v69
	v_exp_f32_e32 v70, v70
	v_exp_f32_e32 v71, v71
	v_add_f32_e32 v149, v149, v64
	v_add_f32_e32 v150, v150, v65
	v_add_f32_e32 v151, v151, v66
	v_add_f32_e32 v152, v152, v67
	v_cvt_pk_bf16_f32 v62, v64, v65
	v_cvt_pk_bf16_f32 v63, v66, v67
	v_sub_f32_e32 v72, v72, v245
	v_sub_f32_e32 v73, v73, v245
	v_sub_f32_e32 v74, v74, v245
	v_sub_f32_e32 v75, v75, v245
	v_exp_f32_e32 v72, v72
	v_exp_f32_e32 v73, v73
	v_exp_f32_e32 v74, v74
	v_exp_f32_e32 v75, v75
	v_add_f32_e32 v149, v149, v68
	v_add_f32_e32 v150, v150, v69
	v_add_f32_e32 v151, v151, v70
	v_add_f32_e32 v152, v152, v71
	v_cvt_pk_bf16_f32 v68, v68, v69
	v_cvt_pk_bf16_f32 v69, v70, v71
	v_sub_f32_e32 v76, v76, v245
	v_sub_f32_e32 v77, v77, v245
	v_sub_f32_e32 v78, v78, v245
	v_sub_f32_e32 v79, v79, v245
	v_exp_f32_e32 v76, v76
	v_exp_f32_e32 v77, v77
	v_exp_f32_e32 v78, v78
	v_exp_f32_e32 v79, v79
	v_add_f32_e32 v149, v149, v72
	v_add_f32_e32 v150, v150, v73
	v_add_f32_e32 v151, v151, v74
	v_add_f32_e32 v152, v152, v75
	v_cvt_pk_bf16_f32 v70, v72, v73
	v_cvt_pk_bf16_f32 v71, v74, v75
	s_nop 0
	v_add_f32_e32 v149, v149, v76
	v_add_f32_e32 v150, v150, v77
	v_add_f32_e32 v151, v151, v78
	v_add_f32_e32 v152, v152, v79
	v_cvt_pk_bf16_f32 v76, v76, v77
	v_cvt_pk_bf16_f32 v77, v78, v79
	v_mov_b32_e32 v78, 0
	v_mov_b32_e32 v79, 0
	v_add_f32_e32 v149, v149, v150
	v_add_f32_e32 v151, v151, v152
	v_add_f32_e32 v246, v149, v151
	s_waitcnt lgkmcnt(0)
	v_mfma_f32_16x16x32_bf16 v[80:83], v[4:7], v[44:47], 0
	v_mfma_f32_16x16x32_bf16 v[84:87], v[8:11], v[44:47], 0
	v_mfma_f32_16x16x32_bf16 v[88:91], v[12:15], v[44:47], 0
	v_mfma_f32_16x16x32_bf16 v[92:95], v[16:19], v[44:47], 0
	ds_read_b64 v[4:5], v225 offset:32768
	ds_read_b64 v[8:9], v225 offset:36864
	ds_read_b64 v[12:13], v225 offset:40960
	ds_read_b64 v[16:17], v225 offset:45056
	ds_read_b64 v[6:7], v226 offset:32768
	ds_read_b64 v[10:11], v226 offset:36864
	ds_read_b64 v[14:15], v226 offset:40960
	ds_read_b64 v[18:19], v226 offset:45056
	v_mfma_f32_16x16x32_bf16 v[80:83], v[20:23], v[52:55], v[80:83]
	v_mfma_f32_16x16x32_bf16 v[84:87], v[24:27], v[52:55], v[84:87]
	v_mfma_f32_16x16x32_bf16 v[88:91], v[28:31], v[52:55], v[88:91]
	v_mfma_f32_16x16x32_bf16 v[92:95], v[32:35], v[52:55], v[92:95]
	ds_read_b64 v[20:21], v227 offset:32768
	ds_read_b64 v[24:25], v227 offset:36864
	ds_read_b64 v[28:29], v227 offset:40960
	ds_read_b64 v[32:33], v227 offset:45056
	ds_read_b64 v[22:23], v228 offset:32768
	ds_read_b64 v[26:27], v228 offset:36864
	ds_read_b64 v[30:31], v228 offset:40960
	ds_read_b64 v[34:35], v228 offset:45056
	s_waitcnt lgkmcnt(8)
	v_mfma_f32_16x16x32_bf16 v[80:83], v[4:7], v[60:63], v[80:83]
	v_mfma_f32_16x16x32_bf16 v[84:87], v[8:11], v[60:63], v[84:87]
	v_mfma_f32_16x16x32_bf16 v[88:91], v[12:15], v[60:63], v[88:91]
	v_mfma_f32_16x16x32_bf16 v[92:95], v[16:19], v[60:63], v[92:95]
	ds_read_b64 v[4:5], v229 offset:32768
	ds_read_b64 v[8:9], v229 offset:36864
	ds_read_b64 v[12:13], v229 offset:40960
	ds_read_b64 v[16:17], v229 offset:45056
	v_mov_b32_e32 v6, 0
	v_mov_b32_e32 v7, 0
	v_mov_b32_e32 v10, 0
	v_mov_b32_e32 v11, 0
	v_mov_b32_e32 v14, 0
	v_mov_b32_e32 v15, 0
	v_mov_b32_e32 v18, 0
	v_mov_b32_e32 v19, 0
	s_waitcnt lgkmcnt(4)
	v_mfma_f32_16x16x32_bf16 v[80:83], v[20:23], v[68:71], v[80:83]
	v_mfma_f32_16x16x32_bf16 v[84:87], v[24:27], v[68:71], v[84:87]
	v_mfma_f32_16x16x32_bf16 v[88:91], v[28:31], v[68:71], v[88:91]
	v_mfma_f32_16x16x32_bf16 v[92:95], v[32:35], v[68:71], v[92:95]
	s_waitcnt lgkmcnt(0)
	v_mfma_f32_16x16x32_bf16 v[80:83], v[4:7], v[76:79], v[80:83]
	v_mfma_f32_16x16x32_bf16 v[84:87], v[8:11], v[76:79], v[84:87]
	v_mfma_f32_16x16x32_bf16 v[88:91], v[12:15], v[76:79], v[88:91]
	v_mfma_f32_16x16x32_bf16 v[92:95], v[16:19], v[76:79], v[92:95]
	v_mov_b32_e32 v148, v246
	s_nop 1
	v_permlane16_swap_b32 v246, v148
	v_add_f32_e32 v246, v246, v148
	v_mov_b32_e32 v148, v246
	s_nop 1
	v_permlane32_swap_b32 v246, v148
	v_add_f32_e32 v246, v246, v148
	v_rcp_f32_e32 v149, v246
	v_log_f32_e32 v150, v246
	s_nop 0
	v_add_f32_e32 v151, v245, v150
	v_mul_f32_e32 v151, 0x3f317218, v151
	v_mov_b32_e32 v140, v151
	v_mul_f32_e32 v80, v80, v149
	v_mul_f32_e32 v81, v81, v149
	v_mul_f32_e32 v82, v82, v149
	v_mul_f32_e32 v83, v83, v149
	v_mul_f32_e32 v84, v84, v149
	v_mul_f32_e32 v85, v85, v149
	v_mul_f32_e32 v86, v86, v149
	v_mul_f32_e32 v87, v87, v149
	v_mul_f32_e32 v88, v88, v149
	v_mul_f32_e32 v89, v89, v149
	v_mul_f32_e32 v90, v90, v149
	v_mul_f32_e32 v91, v91, v149
	v_mul_f32_e32 v92, v92, v149
	v_mul_f32_e32 v93, v93, v149
	v_mul_f32_e32 v94, v94, v149
	v_mul_f32_e32 v95, v95, v149
	v_cvt_pk_bf16_f32 v132, v80, v81
	v_cvt_pk_bf16_f32 v133, v82, v83
	v_cvt_pk_bf16_f32 v134, v84, v85
	v_cvt_pk_bf16_f32 v135, v86, v87
	v_cvt_pk_bf16_f32 v136, v88, v89
	v_cvt_pk_bf16_f32 v137, v90, v91
	v_cvt_pk_bf16_f32 v138, v92, v93
	v_cvt_pk_bf16_f32 v139, v94, v95
	s_mov_b64 s[26:27], s[86:87]
	s_mov_b64 s[28:29], s[88:89]
	s_mov_b64 s[86:87], s[12:13]
	s_mov_b64 s[88:89], s[14:15]
	s_mov_b32 s4, s83
	s_mov_b32 s5, s84
	s_add_u32 s7, s7, 1
	s_cmp_lt_u32 s7, 2
	s_cbranch_scc1 .Lat738_loop
	s_setprio 0
	global_store_dwordx2 v237, v[132:133], s[26:27]
	global_store_dwordx2 v237, v[134:135], s[26:27] offset:32
	global_store_dwordx2 v237, v[136:137], s[26:27] offset:64
	global_store_dwordx2 v237, v[138:139], s[26:27] offset:96
	s_mov_b64 s[90:91], exec
	s_mov_b64 exec, 0xffff
	global_store_dword v238, v140, s[28:29]
	s_mov_b64 exec, s[90:91]
	s_mov_b64 s[0:1], s[42:43]
	v_writelane_b32 v253, s0, 4
	s_waitcnt vmcnt(0)
	v_readlane_b32 s34, v252, 27
	v_readlane_b32 s36, v252, 29
	v_writelane_b32 v253, s1, 5
	v_readlane_b32 s70, v252, 31
	v_readlane_b32 s56, v253, 19
	v_readlane_b32 s16, v253, 21
	v_readlane_b32 s74, v252, 33
	v_readlane_b32 s76, v252, 35
	v_readlane_b32 s78, v252, 37
	s_mov_b64 s[6:7], 0
	v_readlane_b32 s85, v253, 23
	v_readlane_b32 s92, v253, 24
	v_readlane_b32 s35, v252, 28
	v_readlane_b32 s57, v253, 20
	v_readlane_b32 s17, v253, 22
	v_readlane_b32 s37, v252, 30
	v_readlane_b32 s71, v252, 32
	v_readlane_b32 s75, v252, 34
	v_readlane_b32 s77, v252, 36
	v_readlane_b32 s79, v252, 38
	s_barrier
	v_readlane_b32 s93, v253, 25

.Lat768_i3_nomask:
	v_max3_f32 v245, v44, v45, v46
	v_max3_f32 v245, v245, v47, v48
	v_max3_f32 v245, v245, v49, v50
	v_max3_f32 v245, v245, v51, v52
	v_max3_f32 v245, v245, v53, v54
	v_max3_f32 v245, v245, v55, v56
	v_max3_f32 v245, v245, v57, v58
	v_max3_f32 v245, v245, v59, v60
	v_max3_f32 v245, v245, v61, v62
	v_max3_f32 v245, v245, v63, v64
	v_max3_f32 v245, v245, v65, v66
	v_max3_f32 v245, v245, v67, v68
	v_max3_f32 v245, v245, v69, v70
	v_max3_f32 v245, v245, v71, v72
	v_max3_f32 v245, v245, v73, v74
	v_max3_f32 v245, v245, v75, v76
	v_max3_f32 v245, v245, v77, v78
	v_max_f32_e32 v245, v245, v79
	v_mov_b32_e32 v148, v245
	s_nop 1
	v_permlane16_swap_b32 v245, v148
	v_max_f32_e32 v245, v245, v148
	v_mov_b32_e32 v148, v245
	s_nop 1
	v_permlane32_swap_b32 v245, v148
	v_max_f32_e32 v245, v245, v148
	v_sub_f32_e32 v44, v44, v245
	v_sub_f32_e32 v45, v45, v245
	v_sub_f32_e32 v46, v46, v245
	v_sub_f32_e32 v47, v47, v245
	v_exp_f32_e32 v44, v44
	v_exp_f32_e32 v45, v45
	v_exp_f32_e32 v46, v46
	v_exp_f32_e32 v47, v47
	v_sub_f32_e32 v48, v48, v245
	v_sub_f32_e32 v49, v49, v245
	v_sub_f32_e32 v50, v50, v245
	v_sub_f32_e32 v51, v51, v245
	v_exp_f32_e32 v48, v48
	v_exp_f32_e32 v49, v49
	v_exp_f32_e32 v50, v50
	v_exp_f32_e32 v51, v51
	v_mov_b32_e32 v149, v44
	v_mov_b32_e32 v150, v45
	v_mov_b32_e32 v151, v46
	v_mov_b32_e32 v152, v47
	v_cvt_pk_bf16_f32 v44, v44, v45
	v_cvt_pk_bf16_f32 v45, v46, v47
	v_sub_f32_e32 v52, v52, v245
	v_sub_f32_e32 v53, v53, v245
	v_sub_f32_e32 v54, v54, v245
	v_sub_f32_e32 v55, v55, v245
	v_exp_f32_e32 v52, v52
	v_exp_f32_e32 v53, v53
	v_exp_f32_e32 v54, v54
	v_exp_f32_e32 v55, v55
	v_add_f32_e32 v149, v149, v48
	v_add_f32_e32 v150, v150, v49
	v_add_f32_e32 v151, v151, v50
	v_add_f32_e32 v152, v152, v51
	v_cvt_pk_bf16_f32 v46, v48, v49
	v_cvt_pk_bf16_f32 v47, v50, v51
	v_sub_f32_e32 v56, v56, v245
	v_sub_f32_e32 v57, v57, v245
	v_sub_f32_e32 v58, v58, v245
	v_sub_f32_e32 v59, v59, v245
	v_exp_f32_e32 v56, v56
	v_exp_f32_e32 v57, v57
	v_exp_f32_e32 v58, v58
	v_exp_f32_e32 v59, v59
	v_add_f32_e32 v149, v149, v52
	v_add_f32_e32 v150, v150, v53
	v_add_f32_e32 v151, v151, v54
	v_add_f32_e32 v152, v152, v55
	v_cvt_pk_bf16_f32 v52, v52, v53
	v_cvt_pk_bf16_f32 v53, v54, v55
	v_sub_f32_e32 v60, v60, v245
	v_sub_f32_e32 v61, v61, v245
	v_sub_f32_e32 v62, v62, v245
	v_sub_f32_e32 v63, v63, v245
	v_exp_f32_e32 v60, v60
	v_exp_f32_e32 v61, v61
	v_exp_f32_e32 v62, v62
	v_exp_f32_e32 v63, v63
	v_add_f32_e32 v149, v149, v56
	v_add_f32_e32 v150, v150, v57
	v_add_f32_e32 v151, v151, v58
	v_add_f32_e32 v152, v152, v59
	v_cvt_pk_bf16_f32 v54, v56, v57
	v_cvt_pk_bf16_f32 v55, v58, v59
	v_sub_f32_e32 v64, v64, v245
	v_sub_f32_e32 v65, v65, v245
	v_sub_f32_e32 v66, v66, v245
	v_sub_f32_e32 v67, v67, v245
	v_exp_f32_e32 v64, v64
	v_exp_f32_e32 v65, v65
	v_exp_f32_e32 v66, v66
	v_exp_f32_e32 v67, v67
	v_add_f32_e32 v149, v149, v60
	v_add_f32_e32 v150, v150, v61
	v_add_f32_e32 v151, v151, v62
	v_add_f32_e32 v152, v152, v63
	v_cvt_pk_bf16_f32 v60, v60, v61
	v_cvt_pk_bf16_f32 v61, v62, v63
	v_sub_f32_e32 v68, v68, v245
	v_sub_f32_e32 v69, v69, v245
	v_sub_f32_e32 v70, v70, v245
	v_sub_f32_e32 v71, v71, v245
	v_exp_f32_e32 v68, v68
	v_exp_f32_e32 v69, v69
	v_exp_f32_e32 v70, v70
	v_exp_f32_e32 v71, v71
	v_add_f32_e32 v149, v149, v64
	v_add_f32_e32 v150, v150, v65
	v_add_f32_e32 v151, v151, v66
	v_add_f32_e32 v152, v152, v67
	v_cvt_pk_bf16_f32 v62, v64, v65
	v_cvt_pk_bf16_f32 v63, v66, v67
	v_sub_f32_e32 v72, v72, v245
	v_sub_f32_e32 v73, v73, v245
	v_sub_f32_e32 v74, v74, v245
	v_sub_f32_e32 v75, v75, v245
	v_exp_f32_e32 v72, v72
	v_exp_f32_e32 v73, v73
	v_exp_f32_e32 v74, v74
	v_exp_f32_e32 v75, v75
	v_add_f32_e32 v149, v149, v68
	v_add_f32_e32 v150, v150, v69
	v_add_f32_e32 v151, v151, v70
	v_add_f32_e32 v152, v152, v71
	v_cvt_pk_bf16_f32 v68, v68, v69
	v_cvt_pk_bf16_f32 v69, v70, v71
	v_sub_f32_e32 v76, v76, v245
	v_sub_f32_e32 v77, v77, v245
	v_sub_f32_e32 v78, v78, v245
	v_sub_f32_e32 v79, v79, v245
	v_exp_f32_e32 v76, v76
	v_exp_f32_e32 v77, v77
	v_exp_f32_e32 v78, v78
	v_exp_f32_e32 v79, v79
	v_add_f32_e32 v149, v149, v72
	v_add_f32_e32 v150, v150, v73
	v_add_f32_e32 v151, v151, v74
	v_add_f32_e32 v152, v152, v75
	v_cvt_pk_bf16_f32 v70, v72, v73
	v_cvt_pk_bf16_f32 v71, v74, v75
	s_nop 0
	v_add_f32_e32 v149, v149, v76
	v_add_f32_e32 v150, v150, v77
	v_add_f32_e32 v151, v151, v78
	v_add_f32_e32 v152, v152, v79
	v_cvt_pk_bf16_f32 v76, v76, v77
	v_cvt_pk_bf16_f32 v77, v78, v79
	v_mov_b32_e32 v78, 0
	v_mov_b32_e32 v79, 0
	v_add_f32_e32 v149, v149, v150
	v_add_f32_e32 v151, v151, v152
	v_add_f32_e32 v246, v149, v151
	s_waitcnt lgkmcnt(0)
	v_mfma_f32_16x16x32_bf16 v[80:83], v[4:7], v[44:47], 0
	v_mfma_f32_16x16x32_bf16 v[84:87], v[8:11], v[44:47], 0
	v_mfma_f32_16x16x32_bf16 v[88:91], v[12:15], v[44:47], 0
	v_mfma_f32_16x16x32_bf16 v[92:95], v[16:19], v[44:47], 0
	ds_read_b64 v[4:5], v225 offset:32768
	ds_read_b64 v[8:9], v225 offset:36864
	ds_read_b64 v[12:13], v225 offset:40960
	ds_read_b64 v[16:17], v225 offset:45056
	ds_read_b64 v[6:7], v226 offset:32768
	ds_read_b64 v[10:11], v226 offset:36864
	ds_read_b64 v[14:15], v226 offset:40960
	ds_read_b64 v[18:19], v226 offset:45056
	v_mfma_f32_16x16x32_bf16 v[80:83], v[20:23], v[52:55], v[80:83]
	v_mfma_f32_16x16x32_bf16 v[84:87], v[24:27], v[52:55], v[84:87]
	v_mfma_f32_16x16x32_bf16 v[88:91], v[28:31], v[52:55], v[88:91]
	v_mfma_f32_16x16x32_bf16 v[92:95], v[32:35], v[52:55], v[92:95]
	ds_read_b64 v[20:21], v227 offset:32768
	ds_read_b64 v[24:25], v227 offset:36864
	ds_read_b64 v[28:29], v227 offset:40960
	ds_read_b64 v[32:33], v227 offset:45056
	ds_read_b64 v[22:23], v228 offset:32768
	ds_read_b64 v[26:27], v228 offset:36864
	ds_read_b64 v[30:31], v228 offset:40960
	ds_read_b64 v[34:35], v228 offset:45056
	s_waitcnt lgkmcnt(8)
	v_mfma_f32_16x16x32_bf16 v[80:83], v[4:7], v[60:63], v[80:83]
	v_mfma_f32_16x16x32_bf16 v[84:87], v[8:11], v[60:63], v[84:87]
	v_mfma_f32_16x16x32_bf16 v[88:91], v[12:15], v[60:63], v[88:91]
	v_mfma_f32_16x16x32_bf16 v[92:95], v[16:19], v[60:63], v[92:95]
	ds_read_b64 v[4:5], v229 offset:32768
	ds_read_b64 v[8:9], v229 offset:36864
	ds_read_b64 v[12:13], v229 offset:40960
	ds_read_b64 v[16:17], v229 offset:45056
	v_mov_b32_e32 v6, 0
	v_mov_b32_e32 v7, 0
	v_mov_b32_e32 v10, 0
	v_mov_b32_e32 v11, 0
	v_mov_b32_e32 v14, 0
	v_mov_b32_e32 v15, 0
	v_mov_b32_e32 v18, 0
	v_mov_b32_e32 v19, 0
	s_waitcnt lgkmcnt(4)
	v_mfma_f32_16x16x32_bf16 v[80:83], v[20:23], v[68:71], v[80:83]
	v_mfma_f32_16x16x32_bf16 v[84:87], v[24:27], v[68:71], v[84:87]
	v_mfma_f32_16x16x32_bf16 v[88:91], v[28:31], v[68:71], v[88:91]
	v_mfma_f32_16x16x32_bf16 v[92:95], v[32:35], v[68:71], v[92:95]
	s_waitcnt lgkmcnt(0)
	v_mfma_f32_16x16x32_bf16 v[80:83], v[4:7], v[76:79], v[80:83]
	v_mfma_f32_16x16x32_bf16 v[84:87], v[8:11], v[76:79], v[84:87]
	v_mfma_f32_16x16x32_bf16 v[88:91], v[12:15], v[76:79], v[88:91]
	v_mfma_f32_16x16x32_bf16 v[92:95], v[16:19], v[76:79], v[92:95]
	v_mov_b32_e32 v148, v246
	s_nop 1
	v_permlane16_swap_b32 v246, v148
	v_add_f32_e32 v246, v246, v148
	v_mov_b32_e32 v148, v246
	s_nop 1
	v_permlane32_swap_b32 v246, v148
	v_add_f32_e32 v246, v246, v148
	v_rcp_f32_e32 v149, v246
	v_log_f32_e32 v150, v246
	s_nop 0
	v_add_f32_e32 v151, v245, v150
	v_mul_f32_e32 v151, 0x3f317218, v151
	v_mov_b32_e32 v140, v151
	v_mul_f32_e32 v80, v80, v149
	v_mul_f32_e32 v81, v81, v149
	v_mul_f32_e32 v82, v82, v149
	v_mul_f32_e32 v83, v83, v149
	v_mul_f32_e32 v84, v84, v149
	v_mul_f32_e32 v85, v85, v149
	v_mul_f32_e32 v86, v86, v149
	v_mul_f32_e32 v87, v87, v149
	v_mul_f32_e32 v88, v88, v149
	v_mul_f32_e32 v89, v89, v149
	v_mul_f32_e32 v90, v90, v149
	v_mul_f32_e32 v91, v91, v149
	v_mul_f32_e32 v92, v92, v149
	v_mul_f32_e32 v93, v93, v149
	v_mul_f32_e32 v94, v94, v149
	v_mul_f32_e32 v95, v95, v149
	v_cvt_pk_bf16_f32 v132, v80, v81
	v_cvt_pk_bf16_f32 v133, v82, v83
	v_cvt_pk_bf16_f32 v134, v84, v85
	v_cvt_pk_bf16_f32 v135, v86, v87
	v_cvt_pk_bf16_f32 v136, v88, v89
	v_cvt_pk_bf16_f32 v137, v90, v91
	v_cvt_pk_bf16_f32 v138, v92, v93
	v_cvt_pk_bf16_f32 v139, v94, v95
	s_mov_b64 s[26:27], s[86:87]
	s_mov_b64 s[28:29], s[88:89]
	s_mov_b64 s[86:87], s[12:13]
	s_mov_b64 s[88:89], s[14:15]
	s_mov_b32 s4, s83
	s_mov_b32 s5, s84
	s_add_u32 s7, s7, 1
	s_cmp_lt_u32 s7, 2
	s_cbranch_scc1 .Lat768_loop
	s_setprio 0
	global_store_dwordx2 v237, v[132:133], s[26:27]
	global_store_dwordx2 v237, v[134:135], s[26:27] offset:32
	global_store_dwordx2 v237, v[136:137], s[26:27] offset:64
	global_store_dwordx2 v237, v[138:139], s[26:27] offset:96
	s_mov_b64 s[90:91], exec
	s_mov_b64 exec, 0xffff
	global_store_dword v238, v140, s[28:29]
	s_mov_b64 exec, s[90:91]
	v_readlane_b32 s0, v253, 62
	v_readlane_b32 s1, v253, 63
	s_waitcnt vmcnt(0)
	v_readlane_b32 s34, v252, 27
	v_writelane_b32 v253, s0, 4
	v_readlane_b32 s36, v252, 29
	v_readlane_b32 s70, v252, 31
	v_writelane_b32 v253, s1, 5
	v_readlane_b32 s74, v252, 33
	v_readlane_b32 s56, v253, 19
	v_readlane_b32 s16, v253, 21
	v_readlane_b32 s76, v252, 35
	v_readlane_b32 s78, v252, 37
	s_barrier
	v_readlane_b32 s35, v252, 28
	v_readlane_b32 s57, v253, 20
	v_readlane_b32 s17, v253, 22
	v_readlane_b32 s37, v252, 30
	v_readlane_b32 s71, v252, 32
	v_readlane_b32 s75, v252, 34
	v_readlane_b32 s77, v252, 36
	v_readlane_b32 s79, v252, 38

.Lat844_i0_nomask:
	v_max3_f32 v245, v44, v45, v46
	v_max3_f32 v245, v245, v47, v48
	v_max3_f32 v245, v245, v49, v50
	v_max3_f32 v245, v245, v51, v52
	v_max3_f32 v245, v245, v53, v54
	v_max3_f32 v245, v245, v55, v56
	v_max3_f32 v245, v245, v57, v58
	v_max3_f32 v245, v245, v59, v60
	v_max3_f32 v245, v245, v61, v62
	v_max3_f32 v245, v245, v63, v64
	v_max3_f32 v245, v245, v65, v66
	v_max3_f32 v245, v245, v67, v68
	v_max3_f32 v245, v245, v69, v70
	v_max3_f32 v245, v245, v71, v72
	v_max3_f32 v245, v245, v73, v74
	v_max3_f32 v245, v245, v75, v76
	v_max3_f32 v245, v245, v77, v78
	v_max_f32_e32 v245, v245, v79
	v_mov_b32_e32 v148, v245
	s_nop 1
	v_permlane16_swap_b32 v245, v148
	v_max_f32_e32 v245, v245, v148
	v_mov_b32_e32 v148, v245
	s_nop 1
	v_permlane32_swap_b32 v245, v148
	v_max_f32_e32 v245, v245, v148
	v_sub_f32_e32 v44, v44, v245
	v_sub_f32_e32 v45, v45, v245
	v_sub_f32_e32 v46, v46, v245
	v_sub_f32_e32 v47, v47, v245
	v_exp_f32_e32 v44, v44
	v_exp_f32_e32 v45, v45
	v_exp_f32_e32 v46, v46
	v_exp_f32_e32 v47, v47
	v_sub_f32_e32 v48, v48, v245
	v_sub_f32_e32 v49, v49, v245
	v_sub_f32_e32 v50, v50, v245
	v_sub_f32_e32 v51, v51, v245
	v_exp_f32_e32 v48, v48
	v_exp_f32_e32 v49, v49
	v_exp_f32_e32 v50, v50
	v_exp_f32_e32 v51, v51
	v_mov_b32_e32 v149, v44
	v_mov_b32_e32 v150, v45
	v_mov_b32_e32 v151, v46
	v_mov_b32_e32 v152, v47
	v_cvt_pk_bf16_f32 v44, v44, v45
	v_cvt_pk_bf16_f32 v45, v46, v47
	v_sub_f32_e32 v52, v52, v245
	v_sub_f32_e32 v53, v53, v245
	v_sub_f32_e32 v54, v54, v245
	v_sub_f32_e32 v55, v55, v245
	v_exp_f32_e32 v52, v52
	v_exp_f32_e32 v53, v53
	v_exp_f32_e32 v54, v54
	v_exp_f32_e32 v55, v55
	v_add_f32_e32 v149, v149, v48
	v_add_f32_e32 v150, v150, v49
	v_add_f32_e32 v151, v151, v50
	v_add_f32_e32 v152, v152, v51
	v_cvt_pk_bf16_f32 v46, v48, v49
	v_cvt_pk_bf16_f32 v47, v50, v51
	v_sub_f32_e32 v56, v56, v245
	v_sub_f32_e32 v57, v57, v245
	v_sub_f32_e32 v58, v58, v245
	v_sub_f32_e32 v59, v59, v245
	v_exp_f32_e32 v56, v56
	v_exp_f32_e32 v57, v57
	v_exp_f32_e32 v58, v58
	v_exp_f32_e32 v59, v59
	v_add_f32_e32 v149, v149, v52
	v_add_f32_e32 v150, v150, v53
	v_add_f32_e32 v151, v151, v54
	v_add_f32_e32 v152, v152, v55
	v_cvt_pk_bf16_f32 v52, v52, v53
	v_cvt_pk_bf16_f32 v53, v54, v55
	v_sub_f32_e32 v60, v60, v245
	v_sub_f32_e32 v61, v61, v245
	v_sub_f32_e32 v62, v62, v245
	v_sub_f32_e32 v63, v63, v245
	v_exp_f32_e32 v60, v60
	v_exp_f32_e32 v61, v61
	v_exp_f32_e32 v62, v62
	v_exp_f32_e32 v63, v63
	v_add_f32_e32 v149, v149, v56
	v_add_f32_e32 v150, v150, v57
	v_add_f32_e32 v151, v151, v58
	v_add_f32_e32 v152, v152, v59
	v_cvt_pk_bf16_f32 v54, v56, v57
	v_cvt_pk_bf16_f32 v55, v58, v59
	v_sub_f32_e32 v64, v64, v245
	v_sub_f32_e32 v65, v65, v245
	v_sub_f32_e32 v66, v66, v245
	v_sub_f32_e32 v67, v67, v245
	v_exp_f32_e32 v64, v64
	v_exp_f32_e32 v65, v65
	v_exp_f32_e32 v66, v66
	v_exp_f32_e32 v67, v67
	v_add_f32_e32 v149, v149, v60
	v_add_f32_e32 v150, v150, v61
	v_add_f32_e32 v151, v151, v62
	v_add_f32_e32 v152, v152, v63
	v_cvt_pk_bf16_f32 v60, v60, v61
	v_cvt_pk_bf16_f32 v61, v62, v63
	v_sub_f32_e32 v68, v68, v245
	v_sub_f32_e32 v69, v69, v245
	v_sub_f32_e32 v70, v70, v245
	v_sub_f32_e32 v71, v71, v245
	v_exp_f32_e32 v68, v68
	v_exp_f32_e32 v69, v69
	v_exp_f32_e32 v70, v70
	v_exp_f32_e32 v71, v71
	v_add_f32_e32 v149, v149, v64
	v_add_f32_e32 v150, v150, v65
	v_add_f32_e32 v151, v151, v66
	v_add_f32_e32 v152, v152, v67
	v_cvt_pk_bf16_f32 v62, v64, v65
	v_cvt_pk_bf16_f32 v63, v66, v67
	v_sub_f32_e32 v72, v72, v245
	v_sub_f32_e32 v73, v73, v245
	v_sub_f32_e32 v74, v74, v245
	v_sub_f32_e32 v75, v75, v245
	v_exp_f32_e32 v72, v72
	v_exp_f32_e32 v73, v73
	v_exp_f32_e32 v74, v74
	v_exp_f32_e32 v75, v75
	v_add_f32_e32 v149, v149, v68
	v_add_f32_e32 v150, v150, v69
	v_add_f32_e32 v151, v151, v70
	v_add_f32_e32 v152, v152, v71
	v_cvt_pk_bf16_f32 v68, v68, v69
	v_cvt_pk_bf16_f32 v69, v70, v71
	v_sub_f32_e32 v76, v76, v245
	v_sub_f32_e32 v77, v77, v245
	v_sub_f32_e32 v78, v78, v245
	v_sub_f32_e32 v79, v79, v245
	v_exp_f32_e32 v76, v76
	v_exp_f32_e32 v77, v77
	v_exp_f32_e32 v78, v78
	v_exp_f32_e32 v79, v79
	v_add_f32_e32 v149, v149, v72
	v_add_f32_e32 v150, v150, v73
	v_add_f32_e32 v151, v151, v74
	v_add_f32_e32 v152, v152, v75
	v_cvt_pk_bf16_f32 v70, v72, v73
	v_cvt_pk_bf16_f32 v71, v74, v75
	s_nop 0
	v_add_f32_e32 v149, v149, v76
	v_add_f32_e32 v150, v150, v77
	v_add_f32_e32 v151, v151, v78
	v_add_f32_e32 v152, v152, v79
	v_cvt_pk_bf16_f32 v76, v76, v77
	v_cvt_pk_bf16_f32 v77, v78, v79
	v_mov_b32_e32 v78, 0
	v_mov_b32_e32 v79, 0
	v_add_f32_e32 v149, v149, v150
	v_add_f32_e32 v151, v151, v152
	v_add_f32_e32 v246, v149, v151
	s_waitcnt lgkmcnt(0)
	v_mfma_f32_16x16x32_bf16 v[80:83], v[4:7], v[44:47], 0
	v_mfma_f32_16x16x32_bf16 v[84:87], v[8:11], v[44:47], 0
	v_mfma_f32_16x16x32_bf16 v[88:91], v[12:15], v[44:47], 0
	v_mfma_f32_16x16x32_bf16 v[92:95], v[16:19], v[44:47], 0
	s_cmp_gt_u32 s6, 4
	s_cselect_b32 s74, 0, 0xffff0000
	v_add_u32_e32 v146, s74, v225
	ds_read_b64 v[4:5], v146 offset:49152
	ds_read_b64 v[8:9], v146 offset:53248
	ds_read_b64 v[12:13], v146 offset:57344
	ds_read_b64 v[16:17], v146 offset:61440
	s_cmp_gt_u32 s6, 5
	s_cselect_b32 s74, 0, 0xffff0000
	v_add_u32_e32 v146, s74, v226
	ds_read_b64 v[6:7], v146 offset:49152
	ds_read_b64 v[10:11], v146 offset:53248
	ds_read_b64 v[14:15], v146 offset:57344
	ds_read_b64 v[18:19], v146 offset:61440
	v_mfma_f32_16x16x32_bf16 v[80:83], v[20:23], v[52:55], v[80:83]
	v_mfma_f32_16x16x32_bf16 v[84:87], v[24:27], v[52:55], v[84:87]
	v_mfma_f32_16x16x32_bf16 v[88:91], v[28:31], v[52:55], v[88:91]
	v_mfma_f32_16x16x32_bf16 v[92:95], v[32:35], v[52:55], v[92:95]
	s_cmp_gt_u32 s6, 6
	s_cselect_b32 s74, 0, 0xffff0000
	v_add_u32_e32 v146, s74, v227
	ds_read_b64 v[20:21], v146 offset:49152
	ds_read_b64 v[24:25], v146 offset:53248
	ds_read_b64 v[28:29], v146 offset:57344
	ds_read_b64 v[32:33], v146 offset:61440
	s_cmp_gt_u32 s6, 7
	s_cselect_b32 s74, 0, 0xffff0000
	v_add_u32_e32 v146, s74, v228
	ds_read_b64 v[22:23], v146 offset:49152
	ds_read_b64 v[26:27], v146 offset:53248
	ds_read_b64 v[30:31], v146 offset:57344
	ds_read_b64 v[34:35], v146 offset:61440
	s_waitcnt lgkmcnt(8)
	v_mfma_f32_16x16x32_bf16 v[80:83], v[4:7], v[60:63], v[80:83]
	v_mfma_f32_16x16x32_bf16 v[84:87], v[8:11], v[60:63], v[84:87]
	v_mfma_f32_16x16x32_bf16 v[88:91], v[12:15], v[60:63], v[88:91]
	v_mfma_f32_16x16x32_bf16 v[92:95], v[16:19], v[60:63], v[92:95]
	s_cmp_gt_u32 s6, 8
	s_cselect_b32 s74, 0, 0xffff0000
	v_add_u32_e32 v146, s74, v229
	ds_read_b64 v[4:5], v146 offset:49152
	ds_read_b64 v[8:9], v146 offset:53248
	ds_read_b64 v[12:13], v146 offset:57344
	ds_read_b64 v[16:17], v146 offset:61440
	v_mov_b32_e32 v6, 0
	v_mov_b32_e32 v7, 0
	v_mov_b32_e32 v10, 0
	v_mov_b32_e32 v11, 0
	v_mov_b32_e32 v14, 0
	v_mov_b32_e32 v15, 0
	v_mov_b32_e32 v18, 0
	v_mov_b32_e32 v19, 0
	s_waitcnt lgkmcnt(4)
	v_mfma_f32_16x16x32_bf16 v[80:83], v[20:23], v[68:71], v[80:83]
	v_mfma_f32_16x16x32_bf16 v[84:87], v[24:27], v[68:71], v[84:87]
	v_mfma_f32_16x16x32_bf16 v[88:91], v[28:31], v[68:71], v[88:91]
	v_mfma_f32_16x16x32_bf16 v[92:95], v[32:35], v[68:71], v[92:95]
	s_waitcnt lgkmcnt(0)
	v_mfma_f32_16x16x32_bf16 v[80:83], v[4:7], v[76:79], v[80:83]
	v_mfma_f32_16x16x32_bf16 v[84:87], v[8:11], v[76:79], v[84:87]
	v_mfma_f32_16x16x32_bf16 v[88:91], v[12:15], v[76:79], v[88:91]
	v_mfma_f32_16x16x32_bf16 v[92:95], v[16:19], v[76:79], v[92:95]
	v_mov_b32_e32 v148, v246
	s_nop 1
	v_permlane16_swap_b32 v246, v148
	v_add_f32_e32 v246, v246, v148
	v_mov_b32_e32 v148, v246
	s_nop 1
	v_permlane32_swap_b32 v246, v148
	v_add_f32_e32 v246, v246, v148
	v_rcp_f32_e32 v149, v246
	v_log_f32_e32 v150, v246
	s_nop 0
	v_add_f32_e32 v151, v245, v150
	v_mul_f32_e32 v151, 0x3f317218, v151
	v_max_f32_e32 v152, v120, v151
	v_sub_f32_e32 v153, v120, v152
	v_sub_f32_e32 v154, v151, v152
	v_mul_f32_e32 v153, 0x3fb8aa3b, v153
	v_mul_f32_e32 v154, 0x3fb8aa3b, v154
	v_exp_f32_e32 v153, v153
	v_exp_f32_e32 v154, v154
	s_nop 0
	v_add_f32_e32 v155, v153, v154
	v_rcp_f32_e32 v146, v155
	v_log_f32_e32 v150, v155
	s_nop 0
	v_mul_f32_e32 v154, v154, v146
	v_mul_f32_e32 v146, v153, v146
	v_mul_f32_e32 v147, v149, v154
	v_mul_f32_e32 v150, 0x3f317218, v150
	v_add_f32_e32 v140, v152, v150
	v_mul_f32_e32 v80, v80, v147
	v_mul_f32_e32 v81, v81, v147
	v_mul_f32_e32 v82, v82, v147
	v_mul_f32_e32 v83, v83, v147
	v_mul_f32_e32 v84, v84, v147
	v_mul_f32_e32 v85, v85, v147
	v_mul_f32_e32 v86, v86, v147
	v_mul_f32_e32 v87, v87, v147
	v_mul_f32_e32 v88, v88, v147
	v_mul_f32_e32 v89, v89, v147
	v_mul_f32_e32 v90, v90, v147
	v_mul_f32_e32 v91, v91, v147
	v_mul_f32_e32 v92, v92, v147
	v_mul_f32_e32 v93, v93, v147
	v_mul_f32_e32 v94, v94, v147
	v_mul_f32_e32 v95, v95, v147
	v_lshlrev_b32_e32 v141, 16, v112
	v_and_b32_e32 v142, 0xffff0000, v112
	v_lshlrev_b32_e32 v143, 16, v113
	v_and_b32_e32 v144, 0xffff0000, v113
	v_fmac_f32_e32 v80, v146, v141
	v_fmac_f32_e32 v81, v146, v142
	v_fmac_f32_e32 v82, v146, v143
	v_fmac_f32_e32 v83, v146, v144
	v_cvt_pk_bf16_f32 v132, v80, v81
	v_cvt_pk_bf16_f32 v133, v82, v83
	v_lshlrev_b32_e32 v141, 16, v114
	v_and_b32_e32 v142, 0xffff0000, v114
	v_lshlrev_b32_e32 v143, 16, v115
	v_and_b32_e32 v144, 0xffff0000, v115
	v_fmac_f32_e32 v84, v146, v141
	v_fmac_f32_e32 v85, v146, v142
	v_fmac_f32_e32 v86, v146, v143
	v_fmac_f32_e32 v87, v146, v144
	v_cvt_pk_bf16_f32 v134, v84, v85
	v_cvt_pk_bf16_f32 v135, v86, v87
	v_lshlrev_b32_e32 v141, 16, v116
	v_and_b32_e32 v142, 0xffff0000, v116
	v_lshlrev_b32_e32 v143, 16, v117
	v_and_b32_e32 v144, 0xffff0000, v117
	v_fmac_f32_e32 v88, v146, v141
	v_fmac_f32_e32 v89, v146, v142
	v_fmac_f32_e32 v90, v146, v143
	v_fmac_f32_e32 v91, v146, v144
	v_cvt_pk_bf16_f32 v136, v88, v89
	v_cvt_pk_bf16_f32 v137, v90, v91
	v_lshlrev_b32_e32 v141, 16, v118
	v_and_b32_e32 v142, 0xffff0000, v118
	v_lshlrev_b32_e32 v143, 16, v119
	v_and_b32_e32 v144, 0xffff0000, v119
	v_fmac_f32_e32 v92, v146, v141
	v_fmac_f32_e32 v93, v146, v142
	v_fmac_f32_e32 v94, v146, v143
	v_fmac_f32_e32 v95, v146, v144
	v_cvt_pk_bf16_f32 v138, v92, v93
	v_cvt_pk_bf16_f32 v139, v94, v95
	s_mov_b64 s[26:27], s[86:87]
	s_mov_b64 s[28:29], s[88:89]
	s_mov_b64 s[86:87], s[12:13]
	s_mov_b64 s[88:89], s[14:15]
	s_mov_b32 s4, s83
	s_mov_b32 s5, s84
	s_waitcnt vmcnt(0)
	s_barrier
	ds_read_b128 v[4:7], v230 offset:0
	ds_read_b128 v[8:11], v231 offset:0
	ds_read_b128 v[12:15], v230 offset:2048
	ds_read_b128 v[16:19], v231 offset:2048
	ds_read_b128 v[20:23], v230 offset:4096
	ds_read_b128 v[24:27], v231 offset:4096
	ds_read_b128 v[28:31], v230 offset:6144
	ds_read_b128 v[32:35], v231 offset:6144
	ds_read_b128 v[36:39], v230 offset:8192
	ds_read_b128 v[40:43], v231 offset:8192
	global_store_dwordx2 v237, v[132:133], s[26:27]
	global_store_dwordx2 v237, v[134:135], s[26:27] offset:32
	global_store_dwordx2 v237, v[136:137], s[26:27] offset:64
	global_store_dwordx2 v237, v[138:139], s[26:27] offset:96
	s_mov_b64 s[90:91], exec
	s_mov_b64 exec, 0xffff
	global_store_dword v238, v140, s[28:29]
	s_mov_b64 exec, s[90:91]
	s_add_u32 s83, s4, 1
	s_mov_b32 s84, s5
	s_mul_i32 s74, s84, 1024
	s_lshl_b32 s75, s83, 7
	s_add_u32 s74, s74, s75
	s_lshl_b32 s75, s74, 7
	s_add_u32 s16, s60, s75
	s_addc_u32 s17, s61, 0
	s_lshl_b32 s75, s74, 1
	s_add_u32 s24, s64, s75
	s_addc_u32 s25, s65, 0
	s_add_u32 m0, s70, 0x8000
	s_nop 0
	global_load_lds_dwordx4 v232, s[16:17] nt
	s_add_u32 m0, s70, 0xa000
	s_nop 0
	global_load_lds_dwordx4 v233, s[16:17] nt
	s_add_u32 m0, s70, 0x18000
	s_nop 0
	global_load_lds_dwordx4 v234, s[24:25] nt
	s_add_u32 m0, s70, 0x1a000
	s_nop 0
	global_load_lds_dwordx4 v235, s[24:25] nt
	s_lshl_b32 s74, s83, 9
	s_add_u32 s74, s74, s84
	s_lshl_b32 s75, s74, 7
	s_add_u32 s10, s30, s75
	s_addc_u32 s11, s31, 0
	s_add_u32 s12, s34, s75
	s_addc_u32 s13, s35, 0
	s_lshl_b32 s75, s74, 2
	s_add_u32 s14, s58, s75
	s_addc_u32 s15, s59, 0
	global_load_dwordx4 v[96:99], v236, s[10:11]
	global_load_dwordx4 v[100:103], v236, s[10:11] offset:64
	global_load_dwordx2 v[112:113], v237, s[12:13]
	global_load_dwordx2 v[114:115], v237, s[12:13] offset:32
	global_load_dwordx2 v[116:117], v237, s[12:13] offset:64
	global_load_dwordx2 v[118:119], v237, s[12:13] offset:96
	global_load_dword v120, v238, s[14:15]
	s_waitcnt lgkmcnt(0)
	v_mfma_f32_16x16x32_bf16 v[44:47], v[4:7], v[104:107], 0
	v_mfma_f32_16x16x32_bf16 v[48:51], v[12:15], v[104:107], 0
	v_mfma_f32_16x16x32_bf16 v[52:55], v[20:23], v[104:107], 0
	v_mfma_f32_16x16x32_bf16 v[56:59], v[28:31], v[104:107], 0
	v_mfma_f32_16x16x32_bf16 v[60:63], v[36:39], v[104:107], 0
	v_mfma_f32_16x16x32_bf16 v[44:47], v[8:11], v[108:111], v[44:47]
	v_mfma_f32_16x16x32_bf16 v[48:51], v[16:19], v[108:111], v[48:51]
	v_mfma_f32_16x16x32_bf16 v[52:55], v[24:27], v[108:111], v[52:55]
	v_mfma_f32_16x16x32_bf16 v[56:59], v[32:35], v[108:111], v[56:59]
	v_mfma_f32_16x16x32_bf16 v[60:63], v[40:43], v[108:111], v[60:63]
	ds_read_b128 v[4:7], v230 offset:10240
	ds_read_b128 v[8:11], v231 offset:10240
	ds_read_b128 v[12:15], v230 offset:12288
	ds_read_b128 v[16:19], v231 offset:12288
	ds_read_b128 v[20:23], v230 offset:14336
	ds_read_b128 v[24:27], v231 offset:14336
	ds_read_b128 v[28:31], v230 offset:16384
	ds_read_b128 v[32:35], v231 offset:16384
	s_nop 1
	v_fma_f32 v44, v44, s79, v185
	v_fma_f32 v45, v45, s79, v186
	v_fma_f32 v46, v46, s79, v187
	v_fma_f32 v47, v47, s79, v188
	v_fma_f32 v48, v48, s79, v189
	v_fma_f32 v49, v49, s79, v190
	v_fma_f32 v50, v50, s79, v191
	v_fma_f32 v51, v51, s79, v192
	v_fma_f32 v52, v52, s79, v193
	v_fma_f32 v53, v53, s79, v194
	v_fma_f32 v54, v54, s79, v195
	v_fma_f32 v55, v55, s79, v196
	v_fma_f32 v56, v56, s79, v197
	v_fma_f32 v57, v57, s79, v198
	v_fma_f32 v58, v58, s79, v199
	v_fma_f32 v59, v59, s79, v200
	v_fma_f32 v60, v60, s79, v201
	v_fma_f32 v61, v61, s79, v202
	v_fma_f32 v62, v62, s79, v203
	v_fma_f32 v63, v63, s79, v204
	s_waitcnt lgkmcnt(0)
	v_mfma_f32_16x16x32_bf16 v[64:67], v[4:7], v[104:107], 0
	v_mfma_f32_16x16x32_bf16 v[68:71], v[12:15], v[104:107], 0
	v_mfma_f32_16x16x32_bf16 v[72:75], v[20:23], v[104:107], 0
	v_mfma_f32_16x16x32_bf16 v[76:79], v[28:31], v[104:107], 0
	v_mfma_f32_16x16x32_bf16 v[64:67], v[8:11], v[108:111], v[64:67]
	v_mfma_f32_16x16x32_bf16 v[68:71], v[16:19], v[108:111], v[68:71]
	v_mfma_f32_16x16x32_bf16 v[72:75], v[24:27], v[108:111], v[72:75]
	v_mfma_f32_16x16x32_bf16 v[76:79], v[32:35], v[108:111], v[76:79]
	ds_read_b64 v[4:5], v221 offset:0
	ds_read_b64 v[8:9], v221 offset:4096
	ds_read_b64 v[12:13], v221 offset:8192
	ds_read_b64 v[16:17], v221 offset:12288
	ds_read_b64 v[6:7], v222 offset:0
	ds_read_b64 v[10:11], v222 offset:4096
	ds_read_b64 v[14:15], v222 offset:8192
	ds_read_b64 v[18:19], v222 offset:12288
	s_nop 1
	v_fma_f32 v64, v64, s79, v205
	v_fma_f32 v65, v65, s79, v206
	v_fma_f32 v66, v66, s79, v207
	v_fma_f32 v67, v67, s79, v208
	v_fma_f32 v68, v68, s79, v209
	v_fma_f32 v69, v69, s79, v210
	v_fma_f32 v70, v70, s79, v211
	v_fma_f32 v71, v71, s79, v212
	v_fma_f32 v72, v72, s79, v213
	v_fma_f32 v73, v73, s79, v214
	v_fma_f32 v74, v74, s79, v215
	v_fma_f32 v75, v75, s79, v216
	v_fma_f32 v76, v76, s79, v217
	v_fma_f32 v77, v77, s79, v218
	v_fma_f32 v78, v78, s79, v219
	v_fma_f32 v79, v79, s79, v220
	ds_read_b64 v[20:21], v223 offset:0
	ds_read_b64 v[24:25], v223 offset:4096
	ds_read_b64 v[28:29], v223 offset:8192
	ds_read_b64 v[32:33], v223 offset:12288
	ds_read_b64 v[22:23], v224 offset:0
	ds_read_b64 v[26:27], v224 offset:4096
	ds_read_b64 v[30:31], v224 offset:8192
	ds_read_b64 v[34:35], v224 offset:12288
	s_cmp_lg_u32 s4, 0
	s_cbranch_scc1 .Lat844_i1_nomask
	s_cmp_le_u32 s6, 0
	s_cbranch_scc1 .Lat844_i1_nomask
	v_mov_b32_e32 v44, v244
	v_mov_b32_e32 v45, v244
	v_mov_b32_e32 v46, v244
	v_mov_b32_e32 v47, v244
	s_cmp_le_u32 s6, 1
	s_cbranch_scc1 .Lat844_i1_nomask
	v_mov_b32_e32 v48, v244
	v_mov_b32_e32 v49, v244
	v_mov_b32_e32 v50, v244
	v_mov_b32_e32 v51, v244
	s_cmp_le_u32 s6, 2
	s_cbranch_scc1 .Lat844_i1_nomask
	v_mov_b32_e32 v52, v244
	v_mov_b32_e32 v53, v244
	v_mov_b32_e32 v54, v244
	v_mov_b32_e32 v55, v244
	s_cmp_le_u32 s6, 3
	s_cbranch_scc1 .Lat844_i1_nomask
	v_mov_b32_e32 v56, v244
	v_mov_b32_e32 v57, v244
	v_mov_b32_e32 v58, v244
	v_mov_b32_e32 v59, v244
	s_cmp_le_u32 s6, 4
	s_cbranch_scc1 .Lat844_i1_nomask
	v_mov_b32_e32 v60, v244
	v_mov_b32_e32 v61, v244
	v_mov_b32_e32 v62, v244
	v_mov_b32_e32 v63, v244
	s_cmp_le_u32 s6, 5
	s_cbranch_scc1 .Lat844_i1_nomask
	v_mov_b32_e32 v64, v244
	v_mov_b32_e32 v65, v244
	v_mov_b32_e32 v66, v244
	v_mov_b32_e32 v67, v244
	s_cmp_le_u32 s6, 6
	s_cbranch_scc1 .Lat844_i1_nomask
	v_mov_b32_e32 v68, v244
	v_mov_b32_e32 v69, v244
	v_mov_b32_e32 v70, v244
	v_mov_b32_e32 v71, v244
	s_cmp_le_u32 s6, 7
	s_cbranch_scc1 .Lat844_i1_nomask
	v_mov_b32_e32 v72, v244
	v_mov_b32_e32 v73, v244
	v_mov_b32_e32 v74, v244
	v_mov_b32_e32 v75, v244
.Lat844_i1_nomask:
	v_max3_f32 v245, v44, v45, v46
	v_max3_f32 v245, v245, v47, v48
	v_max3_f32 v245, v245, v49, v50
	v_max3_f32 v245, v245, v51, v52
	v_max3_f32 v245, v245, v53, v54
	v_max3_f32 v245, v245, v55, v56
	v_max3_f32 v245, v245, v57, v58
	v_max3_f32 v245, v245, v59, v60
	v_max3_f32 v245, v245, v61, v62
	v_max3_f32 v245, v245, v63, v64
	v_max3_f32 v245, v245, v65, v66
	v_max3_f32 v245, v245, v67, v68
	v_max3_f32 v245, v245, v69, v70
	v_max3_f32 v245, v245, v71, v72
	v_max3_f32 v245, v245, v73, v74
	v_max3_f32 v245, v245, v75, v76
	v_max3_f32 v245, v245, v77, v78
	v_max_f32_e32 v245, v245, v79
	v_mov_b32_e32 v148, v245
	s_nop 1
	v_permlane16_swap_b32 v245, v148
	v_max_f32_e32 v245, v245, v148
	v_mov_b32_e32 v148, v245
	s_nop 1
	v_permlane32_swap_b32 v245, v148
	v_max_f32_e32 v245, v245, v148
	v_sub_f32_e32 v44, v44, v245
	v_sub_f32_e32 v45, v45, v245
	v_sub_f32_e32 v46, v46, v245
	v_sub_f32_e32 v47, v47, v245
	v_exp_f32_e32 v44, v44
	v_exp_f32_e32 v45, v45
	v_exp_f32_e32 v46, v46
	v_exp_f32_e32 v47, v47
	v_sub_f32_e32 v48, v48, v245
	v_sub_f32_e32 v49, v49, v245
	v_sub_f32_e32 v50, v50, v245
	v_sub_f32_e32 v51, v51, v245
	v_exp_f32_e32 v48, v48
	v_exp_f32_e32 v49, v49
	v_exp_f32_e32 v50, v50
	v_exp_f32_e32 v51, v51
	v_mov_b32_e32 v149, v44
	v_mov_b32_e32 v150, v45
	v_mov_b32_e32 v151, v46
	v_mov_b32_e32 v152, v47
	v_cvt_pk_bf16_f32 v44, v44, v45
	v_cvt_pk_bf16_f32 v45, v46, v47
	v_sub_f32_e32 v52, v52, v245
	v_sub_f32_e32 v53, v53, v245
	v_sub_f32_e32 v54, v54, v245
	v_sub_f32_e32 v55, v55, v245
	v_exp_f32_e32 v52, v52
	v_exp_f32_e32 v53, v53
	v_exp_f32_e32 v54, v54
	v_exp_f32_e32 v55, v55
	v_add_f32_e32 v149, v149, v48
	v_add_f32_e32 v150, v150, v49
	v_add_f32_e32 v151, v151, v50
	v_add_f32_e32 v152, v152, v51
	v_cvt_pk_bf16_f32 v46, v48, v49
	v_cvt_pk_bf16_f32 v47, v50, v51
	v_sub_f32_e32 v56, v56, v245
	v_sub_f32_e32 v57, v57, v245
	v_sub_f32_e32 v58, v58, v245
	v_sub_f32_e32 v59, v59, v245
	v_exp_f32_e32 v56, v56
	v_exp_f32_e32 v57, v57
	v_exp_f32_e32 v58, v58
	v_exp_f32_e32 v59, v59
	v_add_f32_e32 v149, v149, v52
	v_add_f32_e32 v150, v150, v53
	v_add_f32_e32 v151, v151, v54
	v_add_f32_e32 v152, v152, v55
	v_cvt_pk_bf16_f32 v52, v52, v53
	v_cvt_pk_bf16_f32 v53, v54, v55
	v_sub_f32_e32 v60, v60, v245
	v_sub_f32_e32 v61, v61, v245
	v_sub_f32_e32 v62, v62, v245
	v_sub_f32_e32 v63, v63, v245
	v_exp_f32_e32 v60, v60
	v_exp_f32_e32 v61, v61
	v_exp_f32_e32 v62, v62
	v_exp_f32_e32 v63, v63
	v_add_f32_e32 v149, v149, v56
	v_add_f32_e32 v150, v150, v57
	v_add_f32_e32 v151, v151, v58
	v_add_f32_e32 v152, v152, v59
	v_cvt_pk_bf16_f32 v54, v56, v57
	v_cvt_pk_bf16_f32 v55, v58, v59
	v_sub_f32_e32 v64, v64, v245
	v_sub_f32_e32 v65, v65, v245
	v_sub_f32_e32 v66, v66, v245
	v_sub_f32_e32 v67, v67, v245
	v_exp_f32_e32 v64, v64
	v_exp_f32_e32 v65, v65
	v_exp_f32_e32 v66, v66
	v_exp_f32_e32 v67, v67
	v_add_f32_e32 v149, v149, v60
	v_add_f32_e32 v150, v150, v61
	v_add_f32_e32 v151, v151, v62
	v_add_f32_e32 v152, v152, v63
	v_cvt_pk_bf16_f32 v60, v60, v61
	v_cvt_pk_bf16_f32 v61, v62, v63
	v_sub_f32_e32 v68, v68, v245
	v_sub_f32_e32 v69, v69, v245
	v_sub_f32_e32 v70, v70, v245
	v_sub_f32_e32 v71, v71, v245
	v_exp_f32_e32 v68, v68
	v_exp_f32_e32 v69, v69
	v_exp_f32_e32 v70, v70
	v_exp_f32_e32 v71, v71
	v_add_f32_e32 v149, v149, v64
	v_add_f32_e32 v150, v150, v65
	v_add_f32_e32 v151, v151, v66
	v_add_f32_e32 v152, v152, v67
	v_cvt_pk_bf16_f32 v62, v64, v65
	v_cvt_pk_bf16_f32 v63, v66, v67
	v_sub_f32_e32 v72, v72, v245
	v_sub_f32_e32 v73, v73, v245
	v_sub_f32_e32 v74, v74, v245
	v_sub_f32_e32 v75, v75, v245
	v_exp_f32_e32 v72, v72
	v_exp_f32_e32 v73, v73
	v_exp_f32_e32 v74, v74
	v_exp_f32_e32 v75, v75
	v_add_f32_e32 v149, v149, v68
	v_add_f32_e32 v150, v150, v69
	v_add_f32_e32 v151, v151, v70
	v_add_f32_e32 v152, v152, v71
	v_cvt_pk_bf16_f32 v68, v68, v69
	v_cvt_pk_bf16_f32 v69, v70, v71
	v_sub_f32_e32 v76, v76, v245
	v_sub_f32_e32 v77, v77, v245
	v_sub_f32_e32 v78, v78, v245
	v_sub_f32_e32 v79, v79, v245
	v_exp_f32_e32 v76, v76
	v_exp_f32_e32 v77, v77
	v_exp_f32_e32 v78, v78
	v_exp_f32_e32 v79, v79
	v_add_f32_e32 v149, v149, v72
	v_add_f32_e32 v150, v150, v73
	v_add_f32_e32 v151, v151, v74
	v_add_f32_e32 v152, v152, v75
	v_cvt_pk_bf16_f32 v70, v72, v73
	v_cvt_pk_bf16_f32 v71, v74, v75
	s_nop 0
	v_add_f32_e32 v149, v149, v76
	v_add_f32_e32 v150, v150, v77
	v_add_f32_e32 v151, v151, v78
	v_add_f32_e32 v152, v152, v79
	v_cvt_pk_bf16_f32 v76, v76, v77
	v_cvt_pk_bf16_f32 v77, v78, v79
	v_mov_b32_e32 v78, 0
	v_mov_b32_e32 v79, 0
	v_add_f32_e32 v149, v149, v150
	v_add_f32_e32 v151, v151, v152
	v_add_f32_e32 v246, v149, v151
	s_waitcnt lgkmcnt(0)
	v_mfma_f32_16x16x32_bf16 v[80:83], v[4:7], v[44:47], 0
	v_mfma_f32_16x16x32_bf16 v[84:87], v[8:11], v[44:47], 0
	v_mfma_f32_16x16x32_bf16 v[88:91], v[12:15], v[44:47], 0
	v_mfma_f32_16x16x32_bf16 v[92:95], v[16:19], v[44:47], 0
	ds_read_b64 v[4:5], v225 offset:0
	ds_read_b64 v[8:9], v225 offset:4096
	ds_read_b64 v[12:13], v225 offset:8192
	ds_read_b64 v[16:17], v225 offset:12288
	ds_read_b64 v[6:7], v226 offset:0
	ds_read_b64 v[10:11], v226 offset:4096
	ds_read_b64 v[14:15], v226 offset:8192
	ds_read_b64 v[18:19], v226 offset:12288
	v_mfma_f32_16x16x32_bf16 v[80:83], v[20:23], v[52:55], v[80:83]
	v_mfma_f32_16x16x32_bf16 v[84:87], v[24:27], v[52:55], v[84:87]
	v_mfma_f32_16x16x32_bf16 v[88:91], v[28:31], v[52:55], v[88:91]
	v_mfma_f32_16x16x32_bf16 v[92:95], v[32:35], v[52:55], v[92:95]
	ds_read_b64 v[20:21], v227 offset:0
	ds_read_b64 v[24:25], v227 offset:4096
	ds_read_b64 v[28:29], v227 offset:8192
	ds_read_b64 v[32:33], v227 offset:12288
	ds_read_b64 v[22:23], v228 offset:0
	ds_read_b64 v[26:27], v228 offset:4096
	ds_read_b64 v[30:31], v228 offset:8192
	ds_read_b64 v[34:35], v228 offset:12288
	s_waitcnt lgkmcnt(8)
	v_mfma_f32_16x16x32_bf16 v[80:83], v[4:7], v[60:63], v[80:83]
	v_mfma_f32_16x16x32_bf16 v[84:87], v[8:11], v[60:63], v[84:87]
	v_mfma_f32_16x16x32_bf16 v[88:91], v[12:15], v[60:63], v[88:91]
	v_mfma_f32_16x16x32_bf16 v[92:95], v[16:19], v[60:63], v[92:95]
	ds_read_b64 v[4:5], v229 offset:0
	ds_read_b64 v[8:9], v229 offset:4096
	ds_read_b64 v[12:13], v229 offset:8192
	ds_read_b64 v[16:17], v229 offset:12288
	v_mov_b32_e32 v6, 0
	v_mov_b32_e32 v7, 0
	v_mov_b32_e32 v10, 0
	v_mov_b32_e32 v11, 0
	v_mov_b32_e32 v14, 0
	v_mov_b32_e32 v15, 0
	v_mov_b32_e32 v18, 0
	v_mov_b32_e32 v19, 0
	s_waitcnt lgkmcnt(4)
	v_mfma_f32_16x16x32_bf16 v[80:83], v[20:23], v[68:71], v[80:83]
	v_mfma_f32_16x16x32_bf16 v[84:87], v[24:27], v[68:71], v[84:87]
	v_mfma_f32_16x16x32_bf16 v[88:91], v[28:31], v[68:71], v[88:91]
	v_mfma_f32_16x16x32_bf16 v[92:95], v[32:35], v[68:71], v[92:95]
	s_waitcnt lgkmcnt(0)
	v_mfma_f32_16x16x32_bf16 v[80:83], v[4:7], v[76:79], v[80:83]
	v_mfma_f32_16x16x32_bf16 v[84:87], v[8:11], v[76:79], v[84:87]
	v_mfma_f32_16x16x32_bf16 v[88:91], v[12:15], v[76:79], v[88:91]
	v_mfma_f32_16x16x32_bf16 v[92:95], v[16:19], v[76:79], v[92:95]
	v_mov_b32_e32 v148, v246
	s_nop 1
	v_permlane16_swap_b32 v246, v148
	v_add_f32_e32 v246, v246, v148
	v_mov_b32_e32 v148, v246
	s_nop 1
	v_permlane32_swap_b32 v246, v148
	v_add_f32_e32 v246, v246, v148
	v_rcp_f32_e32 v149, v246
	v_log_f32_e32 v150, v246
	s_nop 0
	v_add_f32_e32 v151, v245, v150
	v_mul_f32_e32 v151, 0x3f317218, v151
	v_max_f32_e32 v152, v121, v151
	v_sub_f32_e32 v153, v121, v152
	v_sub_f32_e32 v154, v151, v152
	v_mul_f32_e32 v153, 0x3fb8aa3b, v153
	v_mul_f32_e32 v154, 0x3fb8aa3b, v154
	v_exp_f32_e32 v153, v153
	v_exp_f32_e32 v154, v154
	s_nop 0
	v_add_f32_e32 v155, v153, v154
	v_rcp_f32_e32 v146, v155
	v_log_f32_e32 v150, v155
	s_nop 0
	v_mul_f32_e32 v154, v154, v146
	v_mul_f32_e32 v146, v153, v146
	v_mul_f32_e32 v147, v149, v154
	v_mul_f32_e32 v150, 0x3f317218, v150
	v_add_f32_e32 v140, v152, v150
	v_mul_f32_e32 v80, v80, v147
	v_mul_f32_e32 v81, v81, v147
	v_mul_f32_e32 v82, v82, v147
	v_mul_f32_e32 v83, v83, v147
	v_mul_f32_e32 v84, v84, v147
	v_mul_f32_e32 v85, v85, v147
	v_mul_f32_e32 v86, v86, v147
	v_mul_f32_e32 v87, v87, v147
	v_mul_f32_e32 v88, v88, v147
	v_mul_f32_e32 v89, v89, v147
	v_mul_f32_e32 v90, v90, v147
	v_mul_f32_e32 v91, v91, v147
	v_mul_f32_e32 v92, v92, v147
	v_mul_f32_e32 v93, v93, v147
	v_mul_f32_e32 v94, v94, v147
	v_mul_f32_e32 v95, v95, v147
	v_lshlrev_b32_e32 v141, 16, v122
	v_and_b32_e32 v142, 0xffff0000, v122
	v_lshlrev_b32_e32 v143, 16, v123
	v_and_b32_e32 v144, 0xffff0000, v123
	v_fmac_f32_e32 v80, v146, v141
	v_fmac_f32_e32 v81, v146, v142
	v_fmac_f32_e32 v82, v146, v143
	v_fmac_f32_e32 v83, v146, v144
	v_cvt_pk_bf16_f32 v132, v80, v81
	v_cvt_pk_bf16_f32 v133, v82, v83
	v_lshlrev_b32_e32 v141, 16, v124
	v_and_b32_e32 v142, 0xffff0000, v124
	v_lshlrev_b32_e32 v143, 16, v125
	v_and_b32_e32 v144, 0xffff0000, v125
	v_fmac_f32_e32 v84, v146, v141
	v_fmac_f32_e32 v85, v146, v142
	v_fmac_f32_e32 v86, v146, v143
	v_fmac_f32_e32 v87, v146, v144
	v_cvt_pk_bf16_f32 v134, v84, v85
	v_cvt_pk_bf16_f32 v135, v86, v87
	v_lshlrev_b32_e32 v141, 16, v126
	v_and_b32_e32 v142, 0xffff0000, v126
	v_lshlrev_b32_e32 v143, 16, v127
	v_and_b32_e32 v144, 0xffff0000, v127
	v_fmac_f32_e32 v88, v146, v141
	v_fmac_f32_e32 v89, v146, v142
	v_fmac_f32_e32 v90, v146, v143
	v_fmac_f32_e32 v91, v146, v144
	v_cvt_pk_bf16_f32 v136, v88, v89
	v_cvt_pk_bf16_f32 v137, v90, v91
	v_lshlrev_b32_e32 v141, 16, v128
	v_and_b32_e32 v142, 0xffff0000, v128
	v_lshlrev_b32_e32 v143, 16, v129
	v_and_b32_e32 v144, 0xffff0000, v129
	v_fmac_f32_e32 v92, v146, v141
	v_fmac_f32_e32 v93, v146, v142
	v_fmac_f32_e32 v94, v146, v143
	v_fmac_f32_e32 v95, v146, v144
	v_cvt_pk_bf16_f32 v138, v92, v93
	v_cvt_pk_bf16_f32 v139, v94, v95
	s_mov_b64 s[26:27], s[86:87]
	s_mov_b64 s[28:29], s[88:89]
	s_mov_b64 s[86:87], s[12:13]
	s_mov_b64 s[88:89], s[14:15]
	s_mov_b32 s4, s83
	s_mov_b32 s5, s84
	s_waitcnt vmcnt(0)
	s_barrier
	ds_read_b128 v[4:7], v230 offset:16384
	ds_read_b128 v[8:11], v231 offset:16384
	ds_read_b128 v[12:15], v230 offset:18432
	ds_read_b128 v[16:19], v231 offset:18432
	ds_read_b128 v[20:23], v230 offset:20480
	ds_read_b128 v[24:27], v231 offset:20480
	ds_read_b128 v[28:31], v230 offset:22528
	ds_read_b128 v[32:35], v231 offset:22528
	ds_read_b128 v[36:39], v230 offset:24576
	ds_read_b128 v[40:43], v231 offset:24576
	global_store_dwordx2 v237, v[132:133], s[26:27]
	global_store_dwordx2 v237, v[134:135], s[26:27] offset:32
	global_store_dwordx2 v237, v[136:137], s[26:27] offset:64
	global_store_dwordx2 v237, v[138:139], s[26:27] offset:96
	s_mov_b64 s[90:91], exec
	s_mov_b64 exec, 0xffff
	global_store_dword v238, v140, s[28:29]
	s_mov_b64 exec, s[90:91]
	s_add_u32 s83, s4, 1
	s_mov_b32 s84, s5
	s_mul_i32 s74, s84, 1024
	s_lshl_b32 s75, s83, 7
	s_add_u32 s74, s74, s75
	s_lshl_b32 s75, s74, 7
	s_add_u32 s16, s60, s75
	s_addc_u32 s17, s61, 0
	s_lshl_b32 s75, s74, 1
	s_add_u32 s24, s64, s75
	s_addc_u32 s25, s65, 0
	s_add_u32 m0, s70, 0xc000
	s_nop 0
	global_load_lds_dwordx4 v232, s[16:17] nt
	s_add_u32 m0, s70, 0xe000
	s_nop 0
	global_load_lds_dwordx4 v233, s[16:17] nt
	s_add_u32 m0, s70, 0x1c000
	s_nop 0
	global_load_lds_dwordx4 v234, s[24:25] nt
	s_add_u32 m0, s70, 0x1e000
	s_nop 0
	global_load_lds_dwordx4 v235, s[24:25] nt
	s_lshl_b32 s74, s83, 9
	s_add_u32 s74, s74, s84
	s_lshl_b32 s75, s74, 7
	s_add_u32 s10, s30, s75
	s_addc_u32 s11, s31, 0
	s_add_u32 s12, s34, s75
	s_addc_u32 s13, s35, 0
	s_lshl_b32 s75, s74, 2
	s_add_u32 s14, s58, s75
	s_addc_u32 s15, s59, 0
	global_load_dwordx4 v[104:107], v236, s[10:11]
	global_load_dwordx4 v[108:111], v236, s[10:11] offset:64
	global_load_dwordx2 v[122:123], v237, s[12:13]
	global_load_dwordx2 v[124:125], v237, s[12:13] offset:32
	global_load_dwordx2 v[126:127], v237, s[12:13] offset:64
	global_load_dwordx2 v[128:129], v237, s[12:13] offset:96
	global_load_dword v121, v238, s[14:15]
	s_waitcnt lgkmcnt(0)
	v_mfma_f32_16x16x32_bf16 v[44:47], v[4:7], v[96:99], 0
	v_mfma_f32_16x16x32_bf16 v[48:51], v[12:15], v[96:99], 0
	v_mfma_f32_16x16x32_bf16 v[52:55], v[20:23], v[96:99], 0
	v_mfma_f32_16x16x32_bf16 v[56:59], v[28:31], v[96:99], 0
	v_mfma_f32_16x16x32_bf16 v[60:63], v[36:39], v[96:99], 0
	v_mfma_f32_16x16x32_bf16 v[44:47], v[8:11], v[100:103], v[44:47]
	v_mfma_f32_16x16x32_bf16 v[48:51], v[16:19], v[100:103], v[48:51]
	v_mfma_f32_16x16x32_bf16 v[52:55], v[24:27], v[100:103], v[52:55]
	v_mfma_f32_16x16x32_bf16 v[56:59], v[32:35], v[100:103], v[56:59]
	v_mfma_f32_16x16x32_bf16 v[60:63], v[40:43], v[100:103], v[60:63]
	ds_read_b128 v[4:7], v230 offset:26624
	ds_read_b128 v[8:11], v231 offset:26624
	ds_read_b128 v[12:15], v230 offset:28672
	ds_read_b128 v[16:19], v231 offset:28672
	ds_read_b128 v[20:23], v230 offset:30720
	ds_read_b128 v[24:27], v231 offset:30720
	ds_read_b128 v[28:31], v230 offset:32768
	ds_read_b128 v[32:35], v231 offset:32768
	s_nop 1
	v_fma_f32 v44, v44, s79, v185
	v_fma_f32 v45, v45, s79, v186
	v_fma_f32 v46, v46, s79, v187
	v_fma_f32 v47, v47, s79, v188
	v_fma_f32 v48, v48, s79, v189
	v_fma_f32 v49, v49, s79, v190
	v_fma_f32 v50, v50, s79, v191
	v_fma_f32 v51, v51, s79, v192
	v_fma_f32 v52, v52, s79, v193
	v_fma_f32 v53, v53, s79, v194
	v_fma_f32 v54, v54, s79, v195
	v_fma_f32 v55, v55, s79, v196
	v_fma_f32 v56, v56, s79, v197
	v_fma_f32 v57, v57, s79, v198
	v_fma_f32 v58, v58, s79, v199
	v_fma_f32 v59, v59, s79, v200
	v_fma_f32 v60, v60, s79, v201
	v_fma_f32 v61, v61, s79, v202
	v_fma_f32 v62, v62, s79, v203
	v_fma_f32 v63, v63, s79, v204
	s_waitcnt lgkmcnt(0)
	v_mfma_f32_16x16x32_bf16 v[64:67], v[4:7], v[96:99], 0
	v_mfma_f32_16x16x32_bf16 v[68:71], v[12:15], v[96:99], 0
	v_mfma_f32_16x16x32_bf16 v[72:75], v[20:23], v[96:99], 0
	v_mfma_f32_16x16x32_bf16 v[76:79], v[28:31], v[96:99], 0
	v_mfma_f32_16x16x32_bf16 v[64:67], v[8:11], v[100:103], v[64:67]
	v_mfma_f32_16x16x32_bf16 v[68:71], v[16:19], v[100:103], v[68:71]
	v_mfma_f32_16x16x32_bf16 v[72:75], v[24:27], v[100:103], v[72:75]
	v_mfma_f32_16x16x32_bf16 v[76:79], v[32:35], v[100:103], v[76:79]
	ds_read_b64 v[4:5], v221 offset:16384
	ds_read_b64 v[8:9], v221 offset:20480
	ds_read_b64 v[12:13], v221 offset:24576
	ds_read_b64 v[16:17], v221 offset:28672
	ds_read_b64 v[6:7], v222 offset:16384
	ds_read_b64 v[10:11], v222 offset:20480
	ds_read_b64 v[14:15], v222 offset:24576
	ds_read_b64 v[18:19], v222 offset:28672
	s_nop 1
	v_fma_f32 v64, v64, s79, v205
	v_fma_f32 v65, v65, s79, v206
	v_fma_f32 v66, v66, s79, v207
	v_fma_f32 v67, v67, s79, v208
	v_fma_f32 v68, v68, s79, v209
	v_fma_f32 v69, v69, s79, v210
	v_fma_f32 v70, v70, s79, v211
	v_fma_f32 v71, v71, s79, v212
	v_fma_f32 v72, v72, s79, v213
	v_fma_f32 v73, v73, s79, v214
	v_fma_f32 v74, v74, s79, v215
	v_fma_f32 v75, v75, s79, v216
	v_fma_f32 v76, v76, s79, v217
	v_fma_f32 v77, v77, s79, v218
	v_fma_f32 v78, v78, s79, v219
	v_fma_f32 v79, v79, s79, v220
	ds_read_b64 v[20:21], v223 offset:16384
	ds_read_b64 v[24:25], v223 offset:20480
	ds_read_b64 v[28:29], v223 offset:24576
	ds_read_b64 v[32:33], v223 offset:28672
	ds_read_b64 v[22:23], v224 offset:16384
	ds_read_b64 v[26:27], v224 offset:20480
	ds_read_b64 v[30:31], v224 offset:24576
	ds_read_b64 v[34:35], v224 offset:28672
	s_cmp_lg_u32 s4, 0
	s_cbranch_scc1 .Lat844_i2_nomask
	s_cmp_le_u32 s6, 0
	s_cbranch_scc1 .Lat844_i2_nomask
	v_mov_b32_e32 v44, v244
	v_mov_b32_e32 v45, v244
	v_mov_b32_e32 v46, v244
	v_mov_b32_e32 v47, v244
	s_cmp_le_u32 s6, 1
	s_cbranch_scc1 .Lat844_i2_nomask
	v_mov_b32_e32 v48, v244
	v_mov_b32_e32 v49, v244
	v_mov_b32_e32 v50, v244
	v_mov_b32_e32 v51, v244
	s_cmp_le_u32 s6, 2
	s_cbranch_scc1 .Lat844_i2_nomask
	v_mov_b32_e32 v52, v244
	v_mov_b32_e32 v53, v244
	v_mov_b32_e32 v54, v244
	v_mov_b32_e32 v55, v244
	s_cmp_le_u32 s6, 3
	s_cbranch_scc1 .Lat844_i2_nomask
	v_mov_b32_e32 v56, v244
	v_mov_b32_e32 v57, v244
	v_mov_b32_e32 v58, v244
	v_mov_b32_e32 v59, v244
	s_cmp_le_u32 s6, 4
	s_cbranch_scc1 .Lat844_i2_nomask
	v_mov_b32_e32 v60, v244
	v_mov_b32_e32 v61, v244
	v_mov_b32_e32 v62, v244
	v_mov_b32_e32 v63, v244
	s_cmp_le_u32 s6, 5
	s_cbranch_scc1 .Lat844_i2_nomask
	v_mov_b32_e32 v64, v244
	v_mov_b32_e32 v65, v244
	v_mov_b32_e32 v66, v244
	v_mov_b32_e32 v67, v244
	s_cmp_le_u32 s6, 6
	s_cbranch_scc1 .Lat844_i2_nomask
	v_mov_b32_e32 v68, v244
	v_mov_b32_e32 v69, v244
	v_mov_b32_e32 v70, v244
	v_mov_b32_e32 v71, v244
	s_cmp_le_u32 s6, 7
	s_cbranch_scc1 .Lat844_i2_nomask
	v_mov_b32_e32 v72, v244
	v_mov_b32_e32 v73, v244
	v_mov_b32_e32 v74, v244
	v_mov_b32_e32 v75, v244
.Lat844_i2_nomask:
	v_max3_f32 v245, v44, v45, v46
	v_max3_f32 v245, v245, v47, v48
	v_max3_f32 v245, v245, v49, v50
	v_max3_f32 v245, v245, v51, v52
	v_max3_f32 v245, v245, v53, v54
	v_max3_f32 v245, v245, v55, v56
	v_max3_f32 v245, v245, v57, v58
	v_max3_f32 v245, v245, v59, v60
	v_max3_f32 v245, v245, v61, v62
	v_max3_f32 v245, v245, v63, v64
	v_max3_f32 v245, v245, v65, v66
	v_max3_f32 v245, v245, v67, v68
	v_max3_f32 v245, v245, v69, v70
	v_max3_f32 v245, v245, v71, v72
	v_max3_f32 v245, v245, v73, v74
	v_max3_f32 v245, v245, v75, v76
	v_max3_f32 v245, v245, v77, v78
	v_max_f32_e32 v245, v245, v79
	v_mov_b32_e32 v148, v245
	s_nop 1
	v_permlane16_swap_b32 v245, v148
	v_max_f32_e32 v245, v245, v148
	v_mov_b32_e32 v148, v245
	s_nop 1
	v_permlane32_swap_b32 v245, v148
	v_max_f32_e32 v245, v245, v148
	v_sub_f32_e32 v44, v44, v245
	v_sub_f32_e32 v45, v45, v245
	v_sub_f32_e32 v46, v46, v245
	v_sub_f32_e32 v47, v47, v245
	v_exp_f32_e32 v44, v44
	v_exp_f32_e32 v45, v45
	v_exp_f32_e32 v46, v46
	v_exp_f32_e32 v47, v47
	v_sub_f32_e32 v48, v48, v245
	v_sub_f32_e32 v49, v49, v245
	v_sub_f32_e32 v50, v50, v245
	v_sub_f32_e32 v51, v51, v245
	v_exp_f32_e32 v48, v48
	v_exp_f32_e32 v49, v49
	v_exp_f32_e32 v50, v50
	v_exp_f32_e32 v51, v51
	v_mov_b32_e32 v149, v44
	v_mov_b32_e32 v150, v45
	v_mov_b32_e32 v151, v46
	v_mov_b32_e32 v152, v47
	v_cvt_pk_bf16_f32 v44, v44, v45
	v_cvt_pk_bf16_f32 v45, v46, v47
	v_sub_f32_e32 v52, v52, v245
	v_sub_f32_e32 v53, v53, v245
	v_sub_f32_e32 v54, v54, v245
	v_sub_f32_e32 v55, v55, v245
	v_exp_f32_e32 v52, v52
	v_exp_f32_e32 v53, v53
	v_exp_f32_e32 v54, v54
	v_exp_f32_e32 v55, v55
	v_add_f32_e32 v149, v149, v48
	v_add_f32_e32 v150, v150, v49
	v_add_f32_e32 v151, v151, v50
	v_add_f32_e32 v152, v152, v51
	v_cvt_pk_bf16_f32 v46, v48, v49
	v_cvt_pk_bf16_f32 v47, v50, v51
	v_sub_f32_e32 v56, v56, v245
	v_sub_f32_e32 v57, v57, v245
	v_sub_f32_e32 v58, v58, v245
	v_sub_f32_e32 v59, v59, v245
	v_exp_f32_e32 v56, v56
	v_exp_f32_e32 v57, v57
	v_exp_f32_e32 v58, v58
	v_exp_f32_e32 v59, v59
	v_add_f32_e32 v149, v149, v52
	v_add_f32_e32 v150, v150, v53
	v_add_f32_e32 v151, v151, v54
	v_add_f32_e32 v152, v152, v55
	v_cvt_pk_bf16_f32 v52, v52, v53
	v_cvt_pk_bf16_f32 v53, v54, v55
	v_sub_f32_e32 v60, v60, v245
	v_sub_f32_e32 v61, v61, v245
	v_sub_f32_e32 v62, v62, v245
	v_sub_f32_e32 v63, v63, v245
	v_exp_f32_e32 v60, v60
	v_exp_f32_e32 v61, v61
	v_exp_f32_e32 v62, v62
	v_exp_f32_e32 v63, v63
	v_add_f32_e32 v149, v149, v56
	v_add_f32_e32 v150, v150, v57
	v_add_f32_e32 v151, v151, v58
	v_add_f32_e32 v152, v152, v59
	v_cvt_pk_bf16_f32 v54, v56, v57
	v_cvt_pk_bf16_f32 v55, v58, v59
	v_sub_f32_e32 v64, v64, v245
	v_sub_f32_e32 v65, v65, v245
	v_sub_f32_e32 v66, v66, v245
	v_sub_f32_e32 v67, v67, v245
	v_exp_f32_e32 v64, v64
	v_exp_f32_e32 v65, v65
	v_exp_f32_e32 v66, v66
	v_exp_f32_e32 v67, v67
	v_add_f32_e32 v149, v149, v60
	v_add_f32_e32 v150, v150, v61
	v_add_f32_e32 v151, v151, v62
	v_add_f32_e32 v152, v152, v63
	v_cvt_pk_bf16_f32 v60, v60, v61
	v_cvt_pk_bf16_f32 v61, v62, v63
	v_sub_f32_e32 v68, v68, v245
	v_sub_f32_e32 v69, v69, v245
	v_sub_f32_e32 v70, v70, v245
	v_sub_f32_e32 v71, v71, v245
	v_exp_f32_e32 v68, v68
	v_exp_f32_e32 v69, v69
	v_exp_f32_e32 v70, v70
	v_exp_f32_e32 v71, v71
	v_add_f32_e32 v149, v149, v64
	v_add_f32_e32 v150, v150, v65
	v_add_f32_e32 v151, v151, v66
	v_add_f32_e32 v152, v152, v67
	v_cvt_pk_bf16_f32 v62, v64, v65
	v_cvt_pk_bf16_f32 v63, v66, v67
	v_sub_f32_e32 v72, v72, v245
	v_sub_f32_e32 v73, v73, v245
	v_sub_f32_e32 v74, v74, v245
	v_sub_f32_e32 v75, v75, v245
	v_exp_f32_e32 v72, v72
	v_exp_f32_e32 v73, v73
	v_exp_f32_e32 v74, v74
	v_exp_f32_e32 v75, v75
	v_add_f32_e32 v149, v149, v68
	v_add_f32_e32 v150, v150, v69
	v_add_f32_e32 v151, v151, v70
	v_add_f32_e32 v152, v152, v71
	v_cvt_pk_bf16_f32 v68, v68, v69
	v_cvt_pk_bf16_f32 v69, v70, v71
	v_sub_f32_e32 v76, v76, v245
	v_sub_f32_e32 v77, v77, v245
	v_sub_f32_e32 v78, v78, v245
	v_sub_f32_e32 v79, v79, v245
	v_exp_f32_e32 v76, v76
	v_exp_f32_e32 v77, v77
	v_exp_f32_e32 v78, v78
	v_exp_f32_e32 v79, v79
	v_add_f32_e32 v149, v149, v72
	v_add_f32_e32 v150, v150, v73
	v_add_f32_e32 v151, v151, v74
	v_add_f32_e32 v152, v152, v75
	v_cvt_pk_bf16_f32 v70, v72, v73
	v_cvt_pk_bf16_f32 v71, v74, v75
	s_nop 0
	v_add_f32_e32 v149, v149, v76
	v_add_f32_e32 v150, v150, v77
	v_add_f32_e32 v151, v151, v78
	v_add_f32_e32 v152, v152, v79
	v_cvt_pk_bf16_f32 v76, v76, v77
	v_cvt_pk_bf16_f32 v77, v78, v79
	v_mov_b32_e32 v78, 0
	v_mov_b32_e32 v79, 0
	v_add_f32_e32 v149, v149, v150
	v_add_f32_e32 v151, v151, v152
	v_add_f32_e32 v246, v149, v151
	s_waitcnt lgkmcnt(0)
	v_mfma_f32_16x16x32_bf16 v[80:83], v[4:7], v[44:47], 0
	v_mfma_f32_16x16x32_bf16 v[84:87], v[8:11], v[44:47], 0
	v_mfma_f32_16x16x32_bf16 v[88:91], v[12:15], v[44:47], 0
	v_mfma_f32_16x16x32_bf16 v[92:95], v[16:19], v[44:47], 0
	ds_read_b64 v[4:5], v225 offset:16384
	ds_read_b64 v[8:9], v225 offset:20480
	ds_read_b64 v[12:13], v225 offset:24576
	ds_read_b64 v[16:17], v225 offset:28672
	ds_read_b64 v[6:7], v226 offset:16384
	ds_read_b64 v[10:11], v226 offset:20480
	ds_read_b64 v[14:15], v226 offset:24576
	ds_read_b64 v[18:19], v226 offset:28672
	v_mfma_f32_16x16x32_bf16 v[80:83], v[20:23], v[52:55], v[80:83]
	v_mfma_f32_16x16x32_bf16 v[84:87], v[24:27], v[52:55], v[84:87]
	v_mfma_f32_16x16x32_bf16 v[88:91], v[28:31], v[52:55], v[88:91]
	v_mfma_f32_16x16x32_bf16 v[92:95], v[32:35], v[52:55], v[92:95]
	ds_read_b64 v[20:21], v227 offset:16384
	ds_read_b64 v[24:25], v227 offset:20480
	ds_read_b64 v[28:29], v227 offset:24576
	ds_read_b64 v[32:33], v227 offset:28672
	ds_read_b64 v[22:23], v228 offset:16384
	ds_read_b64 v[26:27], v228 offset:20480
	ds_read_b64 v[30:31], v228 offset:24576
	ds_read_b64 v[34:35], v228 offset:28672
	s_waitcnt lgkmcnt(8)
	v_mfma_f32_16x16x32_bf16 v[80:83], v[4:7], v[60:63], v[80:83]
	v_mfma_f32_16x16x32_bf16 v[84:87], v[8:11], v[60:63], v[84:87]
	v_mfma_f32_16x16x32_bf16 v[88:91], v[12:15], v[60:63], v[88:91]
	v_mfma_f32_16x16x32_bf16 v[92:95], v[16:19], v[60:63], v[92:95]
	ds_read_b64 v[4:5], v229 offset:16384
	ds_read_b64 v[8:9], v229 offset:20480
	ds_read_b64 v[12:13], v229 offset:24576
	ds_read_b64 v[16:17], v229 offset:28672
	v_mov_b32_e32 v6, 0
	v_mov_b32_e32 v7, 0
	v_mov_b32_e32 v10, 0
	v_mov_b32_e32 v11, 0
	v_mov_b32_e32 v14, 0
	v_mov_b32_e32 v15, 0
	v_mov_b32_e32 v18, 0
	v_mov_b32_e32 v19, 0
	s_waitcnt lgkmcnt(4)
	v_mfma_f32_16x16x32_bf16 v[80:83], v[20:23], v[68:71], v[80:83]
	v_mfma_f32_16x16x32_bf16 v[84:87], v[24:27], v[68:71], v[84:87]
	v_mfma_f32_16x16x32_bf16 v[88:91], v[28:31], v[68:71], v[88:91]
	v_mfma_f32_16x16x32_bf16 v[92:95], v[32:35], v[68:71], v[92:95]
	s_waitcnt lgkmcnt(0)
	v_mfma_f32_16x16x32_bf16 v[80:83], v[4:7], v[76:79], v[80:83]
	v_mfma_f32_16x16x32_bf16 v[84:87], v[8:11], v[76:79], v[84:87]
	v_mfma_f32_16x16x32_bf16 v[88:91], v[12:15], v[76:79], v[88:91]
	v_mfma_f32_16x16x32_bf16 v[92:95], v[16:19], v[76:79], v[92:95]
	v_mov_b32_e32 v148, v246
	s_nop 1
	v_permlane16_swap_b32 v246, v148
	v_add_f32_e32 v246, v246, v148
	v_mov_b32_e32 v148, v246
	s_nop 1
	v_permlane32_swap_b32 v246, v148
	v_add_f32_e32 v246, v246, v148
	v_rcp_f32_e32 v149, v246
	v_log_f32_e32 v150, v246
	s_nop 0
	v_add_f32_e32 v151, v245, v150
	v_mul_f32_e32 v151, 0x3f317218, v151
	v_max_f32_e32 v152, v120, v151
	v_sub_f32_e32 v153, v120, v152
	v_sub_f32_e32 v154, v151, v152
	v_mul_f32_e32 v153, 0x3fb8aa3b, v153
	v_mul_f32_e32 v154, 0x3fb8aa3b, v154
	v_exp_f32_e32 v153, v153
	v_exp_f32_e32 v154, v154
	s_nop 0
	v_add_f32_e32 v155, v153, v154
	v_rcp_f32_e32 v146, v155
	v_log_f32_e32 v150, v155
	s_nop 0
	v_mul_f32_e32 v154, v154, v146
	v_mul_f32_e32 v146, v153, v146
	v_mul_f32_e32 v147, v149, v154
	v_mul_f32_e32 v150, 0x3f317218, v150
	v_add_f32_e32 v140, v152, v150
	v_mul_f32_e32 v80, v80, v147
	v_mul_f32_e32 v81, v81, v147
	v_mul_f32_e32 v82, v82, v147
	v_mul_f32_e32 v83, v83, v147
	v_mul_f32_e32 v84, v84, v147
	v_mul_f32_e32 v85, v85, v147
	v_mul_f32_e32 v86, v86, v147
	v_mul_f32_e32 v87, v87, v147
	v_mul_f32_e32 v88, v88, v147
	v_mul_f32_e32 v89, v89, v147
	v_mul_f32_e32 v90, v90, v147
	v_mul_f32_e32 v91, v91, v147
	v_mul_f32_e32 v92, v92, v147
	v_mul_f32_e32 v93, v93, v147
	v_mul_f32_e32 v94, v94, v147
	v_mul_f32_e32 v95, v95, v147
	v_lshlrev_b32_e32 v141, 16, v112
	v_and_b32_e32 v142, 0xffff0000, v112
	v_lshlrev_b32_e32 v143, 16, v113
	v_and_b32_e32 v144, 0xffff0000, v113
	v_fmac_f32_e32 v80, v146, v141
	v_fmac_f32_e32 v81, v146, v142
	v_fmac_f32_e32 v82, v146, v143
	v_fmac_f32_e32 v83, v146, v144
	v_cvt_pk_bf16_f32 v132, v80, v81
	v_cvt_pk_bf16_f32 v133, v82, v83
	v_lshlrev_b32_e32 v141, 16, v114
	v_and_b32_e32 v142, 0xffff0000, v114
	v_lshlrev_b32_e32 v143, 16, v115
	v_and_b32_e32 v144, 0xffff0000, v115
	v_fmac_f32_e32 v84, v146, v141
	v_fmac_f32_e32 v85, v146, v142
	v_fmac_f32_e32 v86, v146, v143
	v_fmac_f32_e32 v87, v146, v144
	v_cvt_pk_bf16_f32 v134, v84, v85
	v_cvt_pk_bf16_f32 v135, v86, v87
	v_lshlrev_b32_e32 v141, 16, v116
	v_and_b32_e32 v142, 0xffff0000, v116
	v_lshlrev_b32_e32 v143, 16, v117
	v_and_b32_e32 v144, 0xffff0000, v117
	v_fmac_f32_e32 v88, v146, v141
	v_fmac_f32_e32 v89, v146, v142
	v_fmac_f32_e32 v90, v146, v143
	v_fmac_f32_e32 v91, v146, v144
	v_cvt_pk_bf16_f32 v136, v88, v89
	v_cvt_pk_bf16_f32 v137, v90, v91
	v_lshlrev_b32_e32 v141, 16, v118
	v_and_b32_e32 v142, 0xffff0000, v118
	v_lshlrev_b32_e32 v143, 16, v119
	v_and_b32_e32 v144, 0xffff0000, v119
	v_fmac_f32_e32 v92, v146, v141
	v_fmac_f32_e32 v93, v146, v142
	v_fmac_f32_e32 v94, v146, v143
	v_fmac_f32_e32 v95, v146, v144
	v_cvt_pk_bf16_f32 v138, v92, v93
	v_cvt_pk_bf16_f32 v139, v94, v95
	s_mov_b64 s[26:27], s[86:87]
	s_mov_b64 s[28:29], s[88:89]
	s_mov_b64 s[86:87], s[12:13]
	s_mov_b64 s[88:89], s[14:15]
	s_mov_b32 s4, s83
	s_mov_b32 s5, s84
	s_waitcnt vmcnt(0)
	s_barrier
	ds_read_b128 v[4:7], v230 offset:32768
	ds_read_b128 v[8:11], v231 offset:32768
	ds_read_b128 v[12:15], v230 offset:34816
	ds_read_b128 v[16:19], v231 offset:34816
	ds_read_b128 v[20:23], v230 offset:36864
	ds_read_b128 v[24:27], v231 offset:36864
	ds_read_b128 v[28:31], v230 offset:38912
	ds_read_b128 v[32:35], v231 offset:38912
	ds_read_b128 v[36:39], v230 offset:40960
	ds_read_b128 v[40:43], v231 offset:40960
	global_store_dwordx2 v237, v[132:133], s[26:27]
	global_store_dwordx2 v237, v[134:135], s[26:27] offset:32
	global_store_dwordx2 v237, v[136:137], s[26:27] offset:64
	global_store_dwordx2 v237, v[138:139], s[26:27] offset:96
	s_mov_b64 s[90:91], exec
	s_mov_b64 exec, 0xffff
	global_store_dword v238, v140, s[28:29]
	s_mov_b64 exec, s[90:91]
	s_cmp_eq_u32 s7, 1
	s_cbranch_scc1 .Lat844_i3_nonext
	s_add_u32 s83, s4, 1
	s_mov_b32 s84, s5
	s_mul_i32 s74, s84, 1024
	s_lshl_b32 s75, s83, 7
	s_add_u32 s74, s74, s75
	s_lshl_b32 s75, s74, 7
	s_add_u32 s16, s60, s75
	s_addc_u32 s17, s61, 0
	s_lshl_b32 s75, s74, 1
	s_add_u32 s24, s64, s75
	s_addc_u32 s25, s65, 0
	s_add_u32 m0, s70, 0x0
	s_nop 0
	global_load_lds_dwordx4 v232, s[16:17] nt
	s_add_u32 m0, s70, 0x2000
	s_nop 0
	global_load_lds_dwordx4 v233, s[16:17] nt
	s_add_u32 m0, s70, 0x10000
	s_nop 0
	global_load_lds_dwordx4 v234, s[24:25] nt
	s_add_u32 m0, s70, 0x12000
	s_nop 0
	global_load_lds_dwordx4 v235, s[24:25] nt
	s_lshl_b32 s74, s83, 9
	s_add_u32 s74, s74, s84
	s_lshl_b32 s75, s74, 7
	s_add_u32 s10, s30, s75
	s_addc_u32 s11, s31, 0
	s_add_u32 s12, s34, s75
	s_addc_u32 s13, s35, 0
	s_lshl_b32 s75, s74, 2
	s_add_u32 s14, s58, s75
	s_addc_u32 s15, s59, 0
	global_load_dwordx4 v[96:99], v236, s[10:11]
	global_load_dwordx4 v[100:103], v236, s[10:11] offset:64
	global_load_dwordx2 v[112:113], v237, s[12:13]
	global_load_dwordx2 v[114:115], v237, s[12:13] offset:32
	global_load_dwordx2 v[116:117], v237, s[12:13] offset:64
	global_load_dwordx2 v[118:119], v237, s[12:13] offset:96
	global_load_dword v120, v238, s[14:15]

.Lat844_i3_nomask:
	v_max3_f32 v245, v44, v45, v46
	v_max3_f32 v245, v245, v47, v48
	v_max3_f32 v245, v245, v49, v50
	v_max3_f32 v245, v245, v51, v52
	v_max3_f32 v245, v245, v53, v54
	v_max3_f32 v245, v245, v55, v56
	v_max3_f32 v245, v245, v57, v58
	v_max3_f32 v245, v245, v59, v60
	v_max3_f32 v245, v245, v61, v62
	v_max3_f32 v245, v245, v63, v64
	v_max3_f32 v245, v245, v65, v66
	v_max3_f32 v245, v245, v67, v68
	v_max3_f32 v245, v245, v69, v70
	v_max3_f32 v245, v245, v71, v72
	v_max3_f32 v245, v245, v73, v74
	v_max3_f32 v245, v245, v75, v76
	v_max3_f32 v245, v245, v77, v78
	v_max_f32_e32 v245, v245, v79
	v_mov_b32_e32 v148, v245
	s_nop 1
	v_permlane16_swap_b32 v245, v148
	v_max_f32_e32 v245, v245, v148
	v_mov_b32_e32 v148, v245
	s_nop 1
	v_permlane32_swap_b32 v245, v148
	v_max_f32_e32 v245, v245, v148
	v_sub_f32_e32 v44, v44, v245
	v_sub_f32_e32 v45, v45, v245
	v_sub_f32_e32 v46, v46, v245
	v_sub_f32_e32 v47, v47, v245
	v_exp_f32_e32 v44, v44
	v_exp_f32_e32 v45, v45
	v_exp_f32_e32 v46, v46
	v_exp_f32_e32 v47, v47
	v_sub_f32_e32 v48, v48, v245
	v_sub_f32_e32 v49, v49, v245
	v_sub_f32_e32 v50, v50, v245
	v_sub_f32_e32 v51, v51, v245
	v_exp_f32_e32 v48, v48
	v_exp_f32_e32 v49, v49
	v_exp_f32_e32 v50, v50
	v_exp_f32_e32 v51, v51
	v_mov_b32_e32 v149, v44
	v_mov_b32_e32 v150, v45
	v_mov_b32_e32 v151, v46
	v_mov_b32_e32 v152, v47
	v_cvt_pk_bf16_f32 v44, v44, v45
	v_cvt_pk_bf16_f32 v45, v46, v47
	v_sub_f32_e32 v52, v52, v245
	v_sub_f32_e32 v53, v53, v245
	v_sub_f32_e32 v54, v54, v245
	v_sub_f32_e32 v55, v55, v245
	v_exp_f32_e32 v52, v52
	v_exp_f32_e32 v53, v53
	v_exp_f32_e32 v54, v54
	v_exp_f32_e32 v55, v55
	v_add_f32_e32 v149, v149, v48
	v_add_f32_e32 v150, v150, v49
	v_add_f32_e32 v151, v151, v50
	v_add_f32_e32 v152, v152, v51
	v_cvt_pk_bf16_f32 v46, v48, v49
	v_cvt_pk_bf16_f32 v47, v50, v51
	v_sub_f32_e32 v56, v56, v245
	v_sub_f32_e32 v57, v57, v245
	v_sub_f32_e32 v58, v58, v245
	v_sub_f32_e32 v59, v59, v245
	v_exp_f32_e32 v56, v56
	v_exp_f32_e32 v57, v57
	v_exp_f32_e32 v58, v58
	v_exp_f32_e32 v59, v59
	v_add_f32_e32 v149, v149, v52
	v_add_f32_e32 v150, v150, v53
	v_add_f32_e32 v151, v151, v54
	v_add_f32_e32 v152, v152, v55
	v_cvt_pk_bf16_f32 v52, v52, v53
	v_cvt_pk_bf16_f32 v53, v54, v55
	v_sub_f32_e32 v60, v60, v245
	v_sub_f32_e32 v61, v61, v245
	v_sub_f32_e32 v62, v62, v245
	v_sub_f32_e32 v63, v63, v245
	v_exp_f32_e32 v60, v60
	v_exp_f32_e32 v61, v61
	v_exp_f32_e32 v62, v62
	v_exp_f32_e32 v63, v63
	v_add_f32_e32 v149, v149, v56
	v_add_f32_e32 v150, v150, v57
	v_add_f32_e32 v151, v151, v58
	v_add_f32_e32 v152, v152, v59
	v_cvt_pk_bf16_f32 v54, v56, v57
	v_cvt_pk_bf16_f32 v55, v58, v59
	v_sub_f32_e32 v64, v64, v245
	v_sub_f32_e32 v65, v65, v245
	v_sub_f32_e32 v66, v66, v245
	v_sub_f32_e32 v67, v67, v245
	v_exp_f32_e32 v64, v64
	v_exp_f32_e32 v65, v65
	v_exp_f32_e32 v66, v66
	v_exp_f32_e32 v67, v67
	v_add_f32_e32 v149, v149, v60
	v_add_f32_e32 v150, v150, v61
	v_add_f32_e32 v151, v151, v62
	v_add_f32_e32 v152, v152, v63
	v_cvt_pk_bf16_f32 v60, v60, v61
	v_cvt_pk_bf16_f32 v61, v62, v63
	v_sub_f32_e32 v68, v68, v245
	v_sub_f32_e32 v69, v69, v245
	v_sub_f32_e32 v70, v70, v245
	v_sub_f32_e32 v71, v71, v245
	v_exp_f32_e32 v68, v68
	v_exp_f32_e32 v69, v69
	v_exp_f32_e32 v70, v70
	v_exp_f32_e32 v71, v71
	v_add_f32_e32 v149, v149, v64
	v_add_f32_e32 v150, v150, v65
	v_add_f32_e32 v151, v151, v66
	v_add_f32_e32 v152, v152, v67
	v_cvt_pk_bf16_f32 v62, v64, v65
	v_cvt_pk_bf16_f32 v63, v66, v67
	v_sub_f32_e32 v72, v72, v245
	v_sub_f32_e32 v73, v73, v245
	v_sub_f32_e32 v74, v74, v245
	v_sub_f32_e32 v75, v75, v245
	v_exp_f32_e32 v72, v72
	v_exp_f32_e32 v73, v73
	v_exp_f32_e32 v74, v74
	v_exp_f32_e32 v75, v75
	v_add_f32_e32 v149, v149, v68
	v_add_f32_e32 v150, v150, v69
	v_add_f32_e32 v151, v151, v70
	v_add_f32_e32 v152, v152, v71
	v_cvt_pk_bf16_f32 v68, v68, v69
	v_cvt_pk_bf16_f32 v69, v70, v71
	v_sub_f32_e32 v76, v76, v245
	v_sub_f32_e32 v77, v77, v245
	v_sub_f32_e32 v78, v78, v245
	v_sub_f32_e32 v79, v79, v245
	v_exp_f32_e32 v76, v76
	v_exp_f32_e32 v77, v77
	v_exp_f32_e32 v78, v78
	v_exp_f32_e32 v79, v79
	v_add_f32_e32 v149, v149, v72
	v_add_f32_e32 v150, v150, v73
	v_add_f32_e32 v151, v151, v74
	v_add_f32_e32 v152, v152, v75
	v_cvt_pk_bf16_f32 v70, v72, v73
	v_cvt_pk_bf16_f32 v71, v74, v75
	s_nop 0
	v_add_f32_e32 v149, v149, v76
	v_add_f32_e32 v150, v150, v77
	v_add_f32_e32 v151, v151, v78
	v_add_f32_e32 v152, v152, v79
	v_cvt_pk_bf16_f32 v76, v76, v77
	v_cvt_pk_bf16_f32 v77, v78, v79
	v_mov_b32_e32 v78, 0
	v_mov_b32_e32 v79, 0
	v_add_f32_e32 v149, v149, v150
	v_add_f32_e32 v151, v151, v152
	v_add_f32_e32 v246, v149, v151
	s_waitcnt lgkmcnt(0)
	v_mfma_f32_16x16x32_bf16 v[80:83], v[4:7], v[44:47], 0
	v_mfma_f32_16x16x32_bf16 v[84:87], v[8:11], v[44:47], 0
	v_mfma_f32_16x16x32_bf16 v[88:91], v[12:15], v[44:47], 0
	v_mfma_f32_16x16x32_bf16 v[92:95], v[16:19], v[44:47], 0
	ds_read_b64 v[4:5], v225 offset:32768
	ds_read_b64 v[8:9], v225 offset:36864
	ds_read_b64 v[12:13], v225 offset:40960
	ds_read_b64 v[16:17], v225 offset:45056
	ds_read_b64 v[6:7], v226 offset:32768
	ds_read_b64 v[10:11], v226 offset:36864
	ds_read_b64 v[14:15], v226 offset:40960
	ds_read_b64 v[18:19], v226 offset:45056
	v_mfma_f32_16x16x32_bf16 v[80:83], v[20:23], v[52:55], v[80:83]
	v_mfma_f32_16x16x32_bf16 v[84:87], v[24:27], v[52:55], v[84:87]
	v_mfma_f32_16x16x32_bf16 v[88:91], v[28:31], v[52:55], v[88:91]
	v_mfma_f32_16x16x32_bf16 v[92:95], v[32:35], v[52:55], v[92:95]
	ds_read_b64 v[20:21], v227 offset:32768
	ds_read_b64 v[24:25], v227 offset:36864
	ds_read_b64 v[28:29], v227 offset:40960
	ds_read_b64 v[32:33], v227 offset:45056
	ds_read_b64 v[22:23], v228 offset:32768
	ds_read_b64 v[26:27], v228 offset:36864
	ds_read_b64 v[30:31], v228 offset:40960
	ds_read_b64 v[34:35], v228 offset:45056
	s_waitcnt lgkmcnt(8)
	v_mfma_f32_16x16x32_bf16 v[80:83], v[4:7], v[60:63], v[80:83]
	v_mfma_f32_16x16x32_bf16 v[84:87], v[8:11], v[60:63], v[84:87]
	v_mfma_f32_16x16x32_bf16 v[88:91], v[12:15], v[60:63], v[88:91]
	v_mfma_f32_16x16x32_bf16 v[92:95], v[16:19], v[60:63], v[92:95]
	ds_read_b64 v[4:5], v229 offset:32768
	ds_read_b64 v[8:9], v229 offset:36864
	ds_read_b64 v[12:13], v229 offset:40960
	ds_read_b64 v[16:17], v229 offset:45056
	v_mov_b32_e32 v6, 0
	v_mov_b32_e32 v7, 0
	v_mov_b32_e32 v10, 0
	v_mov_b32_e32 v11, 0
	v_mov_b32_e32 v14, 0
	v_mov_b32_e32 v15, 0
	v_mov_b32_e32 v18, 0
	v_mov_b32_e32 v19, 0
	s_waitcnt lgkmcnt(4)
	v_mfma_f32_16x16x32_bf16 v[80:83], v[20:23], v[68:71], v[80:83]
	v_mfma_f32_16x16x32_bf16 v[84:87], v[24:27], v[68:71], v[84:87]
	v_mfma_f32_16x16x32_bf16 v[88:91], v[28:31], v[68:71], v[88:91]
	v_mfma_f32_16x16x32_bf16 v[92:95], v[32:35], v[68:71], v[92:95]
	s_waitcnt lgkmcnt(0)
	v_mfma_f32_16x16x32_bf16 v[80:83], v[4:7], v[76:79], v[80:83]
	v_mfma_f32_16x16x32_bf16 v[84:87], v[8:11], v[76:79], v[84:87]
	v_mfma_f32_16x16x32_bf16 v[88:91], v[12:15], v[76:79], v[88:91]
	v_mfma_f32_16x16x32_bf16 v[92:95], v[16:19], v[76:79], v[92:95]
	v_mov_b32_e32 v148, v246
	s_nop 1
	v_permlane16_swap_b32 v246, v148
	v_add_f32_e32 v246, v246, v148
	v_mov_b32_e32 v148, v246
	s_nop 1
	v_permlane32_swap_b32 v246, v148
	v_add_f32_e32 v246, v246, v148
	v_rcp_f32_e32 v149, v246
	v_log_f32_e32 v150, v246
	s_nop 0
	v_add_f32_e32 v151, v245, v150
	v_mul_f32_e32 v151, 0x3f317218, v151
	v_max_f32_e32 v152, v121, v151
	v_sub_f32_e32 v153, v121, v152
	v_sub_f32_e32 v154, v151, v152
	v_mul_f32_e32 v153, 0x3fb8aa3b, v153
	v_mul_f32_e32 v154, 0x3fb8aa3b, v154
	v_exp_f32_e32 v153, v153
	v_exp_f32_e32 v154, v154
	s_nop 0
	v_add_f32_e32 v155, v153, v154
	v_rcp_f32_e32 v146, v155
	v_log_f32_e32 v150, v155
	s_nop 0
	v_mul_f32_e32 v154, v154, v146
	v_mul_f32_e32 v146, v153, v146
	v_mul_f32_e32 v147, v149, v154
	v_mul_f32_e32 v150, 0x3f317218, v150
	v_add_f32_e32 v140, v152, v150
	v_mul_f32_e32 v80, v80, v147
	v_mul_f32_e32 v81, v81, v147
	v_mul_f32_e32 v82, v82, v147
	v_mul_f32_e32 v83, v83, v147
	v_mul_f32_e32 v84, v84, v147
	v_mul_f32_e32 v85, v85, v147
	v_mul_f32_e32 v86, v86, v147
	v_mul_f32_e32 v87, v87, v147
	v_mul_f32_e32 v88, v88, v147
	v_mul_f32_e32 v89, v89, v147
	v_mul_f32_e32 v90, v90, v147
	v_mul_f32_e32 v91, v91, v147
	v_mul_f32_e32 v92, v92, v147
	v_mul_f32_e32 v93, v93, v147
	v_mul_f32_e32 v94, v94, v147
	v_mul_f32_e32 v95, v95, v147
	v_lshlrev_b32_e32 v141, 16, v122
	v_and_b32_e32 v142, 0xffff0000, v122
	v_lshlrev_b32_e32 v143, 16, v123
	v_and_b32_e32 v144, 0xffff0000, v123
	v_fmac_f32_e32 v80, v146, v141
	v_fmac_f32_e32 v81, v146, v142
	v_fmac_f32_e32 v82, v146, v143
	v_fmac_f32_e32 v83, v146, v144
	v_cvt_pk_bf16_f32 v132, v80, v81
	v_cvt_pk_bf16_f32 v133, v82, v83
	v_lshlrev_b32_e32 v141, 16, v124
	v_and_b32_e32 v142, 0xffff0000, v124
	v_lshlrev_b32_e32 v143, 16, v125
	v_and_b32_e32 v144, 0xffff0000, v125
	v_fmac_f32_e32 v84, v146, v141
	v_fmac_f32_e32 v85, v146, v142
	v_fmac_f32_e32 v86, v146, v143
	v_fmac_f32_e32 v87, v146, v144
	v_cvt_pk_bf16_f32 v134, v84, v85
	v_cvt_pk_bf16_f32 v135, v86, v87
	v_lshlrev_b32_e32 v141, 16, v126
	v_and_b32_e32 v142, 0xffff0000, v126
	v_lshlrev_b32_e32 v143, 16, v127
	v_and_b32_e32 v144, 0xffff0000, v127
	v_fmac_f32_e32 v88, v146, v141
	v_fmac_f32_e32 v89, v146, v142
	v_fmac_f32_e32 v90, v146, v143
	v_fmac_f32_e32 v91, v146, v144
	v_cvt_pk_bf16_f32 v136, v88, v89
	v_cvt_pk_bf16_f32 v137, v90, v91
	v_lshlrev_b32_e32 v141, 16, v128
	v_and_b32_e32 v142, 0xffff0000, v128
	v_lshlrev_b32_e32 v143, 16, v129
	v_and_b32_e32 v144, 0xffff0000, v129
	v_fmac_f32_e32 v92, v146, v141
	v_fmac_f32_e32 v93, v146, v142
	v_fmac_f32_e32 v94, v146, v143
	v_fmac_f32_e32 v95, v146, v144
	v_cvt_pk_bf16_f32 v138, v92, v93
	v_cvt_pk_bf16_f32 v139, v94, v95
	s_mov_b64 s[26:27], s[86:87]
	s_mov_b64 s[28:29], s[88:89]
	s_mov_b64 s[86:87], s[12:13]
	s_mov_b64 s[88:89], s[14:15]
	s_mov_b32 s4, s83
	s_mov_b32 s5, s84
	s_add_u32 s7, s7, 1
	s_cmp_lt_u32 s7, 2
	s_cbranch_scc1 .Lat844_loop
	s_setprio 0
	global_store_dwordx2 v237, v[132:133], s[26:27]
	global_store_dwordx2 v237, v[134:135], s[26:27] offset:32
	global_store_dwordx2 v237, v[136:137], s[26:27] offset:64
	global_store_dwordx2 v237, v[138:139], s[26:27] offset:96
	s_mov_b64 s[90:91], exec
	s_mov_b64 exec, 0xffff
	global_store_dword v238, v140, s[28:29]
	s_mov_b64 exec, s[90:91]
	s_mov_b32 s67, 0x10000
	s_mov_b32 s68, 0x14000
	v_mov_b32_e32 v183, v239
	v_mov_b32_e32 v184, v240
	s_waitcnt vmcnt(0)
	s_barrier
	s_waitcnt vmcnt(0)
	s_barrier
	s_mov_b64 s[4:5], exec
	v_readlane_b32 s0, v252, 2
	v_readlane_b32 s30, v253, 24
	v_readlane_b32 s1, v252, 3
	v_readlane_b32 s31, v253, 25
	v_readlane_b32 s34, v253, 15
	v_readlane_b32 s36, v252, 27
	v_readlane_b32 s8, v253, 19
	v_readlane_b32 s10, v253, 21
	v_readlane_b32 s38, v252, 29
	v_readlane_b32 s60, v252, 31
	v_readlane_b32 s64, v252, 33
	v_readlane_b32 s70, v252, 35
	v_readlane_b32 s74, v252, 37
	s_and_b64 s[0:1], s[4:5], s[0:1]
	v_readlane_b32 s28, v253, 23
	v_readlane_b32 s35, v253, 16
	v_readlane_b32 s29, v252, 26
	v_readlane_b32 s31, v253, 18
	v_readlane_b32 s37, v252, 28
	v_readlane_b32 s9, v253, 20
	v_readlane_b32 s11, v253, 22
	v_readlane_b32 s39, v252, 30
	v_readlane_b32 s61, v252, 32
	v_readlane_b32 s65, v252, 34
	v_readlane_b32 s71, v252, 36
	v_readlane_b32 s75, v252, 38
	v_readlane_b32 s63, v253, 17
	s_mov_b64 exec, s[0:1]
	s_cbranch_execz .LBB0_916
	v_mov_b32_e32 v0, 0x20000
	ds_read_b64 v[0:1], v0
	s_getreg_b32 s44, hwreg(HW_REG_XCC_ID, 0, 4)
	s_lshl_b32 s44, s44, 7
	s_add_u32 s44, s44, 0xdc03600
	v_mov_b32_e32 v2, s44
	v_mov_b32_e32 v4, 1
	s_waitcnt vmcnt(0) lgkmcnt(0)
	global_atomic_add v5, v2, v4, s[42:43] sc0
	buffer_inv sc1
	s_add_u32 s100, s100, 1
	v_readfirstlane_b32 s46, v0
	v_readfirstlane_b32 s47, v1
	v_mov_b32_e32 v2, 0xdc03e00
	s_nop 3
	s_mul_i32 s48, s46, s100
	s_mul_i32 s49, s47, s100
	s_waitcnt vmcnt(1)
	v_readfirstlane_b32 s50, v5
	s_nop 3
	s_add_u32 s50, s50, 1
	s_cmp_lg_u32 s50, s48
	s_cbranch_scc1 .Lxb7_poll
	buffer_wbl2 sc1
	s_waitcnt vmcnt(0)
	global_atomic_add v2, v4, s[42:43]

.Lat991_i0_nomask:
	v_max3_f32 v245, v44, v45, v46
	v_max3_f32 v245, v245, v47, v48
	v_max3_f32 v245, v245, v49, v50
	v_max3_f32 v245, v245, v51, v52
	v_max3_f32 v245, v245, v53, v54
	v_max3_f32 v245, v245, v55, v56
	v_max3_f32 v245, v245, v57, v58
	v_max3_f32 v245, v245, v59, v60
	v_max3_f32 v245, v245, v61, v62
	v_max3_f32 v245, v245, v63, v64
	v_max3_f32 v245, v245, v65, v66
	v_max3_f32 v245, v245, v67, v68
	v_max3_f32 v245, v245, v69, v70
	v_max3_f32 v245, v245, v71, v72
	v_max3_f32 v245, v245, v73, v74
	v_max3_f32 v245, v245, v75, v76
	v_max3_f32 v245, v245, v77, v78
	v_max_f32_e32 v245, v245, v79
	v_mov_b32_e32 v148, v245
	s_nop 1
	v_permlane16_swap_b32 v245, v148
	v_max_f32_e32 v245, v245, v148
	v_mov_b32_e32 v148, v245
	s_nop 1
	v_permlane32_swap_b32 v245, v148
	v_max_f32_e32 v245, v245, v148
	v_sub_f32_e32 v44, v44, v245
	v_sub_f32_e32 v45, v45, v245
	v_sub_f32_e32 v46, v46, v245
	v_sub_f32_e32 v47, v47, v245
	v_exp_f32_e32 v44, v44
	v_exp_f32_e32 v45, v45
	v_exp_f32_e32 v46, v46
	v_exp_f32_e32 v47, v47
	v_sub_f32_e32 v48, v48, v245
	v_sub_f32_e32 v49, v49, v245
	v_sub_f32_e32 v50, v50, v245
	v_sub_f32_e32 v51, v51, v245
	v_exp_f32_e32 v48, v48
	v_exp_f32_e32 v49, v49
	v_exp_f32_e32 v50, v50
	v_exp_f32_e32 v51, v51
	v_mov_b32_e32 v149, v44
	v_mov_b32_e32 v150, v45
	v_mov_b32_e32 v151, v46
	v_mov_b32_e32 v152, v47
	v_cvt_pk_bf16_f32 v44, v44, v45
	v_cvt_pk_bf16_f32 v45, v46, v47
	v_sub_f32_e32 v52, v52, v245
	v_sub_f32_e32 v53, v53, v245
	v_sub_f32_e32 v54, v54, v245
	v_sub_f32_e32 v55, v55, v245
	v_exp_f32_e32 v52, v52
	v_exp_f32_e32 v53, v53
	v_exp_f32_e32 v54, v54
	v_exp_f32_e32 v55, v55
	v_add_f32_e32 v149, v149, v48
	v_add_f32_e32 v150, v150, v49
	v_add_f32_e32 v151, v151, v50
	v_add_f32_e32 v152, v152, v51
	v_cvt_pk_bf16_f32 v46, v48, v49
	v_cvt_pk_bf16_f32 v47, v50, v51
	v_sub_f32_e32 v56, v56, v245
	v_sub_f32_e32 v57, v57, v245
	v_sub_f32_e32 v58, v58, v245
	v_sub_f32_e32 v59, v59, v245
	v_exp_f32_e32 v56, v56
	v_exp_f32_e32 v57, v57
	v_exp_f32_e32 v58, v58
	v_exp_f32_e32 v59, v59
	v_add_f32_e32 v149, v149, v52
	v_add_f32_e32 v150, v150, v53
	v_add_f32_e32 v151, v151, v54
	v_add_f32_e32 v152, v152, v55
	v_cvt_pk_bf16_f32 v52, v52, v53
	v_cvt_pk_bf16_f32 v53, v54, v55
	v_sub_f32_e32 v60, v60, v245
	v_sub_f32_e32 v61, v61, v245
	v_sub_f32_e32 v62, v62, v245
	v_sub_f32_e32 v63, v63, v245
	v_exp_f32_e32 v60, v60
	v_exp_f32_e32 v61, v61
	v_exp_f32_e32 v62, v62
	v_exp_f32_e32 v63, v63
	v_add_f32_e32 v149, v149, v56
	v_add_f32_e32 v150, v150, v57
	v_add_f32_e32 v151, v151, v58
	v_add_f32_e32 v152, v152, v59
	v_cvt_pk_bf16_f32 v54, v56, v57
	v_cvt_pk_bf16_f32 v55, v58, v59
	v_sub_f32_e32 v64, v64, v245
	v_sub_f32_e32 v65, v65, v245
	v_sub_f32_e32 v66, v66, v245
	v_sub_f32_e32 v67, v67, v245
	v_exp_f32_e32 v64, v64
	v_exp_f32_e32 v65, v65
	v_exp_f32_e32 v66, v66
	v_exp_f32_e32 v67, v67
	v_add_f32_e32 v149, v149, v60
	v_add_f32_e32 v150, v150, v61
	v_add_f32_e32 v151, v151, v62
	v_add_f32_e32 v152, v152, v63
	v_cvt_pk_bf16_f32 v60, v60, v61
	v_cvt_pk_bf16_f32 v61, v62, v63
	v_sub_f32_e32 v68, v68, v245
	v_sub_f32_e32 v69, v69, v245
	v_sub_f32_e32 v70, v70, v245
	v_sub_f32_e32 v71, v71, v245
	v_exp_f32_e32 v68, v68
	v_exp_f32_e32 v69, v69
	v_exp_f32_e32 v70, v70
	v_exp_f32_e32 v71, v71
	v_add_f32_e32 v149, v149, v64
	v_add_f32_e32 v150, v150, v65
	v_add_f32_e32 v151, v151, v66
	v_add_f32_e32 v152, v152, v67
	v_cvt_pk_bf16_f32 v62, v64, v65
	v_cvt_pk_bf16_f32 v63, v66, v67
	v_sub_f32_e32 v72, v72, v245
	v_sub_f32_e32 v73, v73, v245
	v_sub_f32_e32 v74, v74, v245
	v_sub_f32_e32 v75, v75, v245
	v_exp_f32_e32 v72, v72
	v_exp_f32_e32 v73, v73
	v_exp_f32_e32 v74, v74
	v_exp_f32_e32 v75, v75
	v_add_f32_e32 v149, v149, v68
	v_add_f32_e32 v150, v150, v69
	v_add_f32_e32 v151, v151, v70
	v_add_f32_e32 v152, v152, v71
	v_cvt_pk_bf16_f32 v68, v68, v69
	v_cvt_pk_bf16_f32 v69, v70, v71
	v_sub_f32_e32 v76, v76, v245
	v_sub_f32_e32 v77, v77, v245
	v_sub_f32_e32 v78, v78, v245
	v_sub_f32_e32 v79, v79, v245
	v_exp_f32_e32 v76, v76
	v_exp_f32_e32 v77, v77
	v_exp_f32_e32 v78, v78
	v_exp_f32_e32 v79, v79
	v_add_f32_e32 v149, v149, v72
	v_add_f32_e32 v150, v150, v73
	v_add_f32_e32 v151, v151, v74
	v_add_f32_e32 v152, v152, v75
	v_cvt_pk_bf16_f32 v70, v72, v73
	v_cvt_pk_bf16_f32 v71, v74, v75
	s_nop 0
	v_add_f32_e32 v149, v149, v76
	v_add_f32_e32 v150, v150, v77
	v_add_f32_e32 v151, v151, v78
	v_add_f32_e32 v152, v152, v79
	v_cvt_pk_bf16_f32 v76, v76, v77
	v_cvt_pk_bf16_f32 v77, v78, v79
	v_mov_b32_e32 v78, 0
	v_mov_b32_e32 v79, 0
	v_add_f32_e32 v149, v149, v150
	v_add_f32_e32 v151, v151, v152
	v_add_f32_e32 v246, v149, v151
	s_waitcnt lgkmcnt(0)
	v_mfma_f32_16x16x32_bf16 v[80:83], v[4:7], v[44:47], 0
	v_mfma_f32_16x16x32_bf16 v[84:87], v[8:11], v[44:47], 0
	v_mfma_f32_16x16x32_bf16 v[88:91], v[12:15], v[44:47], 0
	v_mfma_f32_16x16x32_bf16 v[92:95], v[16:19], v[44:47], 0
	s_cmp_gt_u32 s6, 4
	s_cselect_b32 s74, 0, 0xffff0000
	v_add_u32_e32 v146, s74, v225
	ds_read_b64 v[4:5], v146 offset:49152
	ds_read_b64 v[8:9], v146 offset:53248
	ds_read_b64 v[12:13], v146 offset:57344
	ds_read_b64 v[16:17], v146 offset:61440
	s_cmp_gt_u32 s6, 5
	s_cselect_b32 s74, 0, 0xffff0000
	v_add_u32_e32 v146, s74, v226
	ds_read_b64 v[6:7], v146 offset:49152
	ds_read_b64 v[10:11], v146 offset:53248
	ds_read_b64 v[14:15], v146 offset:57344
	ds_read_b64 v[18:19], v146 offset:61440
	v_mfma_f32_16x16x32_bf16 v[80:83], v[20:23], v[52:55], v[80:83]
	v_mfma_f32_16x16x32_bf16 v[84:87], v[24:27], v[52:55], v[84:87]
	v_mfma_f32_16x16x32_bf16 v[88:91], v[28:31], v[52:55], v[88:91]
	v_mfma_f32_16x16x32_bf16 v[92:95], v[32:35], v[52:55], v[92:95]
	s_cmp_gt_u32 s6, 6
	s_cselect_b32 s74, 0, 0xffff0000
	v_add_u32_e32 v146, s74, v227
	ds_read_b64 v[20:21], v146 offset:49152
	ds_read_b64 v[24:25], v146 offset:53248
	ds_read_b64 v[28:29], v146 offset:57344
	ds_read_b64 v[32:33], v146 offset:61440
	s_cmp_gt_u32 s6, 7
	s_cselect_b32 s74, 0, 0xffff0000
	v_add_u32_e32 v146, s74, v228
	ds_read_b64 v[22:23], v146 offset:49152
	ds_read_b64 v[26:27], v146 offset:53248
	ds_read_b64 v[30:31], v146 offset:57344
	ds_read_b64 v[34:35], v146 offset:61440
	s_waitcnt lgkmcnt(8)
	v_mfma_f32_16x16x32_bf16 v[80:83], v[4:7], v[60:63], v[80:83]
	v_mfma_f32_16x16x32_bf16 v[84:87], v[8:11], v[60:63], v[84:87]
	v_mfma_f32_16x16x32_bf16 v[88:91], v[12:15], v[60:63], v[88:91]
	v_mfma_f32_16x16x32_bf16 v[92:95], v[16:19], v[60:63], v[92:95]
	s_cmp_gt_u32 s6, 8
	s_cselect_b32 s74, 0, 0xffff0000
	v_add_u32_e32 v146, s74, v229
	ds_read_b64 v[4:5], v146 offset:49152
	ds_read_b64 v[8:9], v146 offset:53248
	ds_read_b64 v[12:13], v146 offset:57344
	ds_read_b64 v[16:17], v146 offset:61440
	v_mov_b32_e32 v6, 0
	v_mov_b32_e32 v7, 0
	v_mov_b32_e32 v10, 0
	v_mov_b32_e32 v11, 0
	v_mov_b32_e32 v14, 0
	v_mov_b32_e32 v15, 0
	v_mov_b32_e32 v18, 0
	v_mov_b32_e32 v19, 0
	s_waitcnt lgkmcnt(4)
	v_mfma_f32_16x16x32_bf16 v[80:83], v[20:23], v[68:71], v[80:83]
	v_mfma_f32_16x16x32_bf16 v[84:87], v[24:27], v[68:71], v[84:87]
	v_mfma_f32_16x16x32_bf16 v[88:91], v[28:31], v[68:71], v[88:91]
	v_mfma_f32_16x16x32_bf16 v[92:95], v[32:35], v[68:71], v[92:95]
	s_waitcnt lgkmcnt(0)
	v_mfma_f32_16x16x32_bf16 v[80:83], v[4:7], v[76:79], v[80:83]
	v_mfma_f32_16x16x32_bf16 v[84:87], v[8:11], v[76:79], v[84:87]
	v_mfma_f32_16x16x32_bf16 v[88:91], v[12:15], v[76:79], v[88:91]
	v_mfma_f32_16x16x32_bf16 v[92:95], v[16:19], v[76:79], v[92:95]
	v_mov_b32_e32 v148, v246
	s_nop 1
	v_permlane16_swap_b32 v246, v148
	v_add_f32_e32 v246, v246, v148
	v_mov_b32_e32 v148, v246
	s_nop 1
	v_permlane32_swap_b32 v246, v148
	v_add_f32_e32 v246, v246, v148
	v_rcp_f32_e32 v149, v246
	v_log_f32_e32 v150, v246
	s_nop 0
	v_add_f32_e32 v151, v245, v150
	v_mul_f32_e32 v151, 0x3f317218, v151
	v_max_f32_e32 v152, v120, v151
	v_sub_f32_e32 v153, v120, v152
	v_sub_f32_e32 v154, v151, v152
	v_mul_f32_e32 v153, 0x3fb8aa3b, v153
	v_mul_f32_e32 v154, 0x3fb8aa3b, v154
	v_exp_f32_e32 v153, v153
	v_exp_f32_e32 v154, v154
	s_nop 0
	v_add_f32_e32 v155, v153, v154
	v_rcp_f32_e32 v146, v155
	v_log_f32_e32 v150, v155
	s_nop 0
	v_mul_f32_e32 v154, v154, v146
	v_mul_f32_e32 v146, v153, v146
	v_mul_f32_e32 v147, v149, v154
	v_mul_f32_e32 v150, 0x3f317218, v150
	v_add_f32_e32 v140, v152, v150
	v_mul_f32_e32 v80, v80, v147
	v_mul_f32_e32 v81, v81, v147
	v_mul_f32_e32 v82, v82, v147
	v_mul_f32_e32 v83, v83, v147
	v_mul_f32_e32 v84, v84, v147
	v_mul_f32_e32 v85, v85, v147
	v_mul_f32_e32 v86, v86, v147
	v_mul_f32_e32 v87, v87, v147
	v_mul_f32_e32 v88, v88, v147
	v_mul_f32_e32 v89, v89, v147
	v_mul_f32_e32 v90, v90, v147
	v_mul_f32_e32 v91, v91, v147
	v_mul_f32_e32 v92, v92, v147
	v_mul_f32_e32 v93, v93, v147
	v_mul_f32_e32 v94, v94, v147
	v_mul_f32_e32 v95, v95, v147
	v_lshlrev_b32_e32 v141, 16, v112
	v_and_b32_e32 v142, 0xffff0000, v112
	v_lshlrev_b32_e32 v143, 16, v113
	v_and_b32_e32 v144, 0xffff0000, v113
	v_fmac_f32_e32 v80, v146, v141
	v_fmac_f32_e32 v81, v146, v142
	v_fmac_f32_e32 v82, v146, v143
	v_fmac_f32_e32 v83, v146, v144
	v_cvt_pk_bf16_f32 v132, v80, v81
	v_cvt_pk_bf16_f32 v133, v82, v83
	v_lshlrev_b32_e32 v141, 16, v114
	v_and_b32_e32 v142, 0xffff0000, v114
	v_lshlrev_b32_e32 v143, 16, v115
	v_and_b32_e32 v144, 0xffff0000, v115
	v_fmac_f32_e32 v84, v146, v141
	v_fmac_f32_e32 v85, v146, v142
	v_fmac_f32_e32 v86, v146, v143
	v_fmac_f32_e32 v87, v146, v144
	v_cvt_pk_bf16_f32 v134, v84, v85
	v_cvt_pk_bf16_f32 v135, v86, v87
	v_lshlrev_b32_e32 v141, 16, v116
	v_and_b32_e32 v142, 0xffff0000, v116
	v_lshlrev_b32_e32 v143, 16, v117
	v_and_b32_e32 v144, 0xffff0000, v117
	v_fmac_f32_e32 v88, v146, v141
	v_fmac_f32_e32 v89, v146, v142
	v_fmac_f32_e32 v90, v146, v143
	v_fmac_f32_e32 v91, v146, v144
	v_cvt_pk_bf16_f32 v136, v88, v89
	v_cvt_pk_bf16_f32 v137, v90, v91
	v_lshlrev_b32_e32 v141, 16, v118
	v_and_b32_e32 v142, 0xffff0000, v118
	v_lshlrev_b32_e32 v143, 16, v119
	v_and_b32_e32 v144, 0xffff0000, v119
	v_fmac_f32_e32 v92, v146, v141
	v_fmac_f32_e32 v93, v146, v142
	v_fmac_f32_e32 v94, v146, v143
	v_fmac_f32_e32 v95, v146, v144
	v_cvt_pk_bf16_f32 v138, v92, v93
	v_cvt_pk_bf16_f32 v139, v94, v95
	s_mov_b64 s[26:27], s[86:87]
	s_mov_b64 s[28:29], s[88:89]
	s_mov_b64 s[86:87], s[12:13]
	s_mov_b64 s[88:89], s[14:15]
	s_mov_b32 s4, s83
	s_mov_b32 s5, s84
	s_waitcnt vmcnt(0)
	s_barrier
	ds_read_b128 v[4:7], v230 offset:0
	ds_read_b128 v[8:11], v231 offset:0
	ds_read_b128 v[12:15], v230 offset:2048
	ds_read_b128 v[16:19], v231 offset:2048
	ds_read_b128 v[20:23], v230 offset:4096
	ds_read_b128 v[24:27], v231 offset:4096
	ds_read_b128 v[28:31], v230 offset:6144
	ds_read_b128 v[32:35], v231 offset:6144
	ds_read_b128 v[36:39], v230 offset:8192
	ds_read_b128 v[40:43], v231 offset:8192
	global_store_dwordx2 v237, v[132:133], s[26:27]
	global_store_dwordx2 v237, v[134:135], s[26:27] offset:32
	global_store_dwordx2 v237, v[136:137], s[26:27] offset:64
	global_store_dwordx2 v237, v[138:139], s[26:27] offset:96
	s_mov_b64 s[90:91], exec
	s_mov_b64 exec, 0xffff
	global_store_dword v238, v140, s[28:29]
	s_mov_b64 exec, s[90:91]
	s_add_u32 s84, s5, s4
	s_xor_b32 s83, s4, 1
	s_mul_i32 s74, s84, 256
	s_lshl_b32 s75, s83, 7
	s_add_u32 s74, s74, s75
	s_lshl_b32 s75, s74, 7
	s_add_u32 s16, s60, s75
	s_addc_u32 s17, s61, 0
	s_lshl_b32 s75, s74, 1
	s_add_u32 s24, s64, s75
	s_addc_u32 s25, s65, 0
	s_add_u32 m0, s70, 0x8000
	s_nop 0
	global_load_lds_dwordx4 v232, s[16:17] nt
	s_add_u32 m0, s70, 0xa000
	s_nop 0
	global_load_lds_dwordx4 v233, s[16:17] nt
	s_add_u32 m0, s70, 0x18000
	s_nop 0
	global_load_lds_dwordx4 v234, s[24:25] nt
	s_add_u32 m0, s70, 0x1a000
	s_nop 0
	global_load_lds_dwordx4 v235, s[24:25] nt
	s_lshl_b32 s74, s83, 11
	s_add_u32 s74, s74, s84
	s_lshl_b32 s75, s74, 7
	s_add_u32 s10, s30, s75
	s_addc_u32 s11, s31, 0
	s_add_u32 s12, s34, s75
	s_addc_u32 s13, s35, 0
	s_lshl_b32 s75, s74, 2
	s_add_u32 s14, s58, s75
	s_addc_u32 s15, s59, 0
	global_load_dwordx4 v[96:99], v236, s[10:11]
	global_load_dwordx4 v[100:103], v236, s[10:11] offset:64
	global_load_dwordx2 v[112:113], v237, s[12:13]
	global_load_dwordx2 v[114:115], v237, s[12:13] offset:32
	global_load_dwordx2 v[116:117], v237, s[12:13] offset:64
	global_load_dwordx2 v[118:119], v237, s[12:13] offset:96
	global_load_dword v120, v238, s[14:15]
	s_waitcnt lgkmcnt(0)
	v_mfma_f32_16x16x32_bf16 v[44:47], v[4:7], v[104:107], 0
	v_mfma_f32_16x16x32_bf16 v[48:51], v[12:15], v[104:107], 0
	v_mfma_f32_16x16x32_bf16 v[52:55], v[20:23], v[104:107], 0
	v_mfma_f32_16x16x32_bf16 v[56:59], v[28:31], v[104:107], 0
	v_mfma_f32_16x16x32_bf16 v[60:63], v[36:39], v[104:107], 0
	v_mfma_f32_16x16x32_bf16 v[44:47], v[8:11], v[108:111], v[44:47]
	v_mfma_f32_16x16x32_bf16 v[48:51], v[16:19], v[108:111], v[48:51]
	v_mfma_f32_16x16x32_bf16 v[52:55], v[24:27], v[108:111], v[52:55]
	v_mfma_f32_16x16x32_bf16 v[56:59], v[32:35], v[108:111], v[56:59]
	v_mfma_f32_16x16x32_bf16 v[60:63], v[40:43], v[108:111], v[60:63]
	ds_read_b128 v[4:7], v230 offset:10240
	ds_read_b128 v[8:11], v231 offset:10240
	ds_read_b128 v[12:15], v230 offset:12288
	ds_read_b128 v[16:19], v231 offset:12288
	ds_read_b128 v[20:23], v230 offset:14336
	ds_read_b128 v[24:27], v231 offset:14336
	ds_read_b128 v[28:31], v230 offset:16384
	ds_read_b128 v[32:35], v231 offset:16384
	s_nop 1
	v_fma_f32 v44, v44, s79, v185
	v_fma_f32 v45, v45, s79, v186
	v_fma_f32 v46, v46, s79, v187
	v_fma_f32 v47, v47, s79, v188
	v_fma_f32 v48, v48, s79, v189
	v_fma_f32 v49, v49, s79, v190
	v_fma_f32 v50, v50, s79, v191
	v_fma_f32 v51, v51, s79, v192
	v_fma_f32 v52, v52, s79, v193
	v_fma_f32 v53, v53, s79, v194
	v_fma_f32 v54, v54, s79, v195
	v_fma_f32 v55, v55, s79, v196
	v_fma_f32 v56, v56, s79, v197
	v_fma_f32 v57, v57, s79, v198
	v_fma_f32 v58, v58, s79, v199
	v_fma_f32 v59, v59, s79, v200
	v_fma_f32 v60, v60, s79, v201
	v_fma_f32 v61, v61, s79, v202
	v_fma_f32 v62, v62, s79, v203
	v_fma_f32 v63, v63, s79, v204
	s_waitcnt lgkmcnt(0)
	v_mfma_f32_16x16x32_bf16 v[64:67], v[4:7], v[104:107], 0
	v_mfma_f32_16x16x32_bf16 v[68:71], v[12:15], v[104:107], 0
	v_mfma_f32_16x16x32_bf16 v[72:75], v[20:23], v[104:107], 0
	v_mfma_f32_16x16x32_bf16 v[76:79], v[28:31], v[104:107], 0
	v_mfma_f32_16x16x32_bf16 v[64:67], v[8:11], v[108:111], v[64:67]
	v_mfma_f32_16x16x32_bf16 v[68:71], v[16:19], v[108:111], v[68:71]
	v_mfma_f32_16x16x32_bf16 v[72:75], v[24:27], v[108:111], v[72:75]
	v_mfma_f32_16x16x32_bf16 v[76:79], v[32:35], v[108:111], v[76:79]
	ds_read_b64 v[4:5], v221 offset:0
	ds_read_b64 v[8:9], v221 offset:4096
	ds_read_b64 v[12:13], v221 offset:8192
	ds_read_b64 v[16:17], v221 offset:12288
	ds_read_b64 v[6:7], v222 offset:0
	ds_read_b64 v[10:11], v222 offset:4096
	ds_read_b64 v[14:15], v222 offset:8192
	ds_read_b64 v[18:19], v222 offset:12288
	s_nop 1
	v_fma_f32 v64, v64, s79, v205
	v_fma_f32 v65, v65, s79, v206
	v_fma_f32 v66, v66, s79, v207
	v_fma_f32 v67, v67, s79, v208
	v_fma_f32 v68, v68, s79, v209
	v_fma_f32 v69, v69, s79, v210
	v_fma_f32 v70, v70, s79, v211
	v_fma_f32 v71, v71, s79, v212
	v_fma_f32 v72, v72, s79, v213
	v_fma_f32 v73, v73, s79, v214
	v_fma_f32 v74, v74, s79, v215
	v_fma_f32 v75, v75, s79, v216
	v_fma_f32 v76, v76, s79, v217
	v_fma_f32 v77, v77, s79, v218
	v_fma_f32 v78, v78, s79, v219
	v_fma_f32 v79, v79, s79, v220
	ds_read_b64 v[20:21], v223 offset:0
	ds_read_b64 v[24:25], v223 offset:4096
	ds_read_b64 v[28:29], v223 offset:8192
	ds_read_b64 v[32:33], v223 offset:12288
	ds_read_b64 v[22:23], v224 offset:0
	ds_read_b64 v[26:27], v224 offset:4096
	ds_read_b64 v[30:31], v224 offset:8192
	ds_read_b64 v[34:35], v224 offset:12288
	s_cmp_lg_u32 s4, 0
	s_cbranch_scc1 .Lat991_i1_nomask
	s_cmp_le_u32 s6, 0
	s_cbranch_scc1 .Lat991_i1_nomask
	v_mov_b32_e32 v44, v244
	v_mov_b32_e32 v45, v244
	v_mov_b32_e32 v46, v244
	v_mov_b32_e32 v47, v244
	s_cmp_le_u32 s6, 1
	s_cbranch_scc1 .Lat991_i1_nomask
	v_mov_b32_e32 v48, v244
	v_mov_b32_e32 v49, v244
	v_mov_b32_e32 v50, v244
	v_mov_b32_e32 v51, v244
	s_cmp_le_u32 s6, 2
	s_cbranch_scc1 .Lat991_i1_nomask
	v_mov_b32_e32 v52, v244
	v_mov_b32_e32 v53, v244
	v_mov_b32_e32 v54, v244
	v_mov_b32_e32 v55, v244
	s_cmp_le_u32 s6, 3
	s_cbranch_scc1 .Lat991_i1_nomask
	v_mov_b32_e32 v56, v244
	v_mov_b32_e32 v57, v244
	v_mov_b32_e32 v58, v244
	v_mov_b32_e32 v59, v244
	s_cmp_le_u32 s6, 4
	s_cbranch_scc1 .Lat991_i1_nomask
	v_mov_b32_e32 v60, v244
	v_mov_b32_e32 v61, v244
	v_mov_b32_e32 v62, v244
	v_mov_b32_e32 v63, v244
	s_cmp_le_u32 s6, 5
	s_cbranch_scc1 .Lat991_i1_nomask
	v_mov_b32_e32 v64, v244
	v_mov_b32_e32 v65, v244
	v_mov_b32_e32 v66, v244
	v_mov_b32_e32 v67, v244
	s_cmp_le_u32 s6, 6
	s_cbranch_scc1 .Lat991_i1_nomask
	v_mov_b32_e32 v68, v244
	v_mov_b32_e32 v69, v244
	v_mov_b32_e32 v70, v244
	v_mov_b32_e32 v71, v244
	s_cmp_le_u32 s6, 7
	s_cbranch_scc1 .Lat991_i1_nomask
	v_mov_b32_e32 v72, v244
	v_mov_b32_e32 v73, v244
	v_mov_b32_e32 v74, v244
	v_mov_b32_e32 v75, v244
.Lat991_i1_nomask:
	v_max3_f32 v245, v44, v45, v46
	v_max3_f32 v245, v245, v47, v48
	v_max3_f32 v245, v245, v49, v50
	v_max3_f32 v245, v245, v51, v52
	v_max3_f32 v245, v245, v53, v54
	v_max3_f32 v245, v245, v55, v56
	v_max3_f32 v245, v245, v57, v58
	v_max3_f32 v245, v245, v59, v60
	v_max3_f32 v245, v245, v61, v62
	v_max3_f32 v245, v245, v63, v64
	v_max3_f32 v245, v245, v65, v66
	v_max3_f32 v245, v245, v67, v68
	v_max3_f32 v245, v245, v69, v70
	v_max3_f32 v245, v245, v71, v72
	v_max3_f32 v245, v245, v73, v74
	v_max3_f32 v245, v245, v75, v76
	v_max3_f32 v245, v245, v77, v78
	v_max_f32_e32 v245, v245, v79
	v_mov_b32_e32 v148, v245
	s_nop 1
	v_permlane16_swap_b32 v245, v148
	v_max_f32_e32 v245, v245, v148
	v_mov_b32_e32 v148, v245
	s_nop 1
	v_permlane32_swap_b32 v245, v148
	v_max_f32_e32 v245, v245, v148
	v_sub_f32_e32 v44, v44, v245
	v_sub_f32_e32 v45, v45, v245
	v_sub_f32_e32 v46, v46, v245
	v_sub_f32_e32 v47, v47, v245
	v_exp_f32_e32 v44, v44
	v_exp_f32_e32 v45, v45
	v_exp_f32_e32 v46, v46
	v_exp_f32_e32 v47, v47
	v_sub_f32_e32 v48, v48, v245
	v_sub_f32_e32 v49, v49, v245
	v_sub_f32_e32 v50, v50, v245
	v_sub_f32_e32 v51, v51, v245
	v_exp_f32_e32 v48, v48
	v_exp_f32_e32 v49, v49
	v_exp_f32_e32 v50, v50
	v_exp_f32_e32 v51, v51
	v_mov_b32_e32 v149, v44
	v_mov_b32_e32 v150, v45
	v_mov_b32_e32 v151, v46
	v_mov_b32_e32 v152, v47
	v_cvt_pk_bf16_f32 v44, v44, v45
	v_cvt_pk_bf16_f32 v45, v46, v47
	v_sub_f32_e32 v52, v52, v245
	v_sub_f32_e32 v53, v53, v245
	v_sub_f32_e32 v54, v54, v245
	v_sub_f32_e32 v55, v55, v245
	v_exp_f32_e32 v52, v52
	v_exp_f32_e32 v53, v53
	v_exp_f32_e32 v54, v54
	v_exp_f32_e32 v55, v55
	v_add_f32_e32 v149, v149, v48
	v_add_f32_e32 v150, v150, v49
	v_add_f32_e32 v151, v151, v50
	v_add_f32_e32 v152, v152, v51
	v_cvt_pk_bf16_f32 v46, v48, v49
	v_cvt_pk_bf16_f32 v47, v50, v51
	v_sub_f32_e32 v56, v56, v245
	v_sub_f32_e32 v57, v57, v245
	v_sub_f32_e32 v58, v58, v245
	v_sub_f32_e32 v59, v59, v245
	v_exp_f32_e32 v56, v56
	v_exp_f32_e32 v57, v57
	v_exp_f32_e32 v58, v58
	v_exp_f32_e32 v59, v59
	v_add_f32_e32 v149, v149, v52
	v_add_f32_e32 v150, v150, v53
	v_add_f32_e32 v151, v151, v54
	v_add_f32_e32 v152, v152, v55
	v_cvt_pk_bf16_f32 v52, v52, v53
	v_cvt_pk_bf16_f32 v53, v54, v55
	v_sub_f32_e32 v60, v60, v245
	v_sub_f32_e32 v61, v61, v245
	v_sub_f32_e32 v62, v62, v245
	v_sub_f32_e32 v63, v63, v245
	v_exp_f32_e32 v60, v60
	v_exp_f32_e32 v61, v61
	v_exp_f32_e32 v62, v62
	v_exp_f32_e32 v63, v63
	v_add_f32_e32 v149, v149, v56
	v_add_f32_e32 v150, v150, v57
	v_add_f32_e32 v151, v151, v58
	v_add_f32_e32 v152, v152, v59
	v_cvt_pk_bf16_f32 v54, v56, v57
	v_cvt_pk_bf16_f32 v55, v58, v59
	v_sub_f32_e32 v64, v64, v245
	v_sub_f32_e32 v65, v65, v245
	v_sub_f32_e32 v66, v66, v245
	v_sub_f32_e32 v67, v67, v245
	v_exp_f32_e32 v64, v64
	v_exp_f32_e32 v65, v65
	v_exp_f32_e32 v66, v66
	v_exp_f32_e32 v67, v67
	v_add_f32_e32 v149, v149, v60
	v_add_f32_e32 v150, v150, v61
	v_add_f32_e32 v151, v151, v62
	v_add_f32_e32 v152, v152, v63
	v_cvt_pk_bf16_f32 v60, v60, v61
	v_cvt_pk_bf16_f32 v61, v62, v63
	v_sub_f32_e32 v68, v68, v245
	v_sub_f32_e32 v69, v69, v245
	v_sub_f32_e32 v70, v70, v245
	v_sub_f32_e32 v71, v71, v245
	v_exp_f32_e32 v68, v68
	v_exp_f32_e32 v69, v69
	v_exp_f32_e32 v70, v70
	v_exp_f32_e32 v71, v71
	v_add_f32_e32 v149, v149, v64
	v_add_f32_e32 v150, v150, v65
	v_add_f32_e32 v151, v151, v66
	v_add_f32_e32 v152, v152, v67
	v_cvt_pk_bf16_f32 v62, v64, v65
	v_cvt_pk_bf16_f32 v63, v66, v67
	v_sub_f32_e32 v72, v72, v245
	v_sub_f32_e32 v73, v73, v245
	v_sub_f32_e32 v74, v74, v245
	v_sub_f32_e32 v75, v75, v245
	v_exp_f32_e32 v72, v72
	v_exp_f32_e32 v73, v73
	v_exp_f32_e32 v74, v74
	v_exp_f32_e32 v75, v75
	v_add_f32_e32 v149, v149, v68
	v_add_f32_e32 v150, v150, v69
	v_add_f32_e32 v151, v151, v70
	v_add_f32_e32 v152, v152, v71
	v_cvt_pk_bf16_f32 v68, v68, v69
	v_cvt_pk_bf16_f32 v69, v70, v71
	v_sub_f32_e32 v76, v76, v245
	v_sub_f32_e32 v77, v77, v245
	v_sub_f32_e32 v78, v78, v245
	v_sub_f32_e32 v79, v79, v245
	v_exp_f32_e32 v76, v76
	v_exp_f32_e32 v77, v77
	v_exp_f32_e32 v78, v78
	v_exp_f32_e32 v79, v79
	v_add_f32_e32 v149, v149, v72
	v_add_f32_e32 v150, v150, v73
	v_add_f32_e32 v151, v151, v74
	v_add_f32_e32 v152, v152, v75
	v_cvt_pk_bf16_f32 v70, v72, v73
	v_cvt_pk_bf16_f32 v71, v74, v75
	s_nop 0
	v_add_f32_e32 v149, v149, v76
	v_add_f32_e32 v150, v150, v77
	v_add_f32_e32 v151, v151, v78
	v_add_f32_e32 v152, v152, v79
	v_cvt_pk_bf16_f32 v76, v76, v77
	v_cvt_pk_bf16_f32 v77, v78, v79
	v_mov_b32_e32 v78, 0
	v_mov_b32_e32 v79, 0
	v_add_f32_e32 v149, v149, v150
	v_add_f32_e32 v151, v151, v152
	v_add_f32_e32 v246, v149, v151
	s_waitcnt lgkmcnt(0)
	v_mfma_f32_16x16x32_bf16 v[80:83], v[4:7], v[44:47], 0
	v_mfma_f32_16x16x32_bf16 v[84:87], v[8:11], v[44:47], 0
	v_mfma_f32_16x16x32_bf16 v[88:91], v[12:15], v[44:47], 0
	v_mfma_f32_16x16x32_bf16 v[92:95], v[16:19], v[44:47], 0
	ds_read_b64 v[4:5], v225 offset:0
	ds_read_b64 v[8:9], v225 offset:4096
	ds_read_b64 v[12:13], v225 offset:8192
	ds_read_b64 v[16:17], v225 offset:12288
	ds_read_b64 v[6:7], v226 offset:0
	ds_read_b64 v[10:11], v226 offset:4096
	ds_read_b64 v[14:15], v226 offset:8192
	ds_read_b64 v[18:19], v226 offset:12288
	v_mfma_f32_16x16x32_bf16 v[80:83], v[20:23], v[52:55], v[80:83]
	v_mfma_f32_16x16x32_bf16 v[84:87], v[24:27], v[52:55], v[84:87]
	v_mfma_f32_16x16x32_bf16 v[88:91], v[28:31], v[52:55], v[88:91]
	v_mfma_f32_16x16x32_bf16 v[92:95], v[32:35], v[52:55], v[92:95]
	ds_read_b64 v[20:21], v227 offset:0
	ds_read_b64 v[24:25], v227 offset:4096
	ds_read_b64 v[28:29], v227 offset:8192
	ds_read_b64 v[32:33], v227 offset:12288
	ds_read_b64 v[22:23], v228 offset:0
	ds_read_b64 v[26:27], v228 offset:4096
	ds_read_b64 v[30:31], v228 offset:8192
	ds_read_b64 v[34:35], v228 offset:12288
	s_waitcnt lgkmcnt(8)
	v_mfma_f32_16x16x32_bf16 v[80:83], v[4:7], v[60:63], v[80:83]
	v_mfma_f32_16x16x32_bf16 v[84:87], v[8:11], v[60:63], v[84:87]
	v_mfma_f32_16x16x32_bf16 v[88:91], v[12:15], v[60:63], v[88:91]
	v_mfma_f32_16x16x32_bf16 v[92:95], v[16:19], v[60:63], v[92:95]
	ds_read_b64 v[4:5], v229 offset:0
	ds_read_b64 v[8:9], v229 offset:4096
	ds_read_b64 v[12:13], v229 offset:8192
	ds_read_b64 v[16:17], v229 offset:12288
	v_mov_b32_e32 v6, 0
	v_mov_b32_e32 v7, 0
	v_mov_b32_e32 v10, 0
	v_mov_b32_e32 v11, 0
	v_mov_b32_e32 v14, 0
	v_mov_b32_e32 v15, 0
	v_mov_b32_e32 v18, 0
	v_mov_b32_e32 v19, 0
	s_waitcnt lgkmcnt(4)
	v_mfma_f32_16x16x32_bf16 v[80:83], v[20:23], v[68:71], v[80:83]
	v_mfma_f32_16x16x32_bf16 v[84:87], v[24:27], v[68:71], v[84:87]
	v_mfma_f32_16x16x32_bf16 v[88:91], v[28:31], v[68:71], v[88:91]
	v_mfma_f32_16x16x32_bf16 v[92:95], v[32:35], v[68:71], v[92:95]
	s_waitcnt lgkmcnt(0)
	v_mfma_f32_16x16x32_bf16 v[80:83], v[4:7], v[76:79], v[80:83]
	v_mfma_f32_16x16x32_bf16 v[84:87], v[8:11], v[76:79], v[84:87]
	v_mfma_f32_16x16x32_bf16 v[88:91], v[12:15], v[76:79], v[88:91]
	v_mfma_f32_16x16x32_bf16 v[92:95], v[16:19], v[76:79], v[92:95]
	v_mov_b32_e32 v148, v246
	s_nop 1
	v_permlane16_swap_b32 v246, v148
	v_add_f32_e32 v246, v246, v148
	v_mov_b32_e32 v148, v246
	s_nop 1
	v_permlane32_swap_b32 v246, v148
	v_add_f32_e32 v246, v246, v148
	v_rcp_f32_e32 v149, v246
	v_log_f32_e32 v150, v246
	s_nop 0
	v_add_f32_e32 v151, v245, v150
	v_mul_f32_e32 v151, 0x3f317218, v151
	v_max_f32_e32 v152, v121, v151
	v_sub_f32_e32 v153, v121, v152
	v_sub_f32_e32 v154, v151, v152
	v_mul_f32_e32 v153, 0x3fb8aa3b, v153
	v_mul_f32_e32 v154, 0x3fb8aa3b, v154
	v_exp_f32_e32 v153, v153
	v_exp_f32_e32 v154, v154
	s_nop 0
	v_add_f32_e32 v155, v153, v154
	v_rcp_f32_e32 v146, v155
	v_log_f32_e32 v150, v155
	s_nop 0
	v_mul_f32_e32 v154, v154, v146
	v_mul_f32_e32 v146, v153, v146
	v_mul_f32_e32 v147, v149, v154
	v_mul_f32_e32 v150, 0x3f317218, v150
	v_add_f32_e32 v140, v152, v150
	v_mul_f32_e32 v80, v80, v147
	v_mul_f32_e32 v81, v81, v147
	v_mul_f32_e32 v82, v82, v147
	v_mul_f32_e32 v83, v83, v147
	v_mul_f32_e32 v84, v84, v147
	v_mul_f32_e32 v85, v85, v147
	v_mul_f32_e32 v86, v86, v147
	v_mul_f32_e32 v87, v87, v147
	v_mul_f32_e32 v88, v88, v147
	v_mul_f32_e32 v89, v89, v147
	v_mul_f32_e32 v90, v90, v147
	v_mul_f32_e32 v91, v91, v147
	v_mul_f32_e32 v92, v92, v147
	v_mul_f32_e32 v93, v93, v147
	v_mul_f32_e32 v94, v94, v147
	v_mul_f32_e32 v95, v95, v147
	v_lshlrev_b32_e32 v141, 16, v122
	v_and_b32_e32 v142, 0xffff0000, v122
	v_lshlrev_b32_e32 v143, 16, v123
	v_and_b32_e32 v144, 0xffff0000, v123
	v_fmac_f32_e32 v80, v146, v141
	v_fmac_f32_e32 v81, v146, v142
	v_fmac_f32_e32 v82, v146, v143
	v_fmac_f32_e32 v83, v146, v144
	v_cvt_pk_bf16_f32 v132, v80, v81
	v_cvt_pk_bf16_f32 v133, v82, v83
	v_lshlrev_b32_e32 v141, 16, v124
	v_and_b32_e32 v142, 0xffff0000, v124
	v_lshlrev_b32_e32 v143, 16, v125
	v_and_b32_e32 v144, 0xffff0000, v125
	v_fmac_f32_e32 v84, v146, v141
	v_fmac_f32_e32 v85, v146, v142
	v_fmac_f32_e32 v86, v146, v143
	v_fmac_f32_e32 v87, v146, v144
	v_cvt_pk_bf16_f32 v134, v84, v85
	v_cvt_pk_bf16_f32 v135, v86, v87
	v_lshlrev_b32_e32 v141, 16, v126
	v_and_b32_e32 v142, 0xffff0000, v126
	v_lshlrev_b32_e32 v143, 16, v127
	v_and_b32_e32 v144, 0xffff0000, v127
	v_fmac_f32_e32 v88, v146, v141
	v_fmac_f32_e32 v89, v146, v142
	v_fmac_f32_e32 v90, v146, v143
	v_fmac_f32_e32 v91, v146, v144
	v_cvt_pk_bf16_f32 v136, v88, v89
	v_cvt_pk_bf16_f32 v137, v90, v91
	v_lshlrev_b32_e32 v141, 16, v128
	v_and_b32_e32 v142, 0xffff0000, v128
	v_lshlrev_b32_e32 v143, 16, v129
	v_and_b32_e32 v144, 0xffff0000, v129
	v_fmac_f32_e32 v92, v146, v141
	v_fmac_f32_e32 v93, v146, v142
	v_fmac_f32_e32 v94, v146, v143
	v_fmac_f32_e32 v95, v146, v144
	v_cvt_pk_bf16_f32 v138, v92, v93
	v_cvt_pk_bf16_f32 v139, v94, v95
	s_mov_b64 s[26:27], s[86:87]
	s_mov_b64 s[28:29], s[88:89]
	s_mov_b64 s[86:87], s[12:13]
	s_mov_b64 s[88:89], s[14:15]
	s_mov_b32 s4, s83
	s_mov_b32 s5, s84
	s_waitcnt vmcnt(0)
	s_barrier
	ds_read_b128 v[4:7], v230 offset:16384
	ds_read_b128 v[8:11], v231 offset:16384
	ds_read_b128 v[12:15], v230 offset:18432
	ds_read_b128 v[16:19], v231 offset:18432
	ds_read_b128 v[20:23], v230 offset:20480
	ds_read_b128 v[24:27], v231 offset:20480
	ds_read_b128 v[28:31], v230 offset:22528
	ds_read_b128 v[32:35], v231 offset:22528
	ds_read_b128 v[36:39], v230 offset:24576
	ds_read_b128 v[40:43], v231 offset:24576
	global_store_dwordx2 v237, v[132:133], s[26:27]
	global_store_dwordx2 v237, v[134:135], s[26:27] offset:32
	global_store_dwordx2 v237, v[136:137], s[26:27] offset:64
	global_store_dwordx2 v237, v[138:139], s[26:27] offset:96
	s_mov_b64 s[90:91], exec
	s_mov_b64 exec, 0xffff
	global_store_dword v238, v140, s[28:29]
	s_mov_b64 exec, s[90:91]
	s_add_u32 s84, s5, s4
	s_xor_b32 s83, s4, 1
	s_mul_i32 s74, s84, 256
	s_lshl_b32 s75, s83, 7
	s_add_u32 s74, s74, s75
	s_lshl_b32 s75, s74, 7
	s_add_u32 s16, s60, s75
	s_addc_u32 s17, s61, 0
	s_lshl_b32 s75, s74, 1
	s_add_u32 s24, s64, s75
	s_addc_u32 s25, s65, 0
	s_add_u32 m0, s70, 0xc000
	s_nop 0
	global_load_lds_dwordx4 v232, s[16:17] nt
	s_add_u32 m0, s70, 0xe000
	s_nop 0
	global_load_lds_dwordx4 v233, s[16:17] nt
	s_add_u32 m0, s70, 0x1c000
	s_nop 0
	global_load_lds_dwordx4 v234, s[24:25] nt
	s_add_u32 m0, s70, 0x1e000
	s_nop 0
	global_load_lds_dwordx4 v235, s[24:25] nt
	s_lshl_b32 s74, s83, 11
	s_add_u32 s74, s74, s84
	s_lshl_b32 s75, s74, 7
	s_add_u32 s10, s30, s75
	s_addc_u32 s11, s31, 0
	s_add_u32 s12, s34, s75
	s_addc_u32 s13, s35, 0
	s_lshl_b32 s75, s74, 2
	s_add_u32 s14, s58, s75
	s_addc_u32 s15, s59, 0
	global_load_dwordx4 v[104:107], v236, s[10:11]
	global_load_dwordx4 v[108:111], v236, s[10:11] offset:64
	global_load_dwordx2 v[122:123], v237, s[12:13]
	global_load_dwordx2 v[124:125], v237, s[12:13] offset:32
	global_load_dwordx2 v[126:127], v237, s[12:13] offset:64
	global_load_dwordx2 v[128:129], v237, s[12:13] offset:96
	global_load_dword v121, v238, s[14:15]
	s_waitcnt lgkmcnt(0)
	v_mfma_f32_16x16x32_bf16 v[44:47], v[4:7], v[96:99], 0
	v_mfma_f32_16x16x32_bf16 v[48:51], v[12:15], v[96:99], 0
	v_mfma_f32_16x16x32_bf16 v[52:55], v[20:23], v[96:99], 0
	v_mfma_f32_16x16x32_bf16 v[56:59], v[28:31], v[96:99], 0
	v_mfma_f32_16x16x32_bf16 v[60:63], v[36:39], v[96:99], 0
	v_mfma_f32_16x16x32_bf16 v[44:47], v[8:11], v[100:103], v[44:47]
	v_mfma_f32_16x16x32_bf16 v[48:51], v[16:19], v[100:103], v[48:51]
	v_mfma_f32_16x16x32_bf16 v[52:55], v[24:27], v[100:103], v[52:55]
	v_mfma_f32_16x16x32_bf16 v[56:59], v[32:35], v[100:103], v[56:59]
	v_mfma_f32_16x16x32_bf16 v[60:63], v[40:43], v[100:103], v[60:63]
	ds_read_b128 v[4:7], v230 offset:26624
	ds_read_b128 v[8:11], v231 offset:26624
	ds_read_b128 v[12:15], v230 offset:28672
	ds_read_b128 v[16:19], v231 offset:28672
	ds_read_b128 v[20:23], v230 offset:30720
	ds_read_b128 v[24:27], v231 offset:30720
	ds_read_b128 v[28:31], v230 offset:32768
	ds_read_b128 v[32:35], v231 offset:32768
	s_nop 1
	v_fma_f32 v44, v44, s79, v185
	v_fma_f32 v45, v45, s79, v186
	v_fma_f32 v46, v46, s79, v187
	v_fma_f32 v47, v47, s79, v188
	v_fma_f32 v48, v48, s79, v189
	v_fma_f32 v49, v49, s79, v190
	v_fma_f32 v50, v50, s79, v191
	v_fma_f32 v51, v51, s79, v192
	v_fma_f32 v52, v52, s79, v193
	v_fma_f32 v53, v53, s79, v194
	v_fma_f32 v54, v54, s79, v195
	v_fma_f32 v55, v55, s79, v196
	v_fma_f32 v56, v56, s79, v197
	v_fma_f32 v57, v57, s79, v198
	v_fma_f32 v58, v58, s79, v199
	v_fma_f32 v59, v59, s79, v200
	v_fma_f32 v60, v60, s79, v201
	v_fma_f32 v61, v61, s79, v202
	v_fma_f32 v62, v62, s79, v203
	v_fma_f32 v63, v63, s79, v204
	s_waitcnt lgkmcnt(0)
	v_mfma_f32_16x16x32_bf16 v[64:67], v[4:7], v[96:99], 0
	v_mfma_f32_16x16x32_bf16 v[68:71], v[12:15], v[96:99], 0
	v_mfma_f32_16x16x32_bf16 v[72:75], v[20:23], v[96:99], 0
	v_mfma_f32_16x16x32_bf16 v[76:79], v[28:31], v[96:99], 0
	v_mfma_f32_16x16x32_bf16 v[64:67], v[8:11], v[100:103], v[64:67]
	v_mfma_f32_16x16x32_bf16 v[68:71], v[16:19], v[100:103], v[68:71]
	v_mfma_f32_16x16x32_bf16 v[72:75], v[24:27], v[100:103], v[72:75]
	v_mfma_f32_16x16x32_bf16 v[76:79], v[32:35], v[100:103], v[76:79]
	ds_read_b64 v[4:5], v221 offset:16384
	ds_read_b64 v[8:9], v221 offset:20480
	ds_read_b64 v[12:13], v221 offset:24576
	ds_read_b64 v[16:17], v221 offset:28672
	ds_read_b64 v[6:7], v222 offset:16384
	ds_read_b64 v[10:11], v222 offset:20480
	ds_read_b64 v[14:15], v222 offset:24576
	ds_read_b64 v[18:19], v222 offset:28672
	s_nop 1
	v_fma_f32 v64, v64, s79, v205
	v_fma_f32 v65, v65, s79, v206
	v_fma_f32 v66, v66, s79, v207
	v_fma_f32 v67, v67, s79, v208
	v_fma_f32 v68, v68, s79, v209
	v_fma_f32 v69, v69, s79, v210
	v_fma_f32 v70, v70, s79, v211
	v_fma_f32 v71, v71, s79, v212
	v_fma_f32 v72, v72, s79, v213
	v_fma_f32 v73, v73, s79, v214
	v_fma_f32 v74, v74, s79, v215
	v_fma_f32 v75, v75, s79, v216
	v_fma_f32 v76, v76, s79, v217
	v_fma_f32 v77, v77, s79, v218
	v_fma_f32 v78, v78, s79, v219
	v_fma_f32 v79, v79, s79, v220
	ds_read_b64 v[20:21], v223 offset:16384
	ds_read_b64 v[24:25], v223 offset:20480
	ds_read_b64 v[28:29], v223 offset:24576
	ds_read_b64 v[32:33], v223 offset:28672
	ds_read_b64 v[22:23], v224 offset:16384
	ds_read_b64 v[26:27], v224 offset:20480
	ds_read_b64 v[30:31], v224 offset:24576
	ds_read_b64 v[34:35], v224 offset:28672
	s_cmp_lg_u32 s4, 0
	s_cbranch_scc1 .Lat991_i2_nomask
	s_cmp_le_u32 s6, 0
	s_cbranch_scc1 .Lat991_i2_nomask
	v_mov_b32_e32 v44, v244
	v_mov_b32_e32 v45, v244
	v_mov_b32_e32 v46, v244
	v_mov_b32_e32 v47, v244
	s_cmp_le_u32 s6, 1
	s_cbranch_scc1 .Lat991_i2_nomask
	v_mov_b32_e32 v48, v244
	v_mov_b32_e32 v49, v244
	v_mov_b32_e32 v50, v244
	v_mov_b32_e32 v51, v244
	s_cmp_le_u32 s6, 2
	s_cbranch_scc1 .Lat991_i2_nomask
	v_mov_b32_e32 v52, v244
	v_mov_b32_e32 v53, v244
	v_mov_b32_e32 v54, v244
	v_mov_b32_e32 v55, v244
	s_cmp_le_u32 s6, 3
	s_cbranch_scc1 .Lat991_i2_nomask
	v_mov_b32_e32 v56, v244
	v_mov_b32_e32 v57, v244
	v_mov_b32_e32 v58, v244
	v_mov_b32_e32 v59, v244
	s_cmp_le_u32 s6, 4
	s_cbranch_scc1 .Lat991_i2_nomask
	v_mov_b32_e32 v60, v244
	v_mov_b32_e32 v61, v244
	v_mov_b32_e32 v62, v244
	v_mov_b32_e32 v63, v244
	s_cmp_le_u32 s6, 5
	s_cbranch_scc1 .Lat991_i2_nomask
	v_mov_b32_e32 v64, v244
	v_mov_b32_e32 v65, v244
	v_mov_b32_e32 v66, v244
	v_mov_b32_e32 v67, v244
	s_cmp_le_u32 s6, 6
	s_cbranch_scc1 .Lat991_i2_nomask
	v_mov_b32_e32 v68, v244
	v_mov_b32_e32 v69, v244
	v_mov_b32_e32 v70, v244
	v_mov_b32_e32 v71, v244
	s_cmp_le_u32 s6, 7
	s_cbranch_scc1 .Lat991_i2_nomask
	v_mov_b32_e32 v72, v244
	v_mov_b32_e32 v73, v244
	v_mov_b32_e32 v74, v244
	v_mov_b32_e32 v75, v244
.Lat991_i2_nomask:
	v_max3_f32 v245, v44, v45, v46
	v_max3_f32 v245, v245, v47, v48
	v_max3_f32 v245, v245, v49, v50
	v_max3_f32 v245, v245, v51, v52
	v_max3_f32 v245, v245, v53, v54
	v_max3_f32 v245, v245, v55, v56
	v_max3_f32 v245, v245, v57, v58
	v_max3_f32 v245, v245, v59, v60
	v_max3_f32 v245, v245, v61, v62
	v_max3_f32 v245, v245, v63, v64
	v_max3_f32 v245, v245, v65, v66
	v_max3_f32 v245, v245, v67, v68
	v_max3_f32 v245, v245, v69, v70
	v_max3_f32 v245, v245, v71, v72
	v_max3_f32 v245, v245, v73, v74
	v_max3_f32 v245, v245, v75, v76
	v_max3_f32 v245, v245, v77, v78
	v_max_f32_e32 v245, v245, v79
	v_mov_b32_e32 v148, v245
	s_nop 1
	v_permlane16_swap_b32 v245, v148
	v_max_f32_e32 v245, v245, v148
	v_mov_b32_e32 v148, v245
	s_nop 1
	v_permlane32_swap_b32 v245, v148
	v_max_f32_e32 v245, v245, v148
	v_sub_f32_e32 v44, v44, v245
	v_sub_f32_e32 v45, v45, v245
	v_sub_f32_e32 v46, v46, v245
	v_sub_f32_e32 v47, v47, v245
	v_exp_f32_e32 v44, v44
	v_exp_f32_e32 v45, v45
	v_exp_f32_e32 v46, v46
	v_exp_f32_e32 v47, v47
	v_sub_f32_e32 v48, v48, v245
	v_sub_f32_e32 v49, v49, v245
	v_sub_f32_e32 v50, v50, v245
	v_sub_f32_e32 v51, v51, v245
	v_exp_f32_e32 v48, v48
	v_exp_f32_e32 v49, v49
	v_exp_f32_e32 v50, v50
	v_exp_f32_e32 v51, v51
	v_mov_b32_e32 v149, v44
	v_mov_b32_e32 v150, v45
	v_mov_b32_e32 v151, v46
	v_mov_b32_e32 v152, v47
	v_cvt_pk_bf16_f32 v44, v44, v45
	v_cvt_pk_bf16_f32 v45, v46, v47
	v_sub_f32_e32 v52, v52, v245
	v_sub_f32_e32 v53, v53, v245
	v_sub_f32_e32 v54, v54, v245
	v_sub_f32_e32 v55, v55, v245
	v_exp_f32_e32 v52, v52
	v_exp_f32_e32 v53, v53
	v_exp_f32_e32 v54, v54
	v_exp_f32_e32 v55, v55
	v_add_f32_e32 v149, v149, v48
	v_add_f32_e32 v150, v150, v49
	v_add_f32_e32 v151, v151, v50
	v_add_f32_e32 v152, v152, v51
	v_cvt_pk_bf16_f32 v46, v48, v49
	v_cvt_pk_bf16_f32 v47, v50, v51
	v_sub_f32_e32 v56, v56, v245
	v_sub_f32_e32 v57, v57, v245
	v_sub_f32_e32 v58, v58, v245
	v_sub_f32_e32 v59, v59, v245
	v_exp_f32_e32 v56, v56
	v_exp_f32_e32 v57, v57
	v_exp_f32_e32 v58, v58
	v_exp_f32_e32 v59, v59
	v_add_f32_e32 v149, v149, v52
	v_add_f32_e32 v150, v150, v53
	v_add_f32_e32 v151, v151, v54
	v_add_f32_e32 v152, v152, v55
	v_cvt_pk_bf16_f32 v52, v52, v53
	v_cvt_pk_bf16_f32 v53, v54, v55
	v_sub_f32_e32 v60, v60, v245
	v_sub_f32_e32 v61, v61, v245
	v_sub_f32_e32 v62, v62, v245
	v_sub_f32_e32 v63, v63, v245
	v_exp_f32_e32 v60, v60
	v_exp_f32_e32 v61, v61
	v_exp_f32_e32 v62, v62
	v_exp_f32_e32 v63, v63
	v_add_f32_e32 v149, v149, v56
	v_add_f32_e32 v150, v150, v57
	v_add_f32_e32 v151, v151, v58
	v_add_f32_e32 v152, v152, v59
	v_cvt_pk_bf16_f32 v54, v56, v57
	v_cvt_pk_bf16_f32 v55, v58, v59
	v_sub_f32_e32 v64, v64, v245
	v_sub_f32_e32 v65, v65, v245
	v_sub_f32_e32 v66, v66, v245
	v_sub_f32_e32 v67, v67, v245
	v_exp_f32_e32 v64, v64
	v_exp_f32_e32 v65, v65
	v_exp_f32_e32 v66, v66
	v_exp_f32_e32 v67, v67
	v_add_f32_e32 v149, v149, v60
	v_add_f32_e32 v150, v150, v61
	v_add_f32_e32 v151, v151, v62
	v_add_f32_e32 v152, v152, v63
	v_cvt_pk_bf16_f32 v60, v60, v61
	v_cvt_pk_bf16_f32 v61, v62, v63
	v_sub_f32_e32 v68, v68, v245
	v_sub_f32_e32 v69, v69, v245
	v_sub_f32_e32 v70, v70, v245
	v_sub_f32_e32 v71, v71, v245
	v_exp_f32_e32 v68, v68
	v_exp_f32_e32 v69, v69
	v_exp_f32_e32 v70, v70
	v_exp_f32_e32 v71, v71
	v_add_f32_e32 v149, v149, v64
	v_add_f32_e32 v150, v150, v65
	v_add_f32_e32 v151, v151, v66
	v_add_f32_e32 v152, v152, v67
	v_cvt_pk_bf16_f32 v62, v64, v65
	v_cvt_pk_bf16_f32 v63, v66, v67
	v_sub_f32_e32 v72, v72, v245
	v_sub_f32_e32 v73, v73, v245
	v_sub_f32_e32 v74, v74, v245
	v_sub_f32_e32 v75, v75, v245
	v_exp_f32_e32 v72, v72
	v_exp_f32_e32 v73, v73
	v_exp_f32_e32 v74, v74
	v_exp_f32_e32 v75, v75
	v_add_f32_e32 v149, v149, v68
	v_add_f32_e32 v150, v150, v69
	v_add_f32_e32 v151, v151, v70
	v_add_f32_e32 v152, v152, v71
	v_cvt_pk_bf16_f32 v68, v68, v69
	v_cvt_pk_bf16_f32 v69, v70, v71
	v_sub_f32_e32 v76, v76, v245
	v_sub_f32_e32 v77, v77, v245
	v_sub_f32_e32 v78, v78, v245
	v_sub_f32_e32 v79, v79, v245
	v_exp_f32_e32 v76, v76
	v_exp_f32_e32 v77, v77
	v_exp_f32_e32 v78, v78
	v_exp_f32_e32 v79, v79
	v_add_f32_e32 v149, v149, v72
	v_add_f32_e32 v150, v150, v73
	v_add_f32_e32 v151, v151, v74
	v_add_f32_e32 v152, v152, v75
	v_cvt_pk_bf16_f32 v70, v72, v73
	v_cvt_pk_bf16_f32 v71, v74, v75
	s_nop 0
	v_add_f32_e32 v149, v149, v76
	v_add_f32_e32 v150, v150, v77
	v_add_f32_e32 v151, v151, v78
	v_add_f32_e32 v152, v152, v79
	v_cvt_pk_bf16_f32 v76, v76, v77
	v_cvt_pk_bf16_f32 v77, v78, v79
	v_mov_b32_e32 v78, 0
	v_mov_b32_e32 v79, 0
	v_add_f32_e32 v149, v149, v150
	v_add_f32_e32 v151, v151, v152
	v_add_f32_e32 v246, v149, v151
	s_waitcnt lgkmcnt(0)
	v_mfma_f32_16x16x32_bf16 v[80:83], v[4:7], v[44:47], 0
	v_mfma_f32_16x16x32_bf16 v[84:87], v[8:11], v[44:47], 0
	v_mfma_f32_16x16x32_bf16 v[88:91], v[12:15], v[44:47], 0
	v_mfma_f32_16x16x32_bf16 v[92:95], v[16:19], v[44:47], 0
	ds_read_b64 v[4:5], v225 offset:16384
	ds_read_b64 v[8:9], v225 offset:20480
	ds_read_b64 v[12:13], v225 offset:24576
	ds_read_b64 v[16:17], v225 offset:28672
	ds_read_b64 v[6:7], v226 offset:16384
	ds_read_b64 v[10:11], v226 offset:20480
	ds_read_b64 v[14:15], v226 offset:24576
	ds_read_b64 v[18:19], v226 offset:28672
	v_mfma_f32_16x16x32_bf16 v[80:83], v[20:23], v[52:55], v[80:83]
	v_mfma_f32_16x16x32_bf16 v[84:87], v[24:27], v[52:55], v[84:87]
	v_mfma_f32_16x16x32_bf16 v[88:91], v[28:31], v[52:55], v[88:91]
	v_mfma_f32_16x16x32_bf16 v[92:95], v[32:35], v[52:55], v[92:95]
	ds_read_b64 v[20:21], v227 offset:16384
	ds_read_b64 v[24:25], v227 offset:20480
	ds_read_b64 v[28:29], v227 offset:24576
	ds_read_b64 v[32:33], v227 offset:28672
	ds_read_b64 v[22:23], v228 offset:16384
	ds_read_b64 v[26:27], v228 offset:20480
	ds_read_b64 v[30:31], v228 offset:24576
	ds_read_b64 v[34:35], v228 offset:28672
	s_waitcnt lgkmcnt(8)
	v_mfma_f32_16x16x32_bf16 v[80:83], v[4:7], v[60:63], v[80:83]
	v_mfma_f32_16x16x32_bf16 v[84:87], v[8:11], v[60:63], v[84:87]
	v_mfma_f32_16x16x32_bf16 v[88:91], v[12:15], v[60:63], v[88:91]
	v_mfma_f32_16x16x32_bf16 v[92:95], v[16:19], v[60:63], v[92:95]
	ds_read_b64 v[4:5], v229 offset:16384
	ds_read_b64 v[8:9], v229 offset:20480
	ds_read_b64 v[12:13], v229 offset:24576
	ds_read_b64 v[16:17], v229 offset:28672
	v_mov_b32_e32 v6, 0
	v_mov_b32_e32 v7, 0
	v_mov_b32_e32 v10, 0
	v_mov_b32_e32 v11, 0
	v_mov_b32_e32 v14, 0
	v_mov_b32_e32 v15, 0
	v_mov_b32_e32 v18, 0
	v_mov_b32_e32 v19, 0
	s_waitcnt lgkmcnt(4)
	v_mfma_f32_16x16x32_bf16 v[80:83], v[20:23], v[68:71], v[80:83]
	v_mfma_f32_16x16x32_bf16 v[84:87], v[24:27], v[68:71], v[84:87]
	v_mfma_f32_16x16x32_bf16 v[88:91], v[28:31], v[68:71], v[88:91]
	v_mfma_f32_16x16x32_bf16 v[92:95], v[32:35], v[68:71], v[92:95]
	s_waitcnt lgkmcnt(0)
	v_mfma_f32_16x16x32_bf16 v[80:83], v[4:7], v[76:79], v[80:83]
	v_mfma_f32_16x16x32_bf16 v[84:87], v[8:11], v[76:79], v[84:87]
	v_mfma_f32_16x16x32_bf16 v[88:91], v[12:15], v[76:79], v[88:91]
	v_mfma_f32_16x16x32_bf16 v[92:95], v[16:19], v[76:79], v[92:95]
	v_mov_b32_e32 v148, v246
	s_nop 1
	v_permlane16_swap_b32 v246, v148
	v_add_f32_e32 v246, v246, v148
	v_mov_b32_e32 v148, v246
	s_nop 1
	v_permlane32_swap_b32 v246, v148
	v_add_f32_e32 v246, v246, v148
	v_rcp_f32_e32 v149, v246
	v_log_f32_e32 v150, v246
	s_nop 0
	v_add_f32_e32 v151, v245, v150
	v_mul_f32_e32 v151, 0x3f317218, v151
	v_max_f32_e32 v152, v120, v151
	v_sub_f32_e32 v153, v120, v152
	v_sub_f32_e32 v154, v151, v152
	v_mul_f32_e32 v153, 0x3fb8aa3b, v153
	v_mul_f32_e32 v154, 0x3fb8aa3b, v154
	v_exp_f32_e32 v153, v153
	v_exp_f32_e32 v154, v154
	s_nop 0
	v_add_f32_e32 v155, v153, v154
	v_rcp_f32_e32 v146, v155
	v_log_f32_e32 v150, v155
	s_nop 0
	v_mul_f32_e32 v154, v154, v146
	v_mul_f32_e32 v146, v153, v146
	v_mul_f32_e32 v147, v149, v154
	v_mul_f32_e32 v150, 0x3f317218, v150
	v_add_f32_e32 v140, v152, v150
	v_mul_f32_e32 v80, v80, v147
	v_mul_f32_e32 v81, v81, v147
	v_mul_f32_e32 v82, v82, v147
	v_mul_f32_e32 v83, v83, v147
	v_mul_f32_e32 v84, v84, v147
	v_mul_f32_e32 v85, v85, v147
	v_mul_f32_e32 v86, v86, v147
	v_mul_f32_e32 v87, v87, v147
	v_mul_f32_e32 v88, v88, v147
	v_mul_f32_e32 v89, v89, v147
	v_mul_f32_e32 v90, v90, v147
	v_mul_f32_e32 v91, v91, v147
	v_mul_f32_e32 v92, v92, v147
	v_mul_f32_e32 v93, v93, v147
	v_mul_f32_e32 v94, v94, v147
	v_mul_f32_e32 v95, v95, v147
	v_lshlrev_b32_e32 v141, 16, v112
	v_and_b32_e32 v142, 0xffff0000, v112
	v_lshlrev_b32_e32 v143, 16, v113
	v_and_b32_e32 v144, 0xffff0000, v113
	v_fmac_f32_e32 v80, v146, v141
	v_fmac_f32_e32 v81, v146, v142
	v_fmac_f32_e32 v82, v146, v143
	v_fmac_f32_e32 v83, v146, v144
	v_cvt_pk_bf16_f32 v132, v80, v81
	v_cvt_pk_bf16_f32 v133, v82, v83
	v_lshlrev_b32_e32 v141, 16, v114
	v_and_b32_e32 v142, 0xffff0000, v114
	v_lshlrev_b32_e32 v143, 16, v115
	v_and_b32_e32 v144, 0xffff0000, v115
	v_fmac_f32_e32 v84, v146, v141
	v_fmac_f32_e32 v85, v146, v142
	v_fmac_f32_e32 v86, v146, v143
	v_fmac_f32_e32 v87, v146, v144
	v_cvt_pk_bf16_f32 v134, v84, v85
	v_cvt_pk_bf16_f32 v135, v86, v87
	v_lshlrev_b32_e32 v141, 16, v116
	v_and_b32_e32 v142, 0xffff0000, v116
	v_lshlrev_b32_e32 v143, 16, v117
	v_and_b32_e32 v144, 0xffff0000, v117
	v_fmac_f32_e32 v88, v146, v141
	v_fmac_f32_e32 v89, v146, v142
	v_fmac_f32_e32 v90, v146, v143
	v_fmac_f32_e32 v91, v146, v144
	v_cvt_pk_bf16_f32 v136, v88, v89
	v_cvt_pk_bf16_f32 v137, v90, v91
	v_lshlrev_b32_e32 v141, 16, v118
	v_and_b32_e32 v142, 0xffff0000, v118
	v_lshlrev_b32_e32 v143, 16, v119
	v_and_b32_e32 v144, 0xffff0000, v119
	v_fmac_f32_e32 v92, v146, v141
	v_fmac_f32_e32 v93, v146, v142
	v_fmac_f32_e32 v94, v146, v143
	v_fmac_f32_e32 v95, v146, v144
	v_cvt_pk_bf16_f32 v138, v92, v93
	v_cvt_pk_bf16_f32 v139, v94, v95
	s_mov_b64 s[26:27], s[86:87]
	s_mov_b64 s[28:29], s[88:89]
	s_mov_b64 s[86:87], s[12:13]
	s_mov_b64 s[88:89], s[14:15]
	s_mov_b32 s4, s83
	s_mov_b32 s5, s84
	s_waitcnt vmcnt(0)
	s_barrier
	ds_read_b128 v[4:7], v230 offset:32768
	ds_read_b128 v[8:11], v231 offset:32768
	ds_read_b128 v[12:15], v230 offset:34816
	ds_read_b128 v[16:19], v231 offset:34816
	ds_read_b128 v[20:23], v230 offset:36864
	ds_read_b128 v[24:27], v231 offset:36864
	ds_read_b128 v[28:31], v230 offset:38912
	ds_read_b128 v[32:35], v231 offset:38912
	ds_read_b128 v[36:39], v230 offset:40960
	ds_read_b128 v[40:43], v231 offset:40960
	global_store_dwordx2 v237, v[132:133], s[26:27]
	global_store_dwordx2 v237, v[134:135], s[26:27] offset:32
	global_store_dwordx2 v237, v[136:137], s[26:27] offset:64
	global_store_dwordx2 v237, v[138:139], s[26:27] offset:96
	s_mov_b64 s[90:91], exec
	s_mov_b64 exec, 0xffff
	global_store_dword v238, v140, s[28:29]
	s_mov_b64 exec, s[90:91]
	s_cmp_eq_u32 s7, 1
	s_cbranch_scc1 .Lat991_i3_nonext
	s_add_u32 s84, s5, s4
	s_xor_b32 s83, s4, 1
	s_mul_i32 s74, s84, 256
	s_lshl_b32 s75, s83, 7
	s_add_u32 s74, s74, s75
	s_lshl_b32 s75, s74, 7
	s_add_u32 s16, s60, s75
	s_addc_u32 s17, s61, 0
	s_lshl_b32 s75, s74, 1
	s_add_u32 s24, s64, s75
	s_addc_u32 s25, s65, 0
	s_add_u32 m0, s70, 0x0
	s_nop 0
	global_load_lds_dwordx4 v232, s[16:17] nt
	s_add_u32 m0, s70, 0x2000
	s_nop 0
	global_load_lds_dwordx4 v233, s[16:17] nt
	s_add_u32 m0, s70, 0x10000
	s_nop 0
	global_load_lds_dwordx4 v234, s[24:25] nt
	s_add_u32 m0, s70, 0x12000
	s_nop 0
	global_load_lds_dwordx4 v235, s[24:25] nt
	s_lshl_b32 s74, s83, 11
	s_add_u32 s74, s74, s84
	s_lshl_b32 s75, s74, 7
	s_add_u32 s10, s30, s75
	s_addc_u32 s11, s31, 0
	s_add_u32 s12, s34, s75
	s_addc_u32 s13, s35, 0
	s_lshl_b32 s75, s74, 2
	s_add_u32 s14, s58, s75
	s_addc_u32 s15, s59, 0
	global_load_dwordx4 v[96:99], v236, s[10:11]
	global_load_dwordx4 v[100:103], v236, s[10:11] offset:64
	global_load_dwordx2 v[112:113], v237, s[12:13]
	global_load_dwordx2 v[114:115], v237, s[12:13] offset:32
	global_load_dwordx2 v[116:117], v237, s[12:13] offset:64
	global_load_dwordx2 v[118:119], v237, s[12:13] offset:96
	global_load_dword v120, v238, s[14:15]

.Lat991_i3_nomask:
	v_max3_f32 v245, v44, v45, v46
	v_max3_f32 v245, v245, v47, v48
	v_max3_f32 v245, v245, v49, v50
	v_max3_f32 v245, v245, v51, v52
	v_max3_f32 v245, v245, v53, v54
	v_max3_f32 v245, v245, v55, v56
	v_max3_f32 v245, v245, v57, v58
	v_max3_f32 v245, v245, v59, v60
	v_max3_f32 v245, v245, v61, v62
	v_max3_f32 v245, v245, v63, v64
	v_max3_f32 v245, v245, v65, v66
	v_max3_f32 v245, v245, v67, v68
	v_max3_f32 v245, v245, v69, v70
	v_max3_f32 v245, v245, v71, v72
	v_max3_f32 v245, v245, v73, v74
	v_max3_f32 v245, v245, v75, v76
	v_max3_f32 v245, v245, v77, v78
	v_max_f32_e32 v245, v245, v79
	v_mov_b32_e32 v148, v245
	s_nop 1
	v_permlane16_swap_b32 v245, v148
	v_max_f32_e32 v245, v245, v148
	v_mov_b32_e32 v148, v245
	s_nop 1
	v_permlane32_swap_b32 v245, v148
	v_max_f32_e32 v245, v245, v148
	v_sub_f32_e32 v44, v44, v245
	v_sub_f32_e32 v45, v45, v245
	v_sub_f32_e32 v46, v46, v245
	v_sub_f32_e32 v47, v47, v245
	v_exp_f32_e32 v44, v44
	v_exp_f32_e32 v45, v45
	v_exp_f32_e32 v46, v46
	v_exp_f32_e32 v47, v47
	v_sub_f32_e32 v48, v48, v245
	v_sub_f32_e32 v49, v49, v245
	v_sub_f32_e32 v50, v50, v245
	v_sub_f32_e32 v51, v51, v245
	v_exp_f32_e32 v48, v48
	v_exp_f32_e32 v49, v49
	v_exp_f32_e32 v50, v50
	v_exp_f32_e32 v51, v51
	v_mov_b32_e32 v149, v44
	v_mov_b32_e32 v150, v45
	v_mov_b32_e32 v151, v46
	v_mov_b32_e32 v152, v47
	v_cvt_pk_bf16_f32 v44, v44, v45
	v_cvt_pk_bf16_f32 v45, v46, v47
	v_sub_f32_e32 v52, v52, v245
	v_sub_f32_e32 v53, v53, v245
	v_sub_f32_e32 v54, v54, v245
	v_sub_f32_e32 v55, v55, v245
	v_exp_f32_e32 v52, v52
	v_exp_f32_e32 v53, v53
	v_exp_f32_e32 v54, v54
	v_exp_f32_e32 v55, v55
	v_add_f32_e32 v149, v149, v48
	v_add_f32_e32 v150, v150, v49
	v_add_f32_e32 v151, v151, v50
	v_add_f32_e32 v152, v152, v51
	v_cvt_pk_bf16_f32 v46, v48, v49
	v_cvt_pk_bf16_f32 v47, v50, v51
	v_sub_f32_e32 v56, v56, v245
	v_sub_f32_e32 v57, v57, v245
	v_sub_f32_e32 v58, v58, v245
	v_sub_f32_e32 v59, v59, v245
	v_exp_f32_e32 v56, v56
	v_exp_f32_e32 v57, v57
	v_exp_f32_e32 v58, v58
	v_exp_f32_e32 v59, v59
	v_add_f32_e32 v149, v149, v52
	v_add_f32_e32 v150, v150, v53
	v_add_f32_e32 v151, v151, v54
	v_add_f32_e32 v152, v152, v55
	v_cvt_pk_bf16_f32 v52, v52, v53
	v_cvt_pk_bf16_f32 v53, v54, v55
	v_sub_f32_e32 v60, v60, v245
	v_sub_f32_e32 v61, v61, v245
	v_sub_f32_e32 v62, v62, v245
	v_sub_f32_e32 v63, v63, v245
	v_exp_f32_e32 v60, v60
	v_exp_f32_e32 v61, v61
	v_exp_f32_e32 v62, v62
	v_exp_f32_e32 v63, v63
	v_add_f32_e32 v149, v149, v56
	v_add_f32_e32 v150, v150, v57
	v_add_f32_e32 v151, v151, v58
	v_add_f32_e32 v152, v152, v59
	v_cvt_pk_bf16_f32 v54, v56, v57
	v_cvt_pk_bf16_f32 v55, v58, v59
	v_sub_f32_e32 v64, v64, v245
	v_sub_f32_e32 v65, v65, v245
	v_sub_f32_e32 v66, v66, v245
	v_sub_f32_e32 v67, v67, v245
	v_exp_f32_e32 v64, v64
	v_exp_f32_e32 v65, v65
	v_exp_f32_e32 v66, v66
	v_exp_f32_e32 v67, v67
	v_add_f32_e32 v149, v149, v60
	v_add_f32_e32 v150, v150, v61
	v_add_f32_e32 v151, v151, v62
	v_add_f32_e32 v152, v152, v63
	v_cvt_pk_bf16_f32 v60, v60, v61
	v_cvt_pk_bf16_f32 v61, v62, v63
	v_sub_f32_e32 v68, v68, v245
	v_sub_f32_e32 v69, v69, v245
	v_sub_f32_e32 v70, v70, v245
	v_sub_f32_e32 v71, v71, v245
	v_exp_f32_e32 v68, v68
	v_exp_f32_e32 v69, v69
	v_exp_f32_e32 v70, v70
	v_exp_f32_e32 v71, v71
	v_add_f32_e32 v149, v149, v64
	v_add_f32_e32 v150, v150, v65
	v_add_f32_e32 v151, v151, v66
	v_add_f32_e32 v152, v152, v67
	v_cvt_pk_bf16_f32 v62, v64, v65
	v_cvt_pk_bf16_f32 v63, v66, v67
	v_sub_f32_e32 v72, v72, v245
	v_sub_f32_e32 v73, v73, v245
	v_sub_f32_e32 v74, v74, v245
	v_sub_f32_e32 v75, v75, v245
	v_exp_f32_e32 v72, v72
	v_exp_f32_e32 v73, v73
	v_exp_f32_e32 v74, v74
	v_exp_f32_e32 v75, v75
	v_add_f32_e32 v149, v149, v68
	v_add_f32_e32 v150, v150, v69
	v_add_f32_e32 v151, v151, v70
	v_add_f32_e32 v152, v152, v71
	v_cvt_pk_bf16_f32 v68, v68, v69
	v_cvt_pk_bf16_f32 v69, v70, v71
	v_sub_f32_e32 v76, v76, v245
	v_sub_f32_e32 v77, v77, v245
	v_sub_f32_e32 v78, v78, v245
	v_sub_f32_e32 v79, v79, v245
	v_exp_f32_e32 v76, v76
	v_exp_f32_e32 v77, v77
	v_exp_f32_e32 v78, v78
	v_exp_f32_e32 v79, v79
	v_add_f32_e32 v149, v149, v72
	v_add_f32_e32 v150, v150, v73
	v_add_f32_e32 v151, v151, v74
	v_add_f32_e32 v152, v152, v75
	v_cvt_pk_bf16_f32 v70, v72, v73
	v_cvt_pk_bf16_f32 v71, v74, v75
	s_nop 0
	v_add_f32_e32 v149, v149, v76
	v_add_f32_e32 v150, v150, v77
	v_add_f32_e32 v151, v151, v78
	v_add_f32_e32 v152, v152, v79
	v_cvt_pk_bf16_f32 v76, v76, v77
	v_cvt_pk_bf16_f32 v77, v78, v79
	v_mov_b32_e32 v78, 0
	v_mov_b32_e32 v79, 0
	v_add_f32_e32 v149, v149, v150
	v_add_f32_e32 v151, v151, v152
	v_add_f32_e32 v246, v149, v151
	s_waitcnt lgkmcnt(0)
	v_mfma_f32_16x16x32_bf16 v[80:83], v[4:7], v[44:47], 0
	v_mfma_f32_16x16x32_bf16 v[84:87], v[8:11], v[44:47], 0
	v_mfma_f32_16x16x32_bf16 v[88:91], v[12:15], v[44:47], 0
	v_mfma_f32_16x16x32_bf16 v[92:95], v[16:19], v[44:47], 0
	ds_read_b64 v[4:5], v225 offset:32768
	ds_read_b64 v[8:9], v225 offset:36864
	ds_read_b64 v[12:13], v225 offset:40960
	ds_read_b64 v[16:17], v225 offset:45056
	ds_read_b64 v[6:7], v226 offset:32768
	ds_read_b64 v[10:11], v226 offset:36864
	ds_read_b64 v[14:15], v226 offset:40960
	ds_read_b64 v[18:19], v226 offset:45056
	v_mfma_f32_16x16x32_bf16 v[80:83], v[20:23], v[52:55], v[80:83]
	v_mfma_f32_16x16x32_bf16 v[84:87], v[24:27], v[52:55], v[84:87]
	v_mfma_f32_16x16x32_bf16 v[88:91], v[28:31], v[52:55], v[88:91]
	v_mfma_f32_16x16x32_bf16 v[92:95], v[32:35], v[52:55], v[92:95]
	ds_read_b64 v[20:21], v227 offset:32768
	ds_read_b64 v[24:25], v227 offset:36864
	ds_read_b64 v[28:29], v227 offset:40960
	ds_read_b64 v[32:33], v227 offset:45056
	ds_read_b64 v[22:23], v228 offset:32768
	ds_read_b64 v[26:27], v228 offset:36864
	ds_read_b64 v[30:31], v228 offset:40960
	ds_read_b64 v[34:35], v228 offset:45056
	s_waitcnt lgkmcnt(8)
	v_mfma_f32_16x16x32_bf16 v[80:83], v[4:7], v[60:63], v[80:83]
	v_mfma_f32_16x16x32_bf16 v[84:87], v[8:11], v[60:63], v[84:87]
	v_mfma_f32_16x16x32_bf16 v[88:91], v[12:15], v[60:63], v[88:91]
	v_mfma_f32_16x16x32_bf16 v[92:95], v[16:19], v[60:63], v[92:95]
	ds_read_b64 v[4:5], v229 offset:32768
	ds_read_b64 v[8:9], v229 offset:36864
	ds_read_b64 v[12:13], v229 offset:40960
	ds_read_b64 v[16:17], v229 offset:45056
	v_mov_b32_e32 v6, 0
	v_mov_b32_e32 v7, 0
	v_mov_b32_e32 v10, 0
	v_mov_b32_e32 v11, 0
	v_mov_b32_e32 v14, 0
	v_mov_b32_e32 v15, 0
	v_mov_b32_e32 v18, 0
	v_mov_b32_e32 v19, 0
	s_waitcnt lgkmcnt(4)
	v_mfma_f32_16x16x32_bf16 v[80:83], v[20:23], v[68:71], v[80:83]
	v_mfma_f32_16x16x32_bf16 v[84:87], v[24:27], v[68:71], v[84:87]
	v_mfma_f32_16x16x32_bf16 v[88:91], v[28:31], v[68:71], v[88:91]
	v_mfma_f32_16x16x32_bf16 v[92:95], v[32:35], v[68:71], v[92:95]
	s_waitcnt lgkmcnt(0)
	v_mfma_f32_16x16x32_bf16 v[80:83], v[4:7], v[76:79], v[80:83]
	v_mfma_f32_16x16x32_bf16 v[84:87], v[8:11], v[76:79], v[84:87]
	v_mfma_f32_16x16x32_bf16 v[88:91], v[12:15], v[76:79], v[88:91]
	v_mfma_f32_16x16x32_bf16 v[92:95], v[16:19], v[76:79], v[92:95]
	v_mov_b32_e32 v148, v246
	s_nop 1
	v_permlane16_swap_b32 v246, v148
	v_add_f32_e32 v246, v246, v148
	v_mov_b32_e32 v148, v246
	s_nop 1
	v_permlane32_swap_b32 v246, v148
	v_add_f32_e32 v246, v246, v148
	v_rcp_f32_e32 v149, v246
	v_log_f32_e32 v150, v246
	s_nop 0
	v_add_f32_e32 v151, v245, v150
	v_mul_f32_e32 v151, 0x3f317218, v151
	v_max_f32_e32 v152, v121, v151
	v_sub_f32_e32 v153, v121, v152
	v_sub_f32_e32 v154, v151, v152
	v_mul_f32_e32 v153, 0x3fb8aa3b, v153
	v_mul_f32_e32 v154, 0x3fb8aa3b, v154
	v_exp_f32_e32 v153, v153
	v_exp_f32_e32 v154, v154
	s_nop 0
	v_add_f32_e32 v155, v153, v154
	v_rcp_f32_e32 v146, v155
	v_log_f32_e32 v150, v155
	s_nop 0
	v_mul_f32_e32 v154, v154, v146
	v_mul_f32_e32 v146, v153, v146
	v_mul_f32_e32 v147, v149, v154
	v_mul_f32_e32 v150, 0x3f317218, v150
	v_add_f32_e32 v140, v152, v150
	v_mul_f32_e32 v80, v80, v147
	v_mul_f32_e32 v81, v81, v147
	v_mul_f32_e32 v82, v82, v147
	v_mul_f32_e32 v83, v83, v147
	v_mul_f32_e32 v84, v84, v147
	v_mul_f32_e32 v85, v85, v147
	v_mul_f32_e32 v86, v86, v147
	v_mul_f32_e32 v87, v87, v147
	v_mul_f32_e32 v88, v88, v147
	v_mul_f32_e32 v89, v89, v147
	v_mul_f32_e32 v90, v90, v147
	v_mul_f32_e32 v91, v91, v147
	v_mul_f32_e32 v92, v92, v147
	v_mul_f32_e32 v93, v93, v147
	v_mul_f32_e32 v94, v94, v147
	v_mul_f32_e32 v95, v95, v147
	v_lshlrev_b32_e32 v141, 16, v122
	v_and_b32_e32 v142, 0xffff0000, v122
	v_lshlrev_b32_e32 v143, 16, v123
	v_and_b32_e32 v144, 0xffff0000, v123
	v_fmac_f32_e32 v80, v146, v141
	v_fmac_f32_e32 v81, v146, v142
	v_fmac_f32_e32 v82, v146, v143
	v_fmac_f32_e32 v83, v146, v144
	v_cvt_pk_bf16_f32 v132, v80, v81
	v_cvt_pk_bf16_f32 v133, v82, v83
	v_lshlrev_b32_e32 v141, 16, v124
	v_and_b32_e32 v142, 0xffff0000, v124
	v_lshlrev_b32_e32 v143, 16, v125
	v_and_b32_e32 v144, 0xffff0000, v125
	v_fmac_f32_e32 v84, v146, v141
	v_fmac_f32_e32 v85, v146, v142
	v_fmac_f32_e32 v86, v146, v143
	v_fmac_f32_e32 v87, v146, v144
	v_cvt_pk_bf16_f32 v134, v84, v85
	v_cvt_pk_bf16_f32 v135, v86, v87
	v_lshlrev_b32_e32 v141, 16, v126
	v_and_b32_e32 v142, 0xffff0000, v126
	v_lshlrev_b32_e32 v143, 16, v127
	v_and_b32_e32 v144, 0xffff0000, v127
	v_fmac_f32_e32 v88, v146, v141
	v_fmac_f32_e32 v89, v146, v142
	v_fmac_f32_e32 v90, v146, v143
	v_fmac_f32_e32 v91, v146, v144
	v_cvt_pk_bf16_f32 v136, v88, v89
	v_cvt_pk_bf16_f32 v137, v90, v91
	v_lshlrev_b32_e32 v141, 16, v128
	v_and_b32_e32 v142, 0xffff0000, v128
	v_lshlrev_b32_e32 v143, 16, v129
	v_and_b32_e32 v144, 0xffff0000, v129
	v_fmac_f32_e32 v92, v146, v141
	v_fmac_f32_e32 v93, v146, v142
	v_fmac_f32_e32 v94, v146, v143
	v_fmac_f32_e32 v95, v146, v144
	v_cvt_pk_bf16_f32 v138, v92, v93
	v_cvt_pk_bf16_f32 v139, v94, v95
	s_mov_b64 s[26:27], s[86:87]
	s_mov_b64 s[28:29], s[88:89]
	s_mov_b64 s[86:87], s[12:13]
	s_mov_b64 s[88:89], s[14:15]
	s_mov_b32 s4, s83
	s_mov_b32 s5, s84
	s_add_u32 s7, s7, 1
	s_cmp_lt_u32 s7, 2
	s_cbranch_scc1 .Lat991_loop
	s_setprio 0
	global_store_dwordx2 v237, v[132:133], s[26:27]
	global_store_dwordx2 v237, v[134:135], s[26:27] offset:32
	global_store_dwordx2 v237, v[136:137], s[26:27] offset:64
	global_store_dwordx2 v237, v[138:139], s[26:27] offset:96
	s_mov_b64 s[90:91], exec
	s_mov_b64 exec, 0xffff
	global_store_dword v238, v140, s[28:29]
	s_mov_b64 exec, s[90:91]
	s_waitcnt vmcnt(0)
	s_barrier
	s_waitcnt vmcnt(0)
	s_barrier
	s_mov_b64 s[4:5], exec
	v_readlane_b32 s0, v252, 2
	v_readlane_b32 s1, v252, 3
	v_readlane_b32 s64, v253, 15
	v_readlane_b32 s34, v252, 27
	v_readlane_b32 s56, v253, 19
	v_readlane_b32 s16, v253, 21
	v_readlane_b32 s36, v252, 29
	v_readlane_b32 s70, v252, 31
	v_readlane_b32 s74, v252, 33
	v_readlane_b32 s76, v252, 35
	v_readlane_b32 s78, v252, 37
	s_and_b64 s[0:1], s[4:5], s[0:1]
	v_readlane_b32 s85, v253, 23
	v_readlane_b32 s92, v253, 24
	v_readlane_b32 s65, v253, 16
	v_readlane_b32 s63, v252, 26
	v_readlane_b32 s66, v253, 18
	v_readlane_b32 s35, v252, 28
	v_readlane_b32 s57, v253, 20
	v_readlane_b32 s17, v253, 22
	v_readlane_b32 s37, v252, 30
	v_readlane_b32 s71, v252, 32
	v_readlane_b32 s75, v252, 34
	v_readlane_b32 s77, v252, 36
	v_readlane_b32 s79, v252, 38
	v_readlane_b32 s93, v253, 25
	s_mov_b64 exec, s[0:1]
	s_cbranch_execz .LBB0_1061
	v_mov_b32_e32 v0, 0x20000
	ds_read_b64 v[0:1], v0
	s_getreg_b32 s44, hwreg(HW_REG_XCC_ID, 0, 4)
	s_lshl_b32 s44, s44, 7
	s_add_u32 s44, s44, 0xdc03600
	v_mov_b32_e32 v2, s44
	v_mov_b32_e32 v4, 1
	s_waitcnt vmcnt(0) lgkmcnt(0)
	global_atomic_add v5, v2, v4, s[42:43] sc0
	buffer_inv sc1
	s_add_u32 s100, s100, 1
	v_readfirstlane_b32 s46, v0
	v_readfirstlane_b32 s47, v1
	v_mov_b32_e32 v2, 0xdc03e00
	s_nop 3
	s_mul_i32 s48, s46, s100
	s_mul_i32 s49, s47, s100
	s_waitcnt vmcnt(1)
	v_readfirstlane_b32 s50, v5
	s_nop 3
	s_add_u32 s50, s50, 1
	s_cmp_lg_u32 s50, s48
	s_cbranch_scc1 .Lxb9_poll
	buffer_wbl2 sc1
	s_waitcnt vmcnt(0)
	global_atomic_add v2, v4, s[42:43]
